# GEMM K-loops: removed the redundant second s_waitcnt lgkmcnt(0) after s_barrier/s_setprio 1 at the head of each MFMA block
# baseline (speedup 1.0000x reference)
; #define PG8_STAGE(bufoff, gbase, voff) do { _Pragma("unroll") for (int _i = 0; _i < 2; ++_i) \
;         __builtin_amdgcn_global_load_lds((const unsigned*)((const char*)(gbase) + (voff)[_i]), (LAS unsigned*)(lds + (bufoff) + ldsw + _i * 8192), 16, 0, 0); } while (0)
; #define PG8_LDA(dst, b, h) do { _Pragma("unroll") for (int m = 0; m < 4; ++m) _Pragma("unroll") for (int k = 0; k < 2; ++k) dst[m][k] = *(const LAS bf16x8*)(lds + PG8_SA(b, h) + aoff + m * 2048 + k * 1024); } while (0)
; #define PG8_LDB(dst, b, h) do { _Pragma("unroll") for (int n = 0; n < 2; ++n) _Pragma("unroll") for (int k = 0; k < 2; ++k) dst[n][k] = *(const LAS bf16x8*)(lds + PG8_SB(b, h) + boff + n * 2048 + k * 1024); } while (0)
; #define PG8_MMA(ai, bj, At, Bt) do { __builtin_amdgcn_s_setprio(1); _Pragma("unroll") for (int m = 0; m < 4; ++m) _Pragma("unroll") for (int n = 0; n < 2; ++n) _Pragma("unroll") for (int k = 0; k < 2; ++k) \
;         acc[ai][bj][m][n] = __builtin_amdgcn_mfma_f32_16x16x32_bf16(Bt[n][k], At[m][k], acc[ai][bj][m][n], 0, 0, 0); __builtin_amdgcn_s_setprio(0); } while (0)
; #define PG8_WAIT_V(n) asm volatile("s_waitcnt vmcnt(" #n ")" ::: "memory")
; #define PG8_WAIT_L(n) asm volatile("s_waitcnt lgkmcnt(" #n ")" ::: "memory")
; #define PG8_BAR __builtin_amdgcn_s_barrier()
; #define PG8_SCHED __builtin_amdgcn_sched_barrier(0)
; template <class Epi, bool ALIGN_EPI = true, bool SP2 = true>
; __device__ __forceinline__ void gemm_phase(LAS unsigned char* lds, const Gemm g, const StaticOrder& S, const Epi& E, const int wave_s) {
;     ...
;             PG8_LDB(B0, 0, 0); PG8_LDB(B1, 0, 1); PG8_SCHED; PG8_LDA(At, 0, 0); PG8_STAGE(PG8_SA(1, 1), a1 + hstep, voffA);
;             PG8_WAIT_V(8); PG8_WAIT_L(0); PG8_BAR; PG8_MMA(0, 0, At, B0); PG8_MMA(0, 1, At, B1); PG8_BAR; PG8_SCHED;
;             PG8_LDA(At, 0, 1); PG8_STAGE(PG8_SB(0, 0), b2, voffB); PG8_STAGE(PG8_SB(0, 1), b2 + hstep, voffB); PG8_STAGE(PG8_SA(0, 0), a2, voffA);
;             PG8_WAIT_V(8); PG8_WAIT_L(0); PG8_BAR; PG8_MMA(1, 0, At, B0); PG8_MMA(1, 1, At, B1); PG8_BAR; PG8_SCHED;
.LBB0_116:
	ds_read_b128 v[144:147], v151
	ds_read_b128 v[154:157], v151 offset:1024
	ds_read_b128 v[158:161], v151 offset:2048
	ds_read_b128 v[162:165], v151 offset:3072
	ds_read_b128 v[166:169], v152
	ds_read_b128 v[170:173], v152 offset:1024
	ds_read_b128 v[174:177], v152 offset:2048
	ds_read_b128 v[178:181], v152 offset:3072
	s_add_u32 s30, s28, 0xfffc0080
	s_addc_u32 s31, s29, -1
	s_cmp_eq_u32 s52, 12
	s_cselect_b32 s35, s21, s31
	s_cselect_b32 s34, s48, s30
	s_cselect_b32 s31, s19, s51
	s_cselect_b32 s30, s49, s50
	v_lshl_add_u64 v[214:215], s[28:29], 0, v[138:139]
	s_add_i32 m0, s27, 0xc000
	ds_read_b128 v[182:185], v153
	ds_read_b128 v[186:189], v153 offset:1024
	ds_read_b128 v[190:193], v153 offset:2048
	ds_read_b128 v[194:197], v153 offset:3072
	ds_read_b128 v[198:201], v153 offset:4096
	ds_read_b128 v[202:205], v153 offset:5120
	ds_read_b128 v[206:209], v153 offset:6144
	ds_read_b128 v[210:213], v153 offset:7168
	global_load_lds_dwordx4 v[214:215], off
	v_lshl_add_u64 v[214:215], s[28:29], 0, v[136:137]
	s_add_i32 m0, s27, 0xe000
	s_nop 0
	global_load_lds_dwordx4 v[214:215], off
	s_waitcnt vmcnt(8)
	s_waitcnt lgkmcnt(0)
	s_barrier
	s_setprio 1
	v_mfma_f32_16x16x32_bf16 v[124:127], v[144:147], v[182:185], v[124:127]
	v_mfma_f32_16x16x32_bf16 v[120:123], v[158:161], v[182:185], v[120:123]
	v_mfma_f32_16x16x32_bf16 v[116:119], v[144:147], v[190:193], v[116:119]
	v_mfma_f32_16x16x32_bf16 v[108:111], v[158:161], v[190:193], v[108:111]
	v_mfma_f32_16x16x32_bf16 v[100:103], v[144:147], v[198:201], v[100:103]
	v_mfma_f32_16x16x32_bf16 v[92:95], v[158:161], v[198:201], v[92:95]
	v_mfma_f32_16x16x32_bf16 v[84:87], v[144:147], v[206:209], v[84:87]
	v_mfma_f32_16x16x32_bf16 v[76:79], v[158:161], v[206:209], v[76:79]
	v_mfma_f32_16x16x32_bf16 v[124:127], v[154:157], v[186:189], v[124:127]
	v_mfma_f32_16x16x32_bf16 v[120:123], v[162:165], v[186:189], v[120:123]
	v_mfma_f32_16x16x32_bf16 v[116:119], v[154:157], v[194:197], v[116:119]
	v_mfma_f32_16x16x32_bf16 v[108:111], v[162:165], v[194:197], v[108:111]
	v_mfma_f32_16x16x32_bf16 v[100:103], v[154:157], v[202:205], v[100:103]
	v_mfma_f32_16x16x32_bf16 v[92:95], v[162:165], v[202:205], v[92:95]
	v_mfma_f32_16x16x32_bf16 v[84:87], v[154:157], v[210:213], v[84:87]
	v_mfma_f32_16x16x32_bf16 v[76:79], v[162:165], v[210:213], v[76:79]
	v_mfma_f32_16x16x32_bf16 v[112:115], v[166:169], v[182:185], v[112:115]
	v_mfma_f32_16x16x32_bf16 v[104:107], v[174:177], v[182:185], v[104:107]
	v_mfma_f32_16x16x32_bf16 v[96:99], v[166:169], v[190:193], v[96:99]
	v_mfma_f32_16x16x32_bf16 v[88:91], v[174:177], v[190:193], v[88:91]
	v_mfma_f32_16x16x32_bf16 v[80:83], v[166:169], v[198:201], v[80:83]
	v_mfma_f32_16x16x32_bf16 v[72:75], v[174:177], v[198:201], v[72:75]
	v_mfma_f32_16x16x32_bf16 v[68:71], v[166:169], v[206:209], v[68:71]
	v_mfma_f32_16x16x32_bf16 v[64:67], v[174:177], v[206:209], v[64:67]
	v_mfma_f32_16x16x32_bf16 v[112:115], v[170:173], v[186:189], v[112:115]
	v_mfma_f32_16x16x32_bf16 v[104:107], v[178:181], v[186:189], v[104:107]
	v_mfma_f32_16x16x32_bf16 v[96:99], v[170:173], v[194:197], v[96:99]
	v_mfma_f32_16x16x32_bf16 v[88:91], v[178:181], v[194:197], v[88:91]
	v_mfma_f32_16x16x32_bf16 v[80:83], v[170:173], v[202:205], v[80:83]
	v_mfma_f32_16x16x32_bf16 v[72:75], v[178:181], v[202:205], v[72:75]
	v_mfma_f32_16x16x32_bf16 v[68:71], v[170:173], v[210:213], v[68:71]
	v_mfma_f32_16x16x32_bf16 v[64:67], v[178:181], v[210:213], v[64:67]
	s_setprio 0
	s_barrier
	s_add_i32 s53, s44, s61
	v_lshl_add_u64 v[214:215], s[30:31], 0, v[132:133]
	s_mov_b32 m0, s53
	ds_read_b128 v[182:185], v153 offset:16384
	ds_read_b128 v[186:189], v153 offset:17408
	ds_read_b128 v[190:193], v153 offset:18432
	ds_read_b128 v[194:197], v153 offset:19456
	ds_read_b128 v[198:201], v153 offset:20480
	ds_read_b128 v[202:205], v153 offset:21504
	ds_read_b128 v[206:209], v153 offset:22528
	ds_read_b128 v[210:213], v153 offset:23552
	global_load_lds_dwordx4 v[214:215], off
	s_add_i32 m0, s53, 0x2000
	s_add_u32 s54, s30, 0x40000
	v_lshl_add_u64 v[216:217], s[30:31], 0, v[128:129]
	s_addc_u32 s55, s31, 0
	s_add_i32 s53, s45, s61
	global_load_lds_dwordx4 v[216:217], off
	v_lshl_add_u64 v[218:219], s[54:55], 0, v[132:133]
	s_mov_b32 m0, s53
	v_lshl_add_u64 v[220:221], s[34:35], 0, v[130:131]
	global_load_lds_dwordx4 v[218:219], off
	v_lshl_add_u64 v[218:219], s[54:55], 0, v[128:129]
	s_add_i32 m0, s53, 0x2000
	s_nop 0
	global_load_lds_dwordx4 v[218:219], off
	v_lshl_add_u64 v[218:219], s[34:35], 0, v[134:135]
	s_mov_b32 m0, s27
	s_nop 0
	global_load_lds_dwordx4 v[218:219], off
	s_mov_b32 m0, s37
	s_nop 0
	global_load_lds_dwordx4 v[220:221], off
	s_waitcnt vmcnt(8)
	s_waitcnt lgkmcnt(0)
	s_barrier
; #define PG8_STAGE(bufoff, gbase, voff) do { _Pragma("unroll") for (int _i = 0; _i < 2; ++_i) \
;         __builtin_amdgcn_global_load_lds((const unsigned*)((const char*)(gbase) + (voff)[_i]), (LAS unsigned*)(lds + (bufoff) + ldsw + _i * 8192), 16, 0, 0); } while (0)
; #define PG8_LDA(dst, b, h) do { _Pragma("unroll") for (int m = 0; m < 4; ++m) _Pragma("unroll") for (int k = 0; k < 2; ++k) dst[m][k] = *(const LAS bf16x8*)(lds + PG8_SA(b, h) + aoff + m * 2048 + k * 1024); } while (0)
; #define PG8_LDB(dst, b, h) do { _Pragma("unroll") for (int n = 0; n < 2; ++n) _Pragma("unroll") for (int k = 0; k < 2; ++k) dst[n][k] = *(const LAS bf16x8*)(lds + PG8_SB(b, h) + boff + n * 2048 + k * 1024); } while (0)
; #define PG8_MMA(ai, bj, At, Bt) do { __builtin_amdgcn_s_setprio(1); _Pragma("unroll") for (int m = 0; m < 4; ++m) _Pragma("unroll") for (int n = 0; n < 2; ++n) _Pragma("unroll") for (int k = 0; k < 2; ++k) \
;         acc[ai][bj][m][n] = __builtin_amdgcn_mfma_f32_16x16x32_bf16(Bt[n][k], At[m][k], acc[ai][bj][m][n], 0, 0, 0); __builtin_amdgcn_s_setprio(0); } while (0)
; #define PG8_WAIT_V(n) asm volatile("s_waitcnt vmcnt(" #n ")" ::: "memory")
; #define PG8_WAIT_L(n) asm volatile("s_waitcnt lgkmcnt(" #n ")" ::: "memory")
; #define PG8_BAR __builtin_amdgcn_s_barrier()
; #define PG8_SCHED __builtin_amdgcn_sched_barrier(0)
; template <class Epi, bool ALIGN_EPI = true, bool SP2 = true>
; __device__ __forceinline__ void gemm_phase(LAS unsigned char* lds, const Gemm g, const StaticOrder& S, const Epi& E, const int wave_s) {
;     ...
;             PG8_WAIT_V(8); PG8_WAIT_L(0); PG8_BAR; PG8_MMA(1, 0, At, B0); PG8_MMA(1, 1, At, B1); PG8_BAR; PG8_SCHED;
;             PG8_LDB(B0, 1, 0); PG8_LDB(B1, 1, 1); PG8_SCHED; PG8_LDA(At, 1, 0); PG8_STAGE(PG8_SA(0, 1), a2 + hstep, voffA);
;             PG8_WAIT_V(8); PG8_WAIT_L(0); PG8_BAR; PG8_MMA(0, 0, At, B0); PG8_MMA(0, 1, At, B1); PG8_BAR; PG8_SCHED;
	s_setprio 1
	v_mfma_f32_16x16x32_bf16 v[60:63], v[144:147], v[182:185], v[60:63]
	v_mfma_f32_16x16x32_bf16 v[56:59], v[158:161], v[182:185], v[56:59]
	v_mfma_f32_16x16x32_bf16 v[52:55], v[144:147], v[190:193], v[52:55]
	v_mfma_f32_16x16x32_bf16 v[44:47], v[158:161], v[190:193], v[44:47]
	v_mfma_f32_16x16x32_bf16 v[36:39], v[144:147], v[198:201], v[36:39]
	v_mfma_f32_16x16x32_bf16 v[28:31], v[158:161], v[198:201], v[28:31]
	v_mfma_f32_16x16x32_bf16 v[20:23], v[144:147], v[206:209], v[20:23]
	v_mfma_f32_16x16x32_bf16 v[12:15], v[158:161], v[206:209], v[12:15]
	v_mfma_f32_16x16x32_bf16 v[60:63], v[154:157], v[186:189], v[60:63]
	v_mfma_f32_16x16x32_bf16 v[56:59], v[162:165], v[186:189], v[56:59]
	v_mfma_f32_16x16x32_bf16 v[52:55], v[154:157], v[194:197], v[52:55]
	v_mfma_f32_16x16x32_bf16 v[44:47], v[162:165], v[194:197], v[44:47]
	v_mfma_f32_16x16x32_bf16 v[36:39], v[154:157], v[202:205], v[36:39]
	v_mfma_f32_16x16x32_bf16 v[28:31], v[162:165], v[202:205], v[28:31]
	v_mfma_f32_16x16x32_bf16 v[20:23], v[154:157], v[210:213], v[20:23]
	v_mfma_f32_16x16x32_bf16 v[12:15], v[162:165], v[210:213], v[12:15]
	v_mfma_f32_16x16x32_bf16 v[48:51], v[166:169], v[182:185], v[48:51]
	v_mfma_f32_16x16x32_bf16 v[40:43], v[174:177], v[182:185], v[40:43]
	v_mfma_f32_16x16x32_bf16 v[32:35], v[166:169], v[190:193], v[32:35]
	v_mfma_f32_16x16x32_bf16 v[24:27], v[174:177], v[190:193], v[24:27]
	v_mfma_f32_16x16x32_bf16 v[16:19], v[166:169], v[198:201], v[16:19]
	v_mfma_f32_16x16x32_bf16 v[8:11], v[174:177], v[198:201], v[8:11]
	v_mfma_f32_16x16x32_bf16 v[4:7], v[166:169], v[206:209], v[4:7]
	v_mfma_f32_16x16x32_bf16 v[0:3], v[174:177], v[206:209], v[0:3]
	v_mfma_f32_16x16x32_bf16 v[48:51], v[170:173], v[186:189], v[48:51]
	v_mfma_f32_16x16x32_bf16 v[40:43], v[178:181], v[186:189], v[40:43]
	v_mfma_f32_16x16x32_bf16 v[32:35], v[170:173], v[194:197], v[32:35]
	v_mfma_f32_16x16x32_bf16 v[24:27], v[178:181], v[194:197], v[24:27]
	v_mfma_f32_16x16x32_bf16 v[16:19], v[170:173], v[202:205], v[16:19]
	v_mfma_f32_16x16x32_bf16 v[8:11], v[178:181], v[202:205], v[8:11]
	v_mfma_f32_16x16x32_bf16 v[4:7], v[170:173], v[210:213], v[4:7]
	v_mfma_f32_16x16x32_bf16 v[0:3], v[178:181], v[210:213], v[0:3]
	s_setprio 0
	s_barrier
	s_add_i32 s53, 0, 0x18000
	s_add_i32 s54, 0, 0x1c000
	v_add_u32_e32 v162, s53, v149
	v_add_u32_e32 v178, s54, v149
	ds_read_b128 v[144:147], v162
	ds_read_b128 v[154:157], v162 offset:1024
	ds_read_b128 v[158:161], v162 offset:2048
	ds_read_b128 v[162:165], v162 offset:3072
	ds_read_b128 v[166:169], v178
	ds_read_b128 v[170:173], v178 offset:1024
	ds_read_b128 v[174:177], v178 offset:2048
	ds_read_b128 v[178:181], v178 offset:3072
	s_add_u32 s34, s34, 0x40000
	s_addc_u32 s35, s35, 0
	s_mov_b32 m0, s38
	v_lshl_add_u64 v[222:223], s[34:35], 0, v[134:135]
	ds_read_b128 v[182:185], v153 offset:32768
	ds_read_b128 v[186:189], v153 offset:33792
	ds_read_b128 v[190:193], v153 offset:34816
	ds_read_b128 v[194:197], v153 offset:35840
	ds_read_b128 v[198:201], v153 offset:36864
	ds_read_b128 v[202:205], v153 offset:37888
	ds_read_b128 v[206:209], v153 offset:38912
	ds_read_b128 v[210:213], v153 offset:39936
	global_load_lds_dwordx4 v[222:223], off
	v_lshl_add_u64 v[222:223], s[34:35], 0, v[130:131]
	s_mov_b32 m0, s39
	s_nop 0
	global_load_lds_dwordx4 v[222:223], off
	s_waitcnt vmcnt(8)
	s_waitcnt lgkmcnt(0)
	s_barrier
	s_setprio 1
	v_mfma_f32_16x16x32_bf16 v[124:127], v[144:147], v[182:185], v[124:127]
	v_mfma_f32_16x16x32_bf16 v[120:123], v[158:161], v[182:185], v[120:123]
	v_mfma_f32_16x16x32_bf16 v[116:119], v[144:147], v[190:193], v[116:119]
	v_mfma_f32_16x16x32_bf16 v[108:111], v[158:161], v[190:193], v[108:111]
	v_mfma_f32_16x16x32_bf16 v[100:103], v[144:147], v[198:201], v[100:103]
	v_mfma_f32_16x16x32_bf16 v[92:95], v[158:161], v[198:201], v[92:95]
	v_mfma_f32_16x16x32_bf16 v[84:87], v[144:147], v[206:209], v[84:87]
	v_mfma_f32_16x16x32_bf16 v[76:79], v[158:161], v[206:209], v[76:79]
	v_mfma_f32_16x16x32_bf16 v[124:127], v[154:157], v[186:189], v[124:127]
	v_mfma_f32_16x16x32_bf16 v[120:123], v[162:165], v[186:189], v[120:123]
	v_mfma_f32_16x16x32_bf16 v[116:119], v[154:157], v[194:197], v[116:119]
	v_mfma_f32_16x16x32_bf16 v[108:111], v[162:165], v[194:197], v[108:111]
	v_mfma_f32_16x16x32_bf16 v[100:103], v[154:157], v[202:205], v[100:103]
	v_mfma_f32_16x16x32_bf16 v[92:95], v[162:165], v[202:205], v[92:95]
	v_mfma_f32_16x16x32_bf16 v[84:87], v[154:157], v[210:213], v[84:87]
	v_mfma_f32_16x16x32_bf16 v[76:79], v[162:165], v[210:213], v[76:79]
	v_mfma_f32_16x16x32_bf16 v[112:115], v[166:169], v[182:185], v[112:115]
	v_mfma_f32_16x16x32_bf16 v[104:107], v[174:177], v[182:185], v[104:107]
	v_mfma_f32_16x16x32_bf16 v[96:99], v[166:169], v[190:193], v[96:99]
	v_mfma_f32_16x16x32_bf16 v[88:91], v[174:177], v[190:193], v[88:91]
	v_mfma_f32_16x16x32_bf16 v[80:83], v[166:169], v[198:201], v[80:83]
	v_mfma_f32_16x16x32_bf16 v[72:75], v[174:177], v[198:201], v[72:75]
	v_mfma_f32_16x16x32_bf16 v[68:71], v[166:169], v[206:209], v[68:71]
	v_mfma_f32_16x16x32_bf16 v[64:67], v[174:177], v[206:209], v[64:67]
	v_mfma_f32_16x16x32_bf16 v[112:115], v[170:173], v[186:189], v[112:115]
	v_mfma_f32_16x16x32_bf16 v[104:107], v[178:181], v[186:189], v[104:107]
	v_mfma_f32_16x16x32_bf16 v[96:99], v[170:173], v[194:197], v[96:99]
	v_mfma_f32_16x16x32_bf16 v[88:91], v[178:181], v[194:197], v[88:91]
	v_mfma_f32_16x16x32_bf16 v[80:83], v[170:173], v[202:205], v[80:83]
	v_mfma_f32_16x16x32_bf16 v[72:75], v[178:181], v[202:205], v[72:75]
	v_mfma_f32_16x16x32_bf16 v[68:71], v[170:173], v[210:213], v[68:71]
	v_mfma_f32_16x16x32_bf16 v[64:67], v[178:181], v[210:213], v[64:67]
	s_setprio 0
	s_barrier
; #define PG8_STAGE(bufoff, gbase, voff) do { _Pragma("unroll") for (int _i = 0; _i < 2; ++_i) \
;         __builtin_amdgcn_global_load_lds((const unsigned*)((const char*)(gbase) + (voff)[_i]), (LAS unsigned*)(lds + (bufoff) + ldsw + _i * 8192), 16, 0, 0); } while (0)
; #define PG8_LDA(dst, b, h) do { _Pragma("unroll") for (int m = 0; m < 4; ++m) _Pragma("unroll") for (int k = 0; k < 2; ++k) dst[m][k] = *(const LAS bf16x8*)(lds + PG8_SA(b, h) + aoff + m * 2048 + k * 1024); } while (0)
; #define PG8_MMA(ai, bj, At, Bt) do { __builtin_amdgcn_s_setprio(1); _Pragma("unroll") for (int m = 0; m < 4; ++m) _Pragma("unroll") for (int n = 0; n < 2; ++n) _Pragma("unroll") for (int k = 0; k < 2; ++k) \
;         acc[ai][bj][m][n] = __builtin_amdgcn_mfma_f32_16x16x32_bf16(Bt[n][k], At[m][k], acc[ai][bj][m][n], 0, 0, 0); __builtin_amdgcn_s_setprio(0); } while (0)
; #define PG8_WAIT_V(n) asm volatile("s_waitcnt vmcnt(" #n ")" ::: "memory")
; #define PG8_WAIT_L(n) asm volatile("s_waitcnt lgkmcnt(" #n ")" ::: "memory")
; #define PG8_BAR __builtin_amdgcn_s_barrier()
; #define PG8_SCHED __builtin_amdgcn_sched_barrier(0)
; template <class Epi, bool ALIGN_EPI = true, bool SP2 = true>
; __device__ __forceinline__ void gemm_phase(LAS unsigned char* lds, const Gemm g, const StaticOrder& S, const Epi& E, const int wave_s) {
;     ...
;             PG8_LDA(At, 1, 1); PG8_STAGE(PG8_SB(1, 0), b3, voffB); PG8_STAGE(PG8_SB(1, 1), b3 + hstep, voffB); PG8_STAGE(PG8_SA(1, 0), a3, voffA);
;             PG8_WAIT_V(8); PG8_WAIT_L(0); PG8_BAR; PG8_MMA(1, 0, At, B0); PG8_MMA(1, 1, At, B1); PG8_BAR; PG8_SCHED;
;     ...
;         if constexpr (ALIGN_EPI) { if (wr == 0) PG8_BAR; }
	s_add_i32 s34, s53, s61
	v_lshl_add_u64 v[214:215], v[214:215], 0, s[14:15]
	s_mov_b32 m0, s34
	ds_read_b128 v[182:185], v153 offset:49152
	ds_read_b128 v[186:189], v153 offset:50176
	ds_read_b128 v[190:193], v153 offset:51200
	ds_read_b128 v[194:197], v153 offset:52224
	ds_read_b128 v[198:201], v153 offset:53248
	ds_read_b128 v[202:205], v153 offset:54272
	ds_read_b128 v[206:209], v153 offset:55296
	ds_read_b128 v[210:213], v153 offset:56320
	global_load_lds_dwordx4 v[214:215], off
	s_add_i32 m0, s34, 0x2000
	s_add_u32 s30, s30, 0x40080
	v_lshl_add_u64 v[214:215], v[216:217], 0, s[14:15]
	s_addc_u32 s31, s31, 0
	s_add_i32 s34, s54, s61
	global_load_lds_dwordx4 v[214:215], off
	v_lshl_add_u64 v[214:215], s[30:31], 0, v[132:133]
	s_mov_b32 m0, s34
	s_nop 0
	global_load_lds_dwordx4 v[214:215], off
	v_lshl_add_u64 v[214:215], s[30:31], 0, v[128:129]
	s_add_i32 m0, s34, 0x2000
	s_nop 0
	global_load_lds_dwordx4 v[214:215], off
	v_lshl_add_u64 v[214:215], v[218:219], 0, s[14:15]
	s_mov_b32 m0, s40
	s_nop 0
	global_load_lds_dwordx4 v[214:215], off
	v_lshl_add_u64 v[214:215], v[220:221], 0, s[14:15]
	s_mov_b32 m0, s41
	s_nop 0
	global_load_lds_dwordx4 v[214:215], off
	s_waitcnt vmcnt(8)
	s_waitcnt lgkmcnt(0)
	s_barrier
	s_setprio 1
	v_mfma_f32_16x16x32_bf16 v[60:63], v[144:147], v[182:185], v[60:63]
	v_mfma_f32_16x16x32_bf16 v[56:59], v[158:161], v[182:185], v[56:59]
	v_mfma_f32_16x16x32_bf16 v[52:55], v[144:147], v[190:193], v[52:55]
	v_mfma_f32_16x16x32_bf16 v[44:47], v[158:161], v[190:193], v[44:47]
	v_mfma_f32_16x16x32_bf16 v[36:39], v[144:147], v[198:201], v[36:39]
	v_mfma_f32_16x16x32_bf16 v[28:31], v[158:161], v[198:201], v[28:31]
	v_mfma_f32_16x16x32_bf16 v[20:23], v[144:147], v[206:209], v[20:23]
	v_mfma_f32_16x16x32_bf16 v[12:15], v[158:161], v[206:209], v[12:15]
	v_mfma_f32_16x16x32_bf16 v[60:63], v[154:157], v[186:189], v[60:63]
	v_mfma_f32_16x16x32_bf16 v[56:59], v[162:165], v[186:189], v[56:59]
	v_mfma_f32_16x16x32_bf16 v[52:55], v[154:157], v[194:197], v[52:55]
	v_mfma_f32_16x16x32_bf16 v[44:47], v[162:165], v[194:197], v[44:47]
	v_mfma_f32_16x16x32_bf16 v[36:39], v[154:157], v[202:205], v[36:39]
	v_mfma_f32_16x16x32_bf16 v[28:31], v[162:165], v[202:205], v[28:31]
	v_mfma_f32_16x16x32_bf16 v[20:23], v[154:157], v[210:213], v[20:23]
	v_mfma_f32_16x16x32_bf16 v[12:15], v[162:165], v[210:213], v[12:15]
	v_mfma_f32_16x16x32_bf16 v[48:51], v[166:169], v[182:185], v[48:51]
	v_mfma_f32_16x16x32_bf16 v[40:43], v[174:177], v[182:185], v[40:43]
	v_mfma_f32_16x16x32_bf16 v[32:35], v[166:169], v[190:193], v[32:35]
	v_mfma_f32_16x16x32_bf16 v[24:27], v[174:177], v[190:193], v[24:27]
	v_mfma_f32_16x16x32_bf16 v[16:19], v[166:169], v[198:201], v[16:19]
	v_mfma_f32_16x16x32_bf16 v[8:11], v[174:177], v[198:201], v[8:11]
	v_mfma_f32_16x16x32_bf16 v[4:7], v[166:169], v[206:209], v[4:7]
	v_mfma_f32_16x16x32_bf16 v[0:3], v[174:177], v[206:209], v[0:3]
	v_mfma_f32_16x16x32_bf16 v[48:51], v[170:173], v[186:189], v[48:51]
	v_mfma_f32_16x16x32_bf16 v[40:43], v[178:181], v[186:189], v[40:43]
	v_mfma_f32_16x16x32_bf16 v[32:35], v[170:173], v[194:197], v[32:35]
	v_mfma_f32_16x16x32_bf16 v[24:27], v[178:181], v[194:197], v[24:27]
	v_mfma_f32_16x16x32_bf16 v[16:19], v[170:173], v[202:205], v[16:19]
	v_mfma_f32_16x16x32_bf16 v[8:11], v[178:181], v[202:205], v[8:11]
	v_mfma_f32_16x16x32_bf16 v[4:7], v[170:173], v[210:213], v[4:7]
	v_mfma_f32_16x16x32_bf16 v[0:3], v[178:181], v[210:213], v[0:3]
	s_setprio 0
	s_barrier
	s_add_i32 s52, s52, 2
	s_add_u32 s50, s50, 0x100
	s_addc_u32 s51, s51, 0
	s_add_u32 s28, s28, 0x100
	s_addc_u32 s29, s29, 0
	s_cmp_gt_u32 s52, 13
	s_cbranch_scc0 .LBB0_116
	s_and_b64 vcc, exec, s[16:17]
	s_cbranch_vccz .LBB0_119
	s_barrier

; #define PG8_STAGE(bufoff, gbase, voff) do { _Pragma("unroll") for (int _i = 0; _i < 2; ++_i) \
;         __builtin_amdgcn_global_load_lds((const unsigned*)((const char*)(gbase) + (voff)[_i]), (LAS unsigned*)(lds + (bufoff) + ldsw + _i * 8192), 16, 0, 0); } while (0)
; #define PG8_LDA(dst, b, h) do { _Pragma("unroll") for (int m = 0; m < 4; ++m) _Pragma("unroll") for (int k = 0; k < 2; ++k) dst[m][k] = *(const LAS bf16x8*)(lds + PG8_SA(b, h) + aoff + m * 2048 + k * 1024); } while (0)
; #define PG8_LDB(dst, b, h) do { _Pragma("unroll") for (int n = 0; n < 2; ++n) _Pragma("unroll") for (int k = 0; k < 2; ++k) dst[n][k] = *(const LAS bf16x8*)(lds + PG8_SB(b, h) + boff + n * 2048 + k * 1024); } while (0)
; #define PG8_MMA(ai, bj, At, Bt) do { __builtin_amdgcn_s_setprio(1); _Pragma("unroll") for (int m = 0; m < 4; ++m) _Pragma("unroll") for (int n = 0; n < 2; ++n) _Pragma("unroll") for (int k = 0; k < 2; ++k) \
;         acc[ai][bj][m][n] = __builtin_amdgcn_mfma_f32_16x16x32_bf16(Bt[n][k], At[m][k], acc[ai][bj][m][n], 0, 0, 0); __builtin_amdgcn_s_setprio(0); } while (0)
; #define PG8_WAIT_V(n) asm volatile("s_waitcnt vmcnt(" #n ")" ::: "memory")
; #define PG8_WAIT_L(n) asm volatile("s_waitcnt lgkmcnt(" #n ")" ::: "memory")
; #define PG8_BAR __builtin_amdgcn_s_barrier()
; #define PG8_SCHED __builtin_amdgcn_sched_barrier(0)
; template <class Epi, bool ALIGN_EPI = true, bool SP2 = true>
; __device__ __forceinline__ void gemm_phase(LAS unsigned char* lds, const Gemm g, const StaticOrder& S, const Epi& E, const int wave_s) {
;     ...
;             PG8_LDB(B0, 0, 0); PG8_LDB(B1, 0, 1); PG8_SCHED; PG8_LDA(At, 0, 0); PG8_STAGE(PG8_SA(1, 1), a1 + hstep, voffA);
;             PG8_WAIT_V(8); PG8_WAIT_L(0); PG8_BAR; PG8_MMA(0, 0, At, B0); PG8_MMA(0, 1, At, B1); PG8_BAR; PG8_SCHED;
;             PG8_LDA(At, 0, 1); PG8_STAGE(PG8_SB(0, 0), b2, voffB); PG8_STAGE(PG8_SB(0, 1), b2 + hstep, voffB); PG8_STAGE(PG8_SA(0, 0), a2, voffA);
;             PG8_WAIT_V(8); PG8_WAIT_L(0); PG8_BAR; PG8_MMA(1, 0, At, B0); PG8_MMA(1, 1, At, B1); PG8_BAR; PG8_SCHED;
.LBB0_477:
	ds_read_b128 v[128:131], v252
	ds_read_b128 v[132:135], v252 offset:1024
	ds_read_b128 v[136:139], v252 offset:2048
	ds_read_b128 v[140:143], v252 offset:3072
	ds_read_b128 v[144:147], v253
	ds_read_b128 v[148:151], v253 offset:1024
	ds_read_b128 v[152:155], v253 offset:2048
	ds_read_b128 v[156:159], v253 offset:3072
	s_add_u32 s46, s44, 0xfffc0080
	s_addc_u32 s47, s45, -1
	s_cmp_eq_u32 s64, 12
	s_cselect_b32 s49, s31, s47
	s_cselect_b32 s48, s59, s46
	s_cselect_b32 s47, s29, s63
	s_cselect_b32 s46, s60, s62
	v_lshl_add_u64 v[192:193], s[44:45], 0, v[210:211]
	s_add_i32 m0, s39, 0xc000
	ds_read_b128 v[160:163], v254
	ds_read_b128 v[164:167], v254 offset:1024
	ds_read_b128 v[168:171], v254 offset:2048
	ds_read_b128 v[172:175], v254 offset:3072
	ds_read_b128 v[176:179], v254 offset:4096
	ds_read_b128 v[180:183], v254 offset:5120
	ds_read_b128 v[184:187], v254 offset:6144
	ds_read_b128 v[188:191], v254 offset:7168
	global_load_lds_dwordx4 v[192:193], off
	v_lshl_add_u64 v[192:193], s[44:45], 0, v[208:209]
	s_add_i32 m0, s39, 0xe000
	s_nop 0
	global_load_lds_dwordx4 v[192:193], off
	s_waitcnt vmcnt(8)
	s_waitcnt lgkmcnt(0)
	s_barrier
	s_setprio 1
	v_mfma_f32_16x16x32_bf16 v[124:127], v[128:131], v[160:163], v[124:127]
	v_mfma_f32_16x16x32_bf16 v[120:123], v[136:139], v[160:163], v[120:123]
	v_mfma_f32_16x16x32_bf16 v[116:119], v[128:131], v[168:171], v[116:119]
	v_mfma_f32_16x16x32_bf16 v[112:115], v[136:139], v[168:171], v[112:115]
	v_mfma_f32_16x16x32_bf16 v[108:111], v[128:131], v[176:179], v[108:111]
	v_mfma_f32_16x16x32_bf16 v[104:107], v[136:139], v[176:179], v[104:107]
	v_mfma_f32_16x16x32_bf16 v[100:103], v[128:131], v[184:187], v[100:103]
	v_mfma_f32_16x16x32_bf16 v[96:99], v[136:139], v[184:187], v[96:99]
	v_mfma_f32_16x16x32_bf16 v[124:127], v[132:135], v[164:167], v[124:127]
	v_mfma_f32_16x16x32_bf16 v[120:123], v[140:143], v[164:167], v[120:123]
	v_mfma_f32_16x16x32_bf16 v[116:119], v[132:135], v[172:175], v[116:119]
	v_mfma_f32_16x16x32_bf16 v[112:115], v[140:143], v[172:175], v[112:115]
	v_mfma_f32_16x16x32_bf16 v[108:111], v[132:135], v[180:183], v[108:111]
	v_mfma_f32_16x16x32_bf16 v[104:107], v[140:143], v[180:183], v[104:107]
	v_mfma_f32_16x16x32_bf16 v[100:103], v[132:135], v[188:191], v[100:103]
	v_mfma_f32_16x16x32_bf16 v[96:99], v[140:143], v[188:191], v[96:99]
	v_mfma_f32_16x16x32_bf16 v[60:63], v[144:147], v[160:163], v[60:63]
	v_mfma_f32_16x16x32_bf16 v[56:59], v[152:155], v[160:163], v[56:59]
	v_mfma_f32_16x16x32_bf16 v[52:55], v[144:147], v[168:171], v[52:55]
	v_mfma_f32_16x16x32_bf16 v[48:51], v[152:155], v[168:171], v[48:51]
	v_mfma_f32_16x16x32_bf16 v[44:47], v[144:147], v[176:179], v[44:47]
	v_mfma_f32_16x16x32_bf16 v[40:43], v[152:155], v[176:179], v[40:43]
	v_mfma_f32_16x16x32_bf16 v[36:39], v[144:147], v[184:187], v[36:39]
	v_mfma_f32_16x16x32_bf16 v[32:35], v[152:155], v[184:187], v[32:35]
	v_mfma_f32_16x16x32_bf16 v[60:63], v[148:151], v[164:167], v[60:63]
	v_mfma_f32_16x16x32_bf16 v[56:59], v[156:159], v[164:167], v[56:59]
	v_mfma_f32_16x16x32_bf16 v[52:55], v[148:151], v[172:175], v[52:55]
	v_mfma_f32_16x16x32_bf16 v[48:51], v[156:159], v[172:175], v[48:51]
	v_mfma_f32_16x16x32_bf16 v[44:47], v[148:151], v[180:183], v[44:47]
	v_mfma_f32_16x16x32_bf16 v[40:43], v[156:159], v[180:183], v[40:43]
	v_mfma_f32_16x16x32_bf16 v[36:39], v[148:151], v[188:191], v[36:39]
	v_mfma_f32_16x16x32_bf16 v[32:35], v[156:159], v[188:191], v[32:35]
	s_setprio 0
	s_barrier
	s_add_i32 s65, s57, s61
	v_lshl_add_u64 v[192:193], s[46:47], 0, v[202:203]
	s_mov_b32 m0, s65
	ds_read_b128 v[160:163], v254 offset:16384
	ds_read_b128 v[164:167], v254 offset:17408
	ds_read_b128 v[168:171], v254 offset:18432
	ds_read_b128 v[172:175], v254 offset:19456
	ds_read_b128 v[176:179], v254 offset:20480
	ds_read_b128 v[180:183], v254 offset:21504
	ds_read_b128 v[184:187], v254 offset:22528
	ds_read_b128 v[188:191], v254 offset:23552
	global_load_lds_dwordx4 v[192:193], off
	s_add_i32 m0, s65, 0x2000
	s_add_u32 s68, s46, 0x40000
	v_lshl_add_u64 v[194:195], s[46:47], 0, v[206:207]
	s_addc_u32 s69, s47, 0
	s_add_i32 s65, s58, s61
	global_load_lds_dwordx4 v[194:195], off
	v_lshl_add_u64 v[196:197], s[68:69], 0, v[202:203]
	s_mov_b32 m0, s65
	v_lshl_add_u64 v[198:199], s[48:49], 0, v[204:205]
	global_load_lds_dwordx4 v[196:197], off
	v_lshl_add_u64 v[196:197], s[68:69], 0, v[206:207]
	s_add_i32 m0, s65, 0x2000
	s_nop 0
	global_load_lds_dwordx4 v[196:197], off
	v_lshl_add_u64 v[196:197], s[48:49], 0, v[200:201]
	s_mov_b32 m0, s39
	s_nop 0
	global_load_lds_dwordx4 v[196:197], off
	s_mov_b32 m0, s40
	s_nop 0
	global_load_lds_dwordx4 v[198:199], off
	s_waitcnt vmcnt(8)
	s_waitcnt lgkmcnt(0)
	s_barrier
; #define PG8_STAGE(bufoff, gbase, voff) do { _Pragma("unroll") for (int _i = 0; _i < 2; ++_i) \
;         __builtin_amdgcn_global_load_lds((const unsigned*)((const char*)(gbase) + (voff)[_i]), (LAS unsigned*)(lds + (bufoff) + ldsw + _i * 8192), 16, 0, 0); } while (0)
; #define PG8_LDA(dst, b, h) do { _Pragma("unroll") for (int m = 0; m < 4; ++m) _Pragma("unroll") for (int k = 0; k < 2; ++k) dst[m][k] = *(const LAS bf16x8*)(lds + PG8_SA(b, h) + aoff + m * 2048 + k * 1024); } while (0)
; #define PG8_LDB(dst, b, h) do { _Pragma("unroll") for (int n = 0; n < 2; ++n) _Pragma("unroll") for (int k = 0; k < 2; ++k) dst[n][k] = *(const LAS bf16x8*)(lds + PG8_SB(b, h) + boff + n * 2048 + k * 1024); } while (0)
; #define PG8_MMA(ai, bj, At, Bt) do { __builtin_amdgcn_s_setprio(1); _Pragma("unroll") for (int m = 0; m < 4; ++m) _Pragma("unroll") for (int n = 0; n < 2; ++n) _Pragma("unroll") for (int k = 0; k < 2; ++k) \
;         acc[ai][bj][m][n] = __builtin_amdgcn_mfma_f32_16x16x32_bf16(Bt[n][k], At[m][k], acc[ai][bj][m][n], 0, 0, 0); __builtin_amdgcn_s_setprio(0); } while (0)
; #define PG8_WAIT_V(n) asm volatile("s_waitcnt vmcnt(" #n ")" ::: "memory")
; #define PG8_WAIT_L(n) asm volatile("s_waitcnt lgkmcnt(" #n ")" ::: "memory")
; #define PG8_BAR __builtin_amdgcn_s_barrier()
; #define PG8_SCHED __builtin_amdgcn_sched_barrier(0)
; template <class Epi, bool ALIGN_EPI = true, bool SP2 = true>
; __device__ __forceinline__ void gemm_phase(LAS unsigned char* lds, const Gemm g, const StaticOrder& S, const Epi& E, const int wave_s) {
;     ...
;             PG8_WAIT_V(8); PG8_WAIT_L(0); PG8_BAR; PG8_MMA(1, 0, At, B0); PG8_MMA(1, 1, At, B1); PG8_BAR; PG8_SCHED;
;             PG8_LDB(B0, 1, 0); PG8_LDB(B1, 1, 1); PG8_SCHED; PG8_LDA(At, 1, 0); PG8_STAGE(PG8_SA(0, 1), a2 + hstep, voffA);
;             PG8_WAIT_V(8); PG8_WAIT_L(0); PG8_BAR; PG8_MMA(0, 0, At, B0); PG8_MMA(0, 1, At, B1); PG8_BAR; PG8_SCHED;
	s_setprio 1
	v_mfma_f32_16x16x32_bf16 v[92:95], v[128:131], v[160:163], v[92:95]
	v_mfma_f32_16x16x32_bf16 v[88:91], v[136:139], v[160:163], v[88:91]
	v_mfma_f32_16x16x32_bf16 v[84:87], v[128:131], v[168:171], v[84:87]
	v_mfma_f32_16x16x32_bf16 v[80:83], v[136:139], v[168:171], v[80:83]
	v_mfma_f32_16x16x32_bf16 v[76:79], v[128:131], v[176:179], v[76:79]
	v_mfma_f32_16x16x32_bf16 v[72:75], v[136:139], v[176:179], v[72:75]
	v_mfma_f32_16x16x32_bf16 v[68:71], v[128:131], v[184:187], v[68:71]
	v_mfma_f32_16x16x32_bf16 v[64:67], v[136:139], v[184:187], v[64:67]
	v_mfma_f32_16x16x32_bf16 v[92:95], v[132:135], v[164:167], v[92:95]
	v_mfma_f32_16x16x32_bf16 v[88:91], v[140:143], v[164:167], v[88:91]
	v_mfma_f32_16x16x32_bf16 v[84:87], v[132:135], v[172:175], v[84:87]
	v_mfma_f32_16x16x32_bf16 v[80:83], v[140:143], v[172:175], v[80:83]
	v_mfma_f32_16x16x32_bf16 v[76:79], v[132:135], v[180:183], v[76:79]
	v_mfma_f32_16x16x32_bf16 v[72:75], v[140:143], v[180:183], v[72:75]
	v_mfma_f32_16x16x32_bf16 v[68:71], v[132:135], v[188:191], v[68:71]
	v_mfma_f32_16x16x32_bf16 v[64:67], v[140:143], v[188:191], v[64:67]
	v_mfma_f32_16x16x32_bf16 v[28:31], v[144:147], v[160:163], v[28:31]
	v_mfma_f32_16x16x32_bf16 v[24:27], v[152:155], v[160:163], v[24:27]
	v_mfma_f32_16x16x32_bf16 v[20:23], v[144:147], v[168:171], v[20:23]
	v_mfma_f32_16x16x32_bf16 v[16:19], v[152:155], v[168:171], v[16:19]
	v_mfma_f32_16x16x32_bf16 v[12:15], v[144:147], v[176:179], v[12:15]
	v_mfma_f32_16x16x32_bf16 v[8:11], v[152:155], v[176:179], v[8:11]
	v_mfma_f32_16x16x32_bf16 v[4:7], v[144:147], v[184:187], v[4:7]
	v_mfma_f32_16x16x32_bf16 v[0:3], v[152:155], v[184:187], v[0:3]
	v_mfma_f32_16x16x32_bf16 v[28:31], v[148:151], v[164:167], v[28:31]
	v_mfma_f32_16x16x32_bf16 v[24:27], v[156:159], v[164:167], v[24:27]
	v_mfma_f32_16x16x32_bf16 v[20:23], v[148:151], v[172:175], v[20:23]
	v_mfma_f32_16x16x32_bf16 v[16:19], v[156:159], v[172:175], v[16:19]
	v_mfma_f32_16x16x32_bf16 v[12:15], v[148:151], v[180:183], v[12:15]
	v_mfma_f32_16x16x32_bf16 v[8:11], v[156:159], v[180:183], v[8:11]
	v_mfma_f32_16x16x32_bf16 v[4:7], v[148:151], v[188:191], v[4:7]
	v_mfma_f32_16x16x32_bf16 v[0:3], v[156:159], v[188:191], v[0:3]
	s_setprio 0
	s_barrier
	s_add_i32 s65, 0, 0x18000
	s_add_i32 s66, 0, 0x1c000
	v_add_u32_e32 v140, s65, v250
	v_add_u32_e32 v156, s66, v250
	ds_read_b128 v[128:131], v140
	ds_read_b128 v[132:135], v140 offset:1024
	ds_read_b128 v[136:139], v140 offset:2048
	ds_read_b128 v[140:143], v140 offset:3072
	ds_read_b128 v[144:147], v156
	ds_read_b128 v[148:151], v156 offset:1024
	ds_read_b128 v[152:155], v156 offset:2048
	ds_read_b128 v[156:159], v156 offset:3072
	s_add_u32 s48, s48, 0x40000
	s_addc_u32 s49, s49, 0
	s_mov_b32 m0, s41
	v_lshl_add_u64 v[212:213], s[48:49], 0, v[200:201]
	ds_read_b128 v[160:163], v254 offset:32768
	ds_read_b128 v[164:167], v254 offset:33792
	ds_read_b128 v[168:171], v254 offset:34816
	ds_read_b128 v[172:175], v254 offset:35840
	ds_read_b128 v[176:179], v254 offset:36864
	ds_read_b128 v[180:183], v254 offset:37888
	ds_read_b128 v[184:187], v254 offset:38912
	ds_read_b128 v[188:191], v254 offset:39936
	global_load_lds_dwordx4 v[212:213], off
	v_lshl_add_u64 v[212:213], s[48:49], 0, v[204:205]
	s_mov_b32 m0, s50
	s_nop 0
	global_load_lds_dwordx4 v[212:213], off
	s_waitcnt vmcnt(8)
	s_waitcnt lgkmcnt(0)
	s_barrier
	s_setprio 1
	v_mfma_f32_16x16x32_bf16 v[124:127], v[128:131], v[160:163], v[124:127]
	v_mfma_f32_16x16x32_bf16 v[120:123], v[136:139], v[160:163], v[120:123]
	v_mfma_f32_16x16x32_bf16 v[116:119], v[128:131], v[168:171], v[116:119]
	v_mfma_f32_16x16x32_bf16 v[112:115], v[136:139], v[168:171], v[112:115]
	v_mfma_f32_16x16x32_bf16 v[108:111], v[128:131], v[176:179], v[108:111]
	v_mfma_f32_16x16x32_bf16 v[104:107], v[136:139], v[176:179], v[104:107]
	v_mfma_f32_16x16x32_bf16 v[100:103], v[128:131], v[184:187], v[100:103]
	v_mfma_f32_16x16x32_bf16 v[96:99], v[136:139], v[184:187], v[96:99]
	v_mfma_f32_16x16x32_bf16 v[124:127], v[132:135], v[164:167], v[124:127]
	v_mfma_f32_16x16x32_bf16 v[120:123], v[140:143], v[164:167], v[120:123]
	v_mfma_f32_16x16x32_bf16 v[116:119], v[132:135], v[172:175], v[116:119]
	v_mfma_f32_16x16x32_bf16 v[112:115], v[140:143], v[172:175], v[112:115]
	v_mfma_f32_16x16x32_bf16 v[108:111], v[132:135], v[180:183], v[108:111]
	v_mfma_f32_16x16x32_bf16 v[104:107], v[140:143], v[180:183], v[104:107]
	v_mfma_f32_16x16x32_bf16 v[100:103], v[132:135], v[188:191], v[100:103]
	v_mfma_f32_16x16x32_bf16 v[96:99], v[140:143], v[188:191], v[96:99]
	v_mfma_f32_16x16x32_bf16 v[60:63], v[144:147], v[160:163], v[60:63]
	v_mfma_f32_16x16x32_bf16 v[56:59], v[152:155], v[160:163], v[56:59]
	v_mfma_f32_16x16x32_bf16 v[52:55], v[144:147], v[168:171], v[52:55]
	v_mfma_f32_16x16x32_bf16 v[48:51], v[152:155], v[168:171], v[48:51]
	v_mfma_f32_16x16x32_bf16 v[44:47], v[144:147], v[176:179], v[44:47]
	v_mfma_f32_16x16x32_bf16 v[40:43], v[152:155], v[176:179], v[40:43]
	v_mfma_f32_16x16x32_bf16 v[36:39], v[144:147], v[184:187], v[36:39]
	v_mfma_f32_16x16x32_bf16 v[32:35], v[152:155], v[184:187], v[32:35]
	v_mfma_f32_16x16x32_bf16 v[60:63], v[148:151], v[164:167], v[60:63]
	v_mfma_f32_16x16x32_bf16 v[56:59], v[156:159], v[164:167], v[56:59]
	v_mfma_f32_16x16x32_bf16 v[52:55], v[148:151], v[172:175], v[52:55]
	v_mfma_f32_16x16x32_bf16 v[48:51], v[156:159], v[172:175], v[48:51]
	v_mfma_f32_16x16x32_bf16 v[44:47], v[148:151], v[180:183], v[44:47]
	v_mfma_f32_16x16x32_bf16 v[40:43], v[156:159], v[180:183], v[40:43]
	v_mfma_f32_16x16x32_bf16 v[36:39], v[148:151], v[188:191], v[36:39]
	v_mfma_f32_16x16x32_bf16 v[32:35], v[156:159], v[188:191], v[32:35]
	s_setprio 0
	s_barrier
; #define PG8_STAGE(bufoff, gbase, voff) do { _Pragma("unroll") for (int _i = 0; _i < 2; ++_i) \
;         __builtin_amdgcn_global_load_lds((const unsigned*)((const char*)(gbase) + (voff)[_i]), (LAS unsigned*)(lds + (bufoff) + ldsw + _i * 8192), 16, 0, 0); } while (0)
; #define PG8_LDA(dst, b, h) do { _Pragma("unroll") for (int m = 0; m < 4; ++m) _Pragma("unroll") for (int k = 0; k < 2; ++k) dst[m][k] = *(const LAS bf16x8*)(lds + PG8_SA(b, h) + aoff + m * 2048 + k * 1024); } while (0)
; #define PG8_MMA(ai, bj, At, Bt) do { __builtin_amdgcn_s_setprio(1); _Pragma("unroll") for (int m = 0; m < 4; ++m) _Pragma("unroll") for (int n = 0; n < 2; ++n) _Pragma("unroll") for (int k = 0; k < 2; ++k) \
;         acc[ai][bj][m][n] = __builtin_amdgcn_mfma_f32_16x16x32_bf16(Bt[n][k], At[m][k], acc[ai][bj][m][n], 0, 0, 0); __builtin_amdgcn_s_setprio(0); } while (0)
; #define PG8_WAIT_V(n) asm volatile("s_waitcnt vmcnt(" #n ")" ::: "memory")
; #define PG8_WAIT_L(n) asm volatile("s_waitcnt lgkmcnt(" #n ")" ::: "memory")
; #define PG8_BAR __builtin_amdgcn_s_barrier()
; #define PG8_SCHED __builtin_amdgcn_sched_barrier(0)
; template <class Epi, bool ALIGN_EPI = true, bool SP2 = true>
; __device__ __forceinline__ void gemm_phase(LAS unsigned char* lds, const Gemm g, const StaticOrder& S, const Epi& E, const int wave_s) {
;     ...
;             PG8_LDA(At, 1, 1); PG8_STAGE(PG8_SB(1, 0), b3, voffB); PG8_STAGE(PG8_SB(1, 1), b3 + hstep, voffB); PG8_STAGE(PG8_SA(1, 0), a3, voffA);
;             PG8_WAIT_V(8); PG8_WAIT_L(0); PG8_BAR; PG8_MMA(1, 0, At, B0); PG8_MMA(1, 1, At, B1); PG8_BAR; PG8_SCHED;
;     ...
;         if constexpr (ALIGN_EPI) { if (wr == 0) PG8_BAR; }
	s_add_i32 s48, s65, s61
	v_lshl_add_u64 v[192:193], v[192:193], 0, s[14:15]
	s_mov_b32 m0, s48
	ds_read_b128 v[160:163], v254 offset:49152
	ds_read_b128 v[164:167], v254 offset:50176
	ds_read_b128 v[168:171], v254 offset:51200
	ds_read_b128 v[172:175], v254 offset:52224
	ds_read_b128 v[176:179], v254 offset:53248
	ds_read_b128 v[180:183], v254 offset:54272
	ds_read_b128 v[184:187], v254 offset:55296
	ds_read_b128 v[188:191], v254 offset:56320
	global_load_lds_dwordx4 v[192:193], off
	s_add_i32 m0, s48, 0x2000
	s_add_u32 s46, s46, 0x40080
	v_lshl_add_u64 v[192:193], v[194:195], 0, s[14:15]
	s_addc_u32 s47, s47, 0
	s_add_i32 s48, s66, s61
	global_load_lds_dwordx4 v[192:193], off
	v_lshl_add_u64 v[192:193], s[46:47], 0, v[202:203]
	s_mov_b32 m0, s48
	s_nop 0
	global_load_lds_dwordx4 v[192:193], off
	v_lshl_add_u64 v[192:193], s[46:47], 0, v[206:207]
	s_add_i32 m0, s48, 0x2000
	s_nop 0
	global_load_lds_dwordx4 v[192:193], off
	v_lshl_add_u64 v[192:193], v[196:197], 0, s[14:15]
	s_mov_b32 m0, s54
	s_nop 0
	global_load_lds_dwordx4 v[192:193], off
	v_lshl_add_u64 v[192:193], v[198:199], 0, s[14:15]
	s_mov_b32 m0, s55
	s_nop 0
	global_load_lds_dwordx4 v[192:193], off
	s_waitcnt vmcnt(8)
	s_waitcnt lgkmcnt(0)
	s_barrier
	s_setprio 1
	v_mfma_f32_16x16x32_bf16 v[92:95], v[128:131], v[160:163], v[92:95]
	v_mfma_f32_16x16x32_bf16 v[88:91], v[136:139], v[160:163], v[88:91]
	v_mfma_f32_16x16x32_bf16 v[84:87], v[128:131], v[168:171], v[84:87]
	v_mfma_f32_16x16x32_bf16 v[80:83], v[136:139], v[168:171], v[80:83]
	v_mfma_f32_16x16x32_bf16 v[76:79], v[128:131], v[176:179], v[76:79]
	v_mfma_f32_16x16x32_bf16 v[72:75], v[136:139], v[176:179], v[72:75]
	v_mfma_f32_16x16x32_bf16 v[68:71], v[128:131], v[184:187], v[68:71]
	v_mfma_f32_16x16x32_bf16 v[64:67], v[136:139], v[184:187], v[64:67]
	v_mfma_f32_16x16x32_bf16 v[92:95], v[132:135], v[164:167], v[92:95]
	v_mfma_f32_16x16x32_bf16 v[88:91], v[140:143], v[164:167], v[88:91]
	v_mfma_f32_16x16x32_bf16 v[84:87], v[132:135], v[172:175], v[84:87]
	v_mfma_f32_16x16x32_bf16 v[80:83], v[140:143], v[172:175], v[80:83]
	v_mfma_f32_16x16x32_bf16 v[76:79], v[132:135], v[180:183], v[76:79]
	v_mfma_f32_16x16x32_bf16 v[72:75], v[140:143], v[180:183], v[72:75]
	v_mfma_f32_16x16x32_bf16 v[68:71], v[132:135], v[188:191], v[68:71]
	v_mfma_f32_16x16x32_bf16 v[64:67], v[140:143], v[188:191], v[64:67]
	v_mfma_f32_16x16x32_bf16 v[28:31], v[144:147], v[160:163], v[28:31]
	v_mfma_f32_16x16x32_bf16 v[24:27], v[152:155], v[160:163], v[24:27]
	v_mfma_f32_16x16x32_bf16 v[20:23], v[144:147], v[168:171], v[20:23]
	v_mfma_f32_16x16x32_bf16 v[16:19], v[152:155], v[168:171], v[16:19]
	v_mfma_f32_16x16x32_bf16 v[12:15], v[144:147], v[176:179], v[12:15]
	v_mfma_f32_16x16x32_bf16 v[8:11], v[152:155], v[176:179], v[8:11]
	v_mfma_f32_16x16x32_bf16 v[4:7], v[144:147], v[184:187], v[4:7]
	v_mfma_f32_16x16x32_bf16 v[0:3], v[152:155], v[184:187], v[0:3]
	v_mfma_f32_16x16x32_bf16 v[28:31], v[148:151], v[164:167], v[28:31]
	v_mfma_f32_16x16x32_bf16 v[24:27], v[156:159], v[164:167], v[24:27]
	v_mfma_f32_16x16x32_bf16 v[20:23], v[148:151], v[172:175], v[20:23]
	v_mfma_f32_16x16x32_bf16 v[16:19], v[156:159], v[172:175], v[16:19]
	v_mfma_f32_16x16x32_bf16 v[12:15], v[148:151], v[180:183], v[12:15]
	v_mfma_f32_16x16x32_bf16 v[8:11], v[156:159], v[180:183], v[8:11]
	v_mfma_f32_16x16x32_bf16 v[4:7], v[148:151], v[188:191], v[4:7]
	v_mfma_f32_16x16x32_bf16 v[0:3], v[156:159], v[188:191], v[0:3]
	s_setprio 0
	s_barrier
	s_add_i32 s64, s64, 2
	s_add_u32 s62, s62, 0x100
	s_addc_u32 s63, s63, 0
	s_add_u32 s44, s44, 0x100
	s_addc_u32 s45, s45, 0
	s_cmp_gt_u32 s64, 13
	s_cbranch_scc0 .LBB0_477
	s_and_b64 vcc, exec, s[16:17]
	s_cbranch_vccz .LBB0_480
	s_barrier

; #define PG8_STAGE(bufoff, gbase, voff) do { _Pragma("unroll") for (int _i = 0; _i < 2; ++_i) \
;         __builtin_amdgcn_global_load_lds((const unsigned*)((const char*)(gbase) + (voff)[_i]), (LAS unsigned*)(lds + (bufoff) + ldsw + _i * 8192), 16, 0, 0); } while (0)
; #define PG8_LDA(dst, b, h) do { _Pragma("unroll") for (int m = 0; m < 4; ++m) _Pragma("unroll") for (int k = 0; k < 2; ++k) dst[m][k] = *(const LAS bf16x8*)(lds + PG8_SA(b, h) + aoff + m * 2048 + k * 1024); } while (0)
; #define PG8_LDB(dst, b, h) do { _Pragma("unroll") for (int n = 0; n < 2; ++n) _Pragma("unroll") for (int k = 0; k < 2; ++k) dst[n][k] = *(const LAS bf16x8*)(lds + PG8_SB(b, h) + boff + n * 2048 + k * 1024); } while (0)
; #define PG8_MMA(ai, bj, At, Bt) do { __builtin_amdgcn_s_setprio(1); _Pragma("unroll") for (int m = 0; m < 4; ++m) _Pragma("unroll") for (int n = 0; n < 2; ++n) _Pragma("unroll") for (int k = 0; k < 2; ++k) \
;         acc[ai][bj][m][n] = __builtin_amdgcn_mfma_f32_16x16x32_bf16(Bt[n][k], At[m][k], acc[ai][bj][m][n], 0, 0, 0); __builtin_amdgcn_s_setprio(0); } while (0)
; #define PG8_WAIT_V(n) asm volatile("s_waitcnt vmcnt(" #n ")" ::: "memory")
; #define PG8_WAIT_L(n) asm volatile("s_waitcnt lgkmcnt(" #n ")" ::: "memory")
; #define PG8_BAR __builtin_amdgcn_s_barrier()
; #define PG8_SCHED __builtin_amdgcn_sched_barrier(0)
; template <class Epi, bool ALIGN_EPI = true, bool SP2 = true>
; __device__ __forceinline__ void gemm_phase(LAS unsigned char* lds, const Gemm g, const StaticOrder& S, const Epi& E, const int wave_s) {
;     ...
;             PG8_LDB(B0, 0, 0); PG8_LDB(B1, 0, 1); PG8_SCHED; PG8_LDA(At, 0, 0); PG8_STAGE(PG8_SA(1, 1), a1 + hstep, voffA);
;             PG8_WAIT_V(8); PG8_WAIT_L(0); PG8_BAR; PG8_MMA(0, 0, At, B0); PG8_MMA(0, 1, At, B1); PG8_BAR; PG8_SCHED;
;             PG8_LDA(At, 0, 1); PG8_STAGE(PG8_SB(0, 0), b2, voffB); PG8_STAGE(PG8_SB(0, 1), b2 + hstep, voffB); PG8_STAGE(PG8_SA(0, 0), a2, voffA);
;             PG8_WAIT_V(8); PG8_WAIT_L(0); PG8_BAR; PG8_MMA(1, 0, At, B0); PG8_MMA(1, 1, At, B1); PG8_BAR; PG8_SCHED;
.LBB0_616:
	ds_read_b128 v[152:155], v149
	ds_read_b128 v[156:159], v149 offset:1024
	ds_read_b128 v[160:163], v149 offset:2048
	ds_read_b128 v[164:167], v149 offset:3072
	ds_read_b128 v[168:171], v150
	ds_read_b128 v[172:175], v150 offset:1024
	ds_read_b128 v[176:179], v150 offset:2048
	ds_read_b128 v[180:183], v150 offset:3072
	s_add_u32 s28, s26, 0xfffc0080
	s_addc_u32 s29, s27, -1
	s_cmp_eq_u32 s52, 12
	s_cselect_b32 s31, s19, s29
	s_cselect_b32 s30, s48, s28
	s_cselect_b32 s29, s17, s51
	s_cselect_b32 s28, s49, s50
	v_lshl_add_u64 v[144:145], s[26:27], 0, v[138:139]
	s_add_i32 m0, s25, 0xc000
	ds_read_b128 v[184:187], v151
	ds_read_b128 v[188:191], v151 offset:1024
	ds_read_b128 v[192:195], v151 offset:2048
	ds_read_b128 v[196:199], v151 offset:3072
	ds_read_b128 v[200:203], v151 offset:4096
	ds_read_b128 v[204:207], v151 offset:5120
	ds_read_b128 v[208:211], v151 offset:6144
	ds_read_b128 v[212:215], v151 offset:7168
	global_load_lds_dwordx4 v[144:145], off
	v_lshl_add_u64 v[144:145], s[26:27], 0, v[136:137]
	s_add_i32 m0, s25, 0xe000
	s_nop 0
	global_load_lds_dwordx4 v[144:145], off
	s_waitcnt vmcnt(8)
	s_waitcnt lgkmcnt(0)
	s_barrier
	s_setprio 1
	v_mfma_f32_16x16x32_bf16 v[124:127], v[152:155], v[184:187], v[124:127]
	v_mfma_f32_16x16x32_bf16 v[120:123], v[160:163], v[184:187], v[120:123]
	v_mfma_f32_16x16x32_bf16 v[108:111], v[152:155], v[192:195], v[108:111]
	v_mfma_f32_16x16x32_bf16 v[104:107], v[160:163], v[192:195], v[104:107]
	v_mfma_f32_16x16x32_bf16 v[92:95], v[152:155], v[200:203], v[92:95]
	v_mfma_f32_16x16x32_bf16 v[88:91], v[160:163], v[200:203], v[88:91]
	v_mfma_f32_16x16x32_bf16 v[76:79], v[152:155], v[208:211], v[76:79]
	v_mfma_f32_16x16x32_bf16 v[72:75], v[160:163], v[208:211], v[72:75]
	v_mfma_f32_16x16x32_bf16 v[124:127], v[156:159], v[188:191], v[124:127]
	v_mfma_f32_16x16x32_bf16 v[120:123], v[164:167], v[188:191], v[120:123]
	v_mfma_f32_16x16x32_bf16 v[108:111], v[156:159], v[196:199], v[108:111]
	v_mfma_f32_16x16x32_bf16 v[104:107], v[164:167], v[196:199], v[104:107]
	v_mfma_f32_16x16x32_bf16 v[92:95], v[156:159], v[204:207], v[92:95]
	v_mfma_f32_16x16x32_bf16 v[88:91], v[164:167], v[204:207], v[88:91]
	v_mfma_f32_16x16x32_bf16 v[76:79], v[156:159], v[212:215], v[76:79]
	v_mfma_f32_16x16x32_bf16 v[72:75], v[164:167], v[212:215], v[72:75]
	v_mfma_f32_16x16x32_bf16 v[116:119], v[168:171], v[184:187], v[116:119]
	v_mfma_f32_16x16x32_bf16 v[112:115], v[176:179], v[184:187], v[112:115]
	v_mfma_f32_16x16x32_bf16 v[100:103], v[168:171], v[192:195], v[100:103]
	v_mfma_f32_16x16x32_bf16 v[96:99], v[176:179], v[192:195], v[96:99]
	v_mfma_f32_16x16x32_bf16 v[84:87], v[168:171], v[200:203], v[84:87]
	v_mfma_f32_16x16x32_bf16 v[80:83], v[176:179], v[200:203], v[80:83]
	v_mfma_f32_16x16x32_bf16 v[68:71], v[168:171], v[208:211], v[68:71]
	v_mfma_f32_16x16x32_bf16 v[64:67], v[176:179], v[208:211], v[64:67]
	v_mfma_f32_16x16x32_bf16 v[116:119], v[172:175], v[188:191], v[116:119]
	v_mfma_f32_16x16x32_bf16 v[112:115], v[180:183], v[188:191], v[112:115]
	v_mfma_f32_16x16x32_bf16 v[100:103], v[172:175], v[196:199], v[100:103]
	v_mfma_f32_16x16x32_bf16 v[96:99], v[180:183], v[196:199], v[96:99]
	v_mfma_f32_16x16x32_bf16 v[84:87], v[172:175], v[204:207], v[84:87]
	v_mfma_f32_16x16x32_bf16 v[80:83], v[180:183], v[204:207], v[80:83]
	v_mfma_f32_16x16x32_bf16 v[68:71], v[172:175], v[212:215], v[68:71]
	v_mfma_f32_16x16x32_bf16 v[64:67], v[180:183], v[212:215], v[64:67]
	s_setprio 0
	s_barrier
	s_add_i32 s53, s44, s61
	v_lshl_add_u64 v[144:145], s[28:29], 0, v[132:133]
	s_mov_b32 m0, s53
	ds_read_b128 v[184:187], v151 offset:16384
	ds_read_b128 v[188:191], v151 offset:17408
	ds_read_b128 v[192:195], v151 offset:18432
	ds_read_b128 v[196:199], v151 offset:19456
	ds_read_b128 v[200:203], v151 offset:20480
	ds_read_b128 v[204:207], v151 offset:21504
	ds_read_b128 v[208:211], v151 offset:22528
	ds_read_b128 v[212:215], v151 offset:23552
	global_load_lds_dwordx4 v[144:145], off
	s_add_i32 m0, s53, 0x2000
	s_add_u32 s54, s28, 0x40000
	v_lshl_add_u64 v[216:217], s[28:29], 0, v[128:129]
	s_addc_u32 s55, s29, 0
	s_add_i32 s53, s45, s61
	global_load_lds_dwordx4 v[216:217], off
	v_lshl_add_u64 v[218:219], s[54:55], 0, v[132:133]
	s_mov_b32 m0, s53
	v_lshl_add_u64 v[220:221], s[30:31], 0, v[130:131]
	global_load_lds_dwordx4 v[218:219], off
	v_lshl_add_u64 v[218:219], s[54:55], 0, v[128:129]
	s_add_i32 m0, s53, 0x2000
	s_nop 0
	global_load_lds_dwordx4 v[218:219], off
	v_lshl_add_u64 v[218:219], s[30:31], 0, v[134:135]
	s_mov_b32 m0, s25
	s_nop 0
	global_load_lds_dwordx4 v[218:219], off
	s_mov_b32 m0, s37
	s_nop 0
	global_load_lds_dwordx4 v[220:221], off
	s_waitcnt vmcnt(8)
	s_waitcnt lgkmcnt(0)
	s_barrier
; #define PG8_STAGE(bufoff, gbase, voff) do { _Pragma("unroll") for (int _i = 0; _i < 2; ++_i) \
;         __builtin_amdgcn_global_load_lds((const unsigned*)((const char*)(gbase) + (voff)[_i]), (LAS unsigned*)(lds + (bufoff) + ldsw + _i * 8192), 16, 0, 0); } while (0)
; #define PG8_LDA(dst, b, h) do { _Pragma("unroll") for (int m = 0; m < 4; ++m) _Pragma("unroll") for (int k = 0; k < 2; ++k) dst[m][k] = *(const LAS bf16x8*)(lds + PG8_SA(b, h) + aoff + m * 2048 + k * 1024); } while (0)
; #define PG8_LDB(dst, b, h) do { _Pragma("unroll") for (int n = 0; n < 2; ++n) _Pragma("unroll") for (int k = 0; k < 2; ++k) dst[n][k] = *(const LAS bf16x8*)(lds + PG8_SB(b, h) + boff + n * 2048 + k * 1024); } while (0)
; #define PG8_MMA(ai, bj, At, Bt) do { __builtin_amdgcn_s_setprio(1); _Pragma("unroll") for (int m = 0; m < 4; ++m) _Pragma("unroll") for (int n = 0; n < 2; ++n) _Pragma("unroll") for (int k = 0; k < 2; ++k) \
;         acc[ai][bj][m][n] = __builtin_amdgcn_mfma_f32_16x16x32_bf16(Bt[n][k], At[m][k], acc[ai][bj][m][n], 0, 0, 0); __builtin_amdgcn_s_setprio(0); } while (0)
; #define PG8_WAIT_V(n) asm volatile("s_waitcnt vmcnt(" #n ")" ::: "memory")
; #define PG8_WAIT_L(n) asm volatile("s_waitcnt lgkmcnt(" #n ")" ::: "memory")
; #define PG8_BAR __builtin_amdgcn_s_barrier()
; #define PG8_SCHED __builtin_amdgcn_sched_barrier(0)
; template <class Epi, bool ALIGN_EPI = true, bool SP2 = true>
; __device__ __forceinline__ void gemm_phase(LAS unsigned char* lds, const Gemm g, const StaticOrder& S, const Epi& E, const int wave_s) {
;     ...
;             PG8_WAIT_V(8); PG8_WAIT_L(0); PG8_BAR; PG8_MMA(1, 0, At, B0); PG8_MMA(1, 1, At, B1); PG8_BAR; PG8_SCHED;
;             PG8_LDB(B0, 1, 0); PG8_LDB(B1, 1, 1); PG8_SCHED; PG8_LDA(At, 1, 0); PG8_STAGE(PG8_SA(0, 1), a2 + hstep, voffA);
;             PG8_WAIT_V(8); PG8_WAIT_L(0); PG8_BAR; PG8_MMA(0, 0, At, B0); PG8_MMA(0, 1, At, B1); PG8_BAR; PG8_SCHED;
	s_setprio 1
	v_mfma_f32_16x16x32_bf16 v[60:63], v[152:155], v[184:187], v[60:63]
	v_mfma_f32_16x16x32_bf16 v[56:59], v[160:163], v[184:187], v[56:59]
	v_mfma_f32_16x16x32_bf16 v[44:47], v[152:155], v[192:195], v[44:47]
	v_mfma_f32_16x16x32_bf16 v[40:43], v[160:163], v[192:195], v[40:43]
	v_mfma_f32_16x16x32_bf16 v[28:31], v[152:155], v[200:203], v[28:31]
	v_mfma_f32_16x16x32_bf16 v[24:27], v[160:163], v[200:203], v[24:27]
	v_mfma_f32_16x16x32_bf16 v[12:15], v[152:155], v[208:211], v[12:15]
	v_mfma_f32_16x16x32_bf16 v[8:11], v[160:163], v[208:211], v[8:11]
	v_mfma_f32_16x16x32_bf16 v[60:63], v[156:159], v[188:191], v[60:63]
	v_mfma_f32_16x16x32_bf16 v[56:59], v[164:167], v[188:191], v[56:59]
	v_mfma_f32_16x16x32_bf16 v[44:47], v[156:159], v[196:199], v[44:47]
	v_mfma_f32_16x16x32_bf16 v[40:43], v[164:167], v[196:199], v[40:43]
	v_mfma_f32_16x16x32_bf16 v[28:31], v[156:159], v[204:207], v[28:31]
	v_mfma_f32_16x16x32_bf16 v[24:27], v[164:167], v[204:207], v[24:27]
	v_mfma_f32_16x16x32_bf16 v[12:15], v[156:159], v[212:215], v[12:15]
	v_mfma_f32_16x16x32_bf16 v[8:11], v[164:167], v[212:215], v[8:11]
	v_mfma_f32_16x16x32_bf16 v[52:55], v[168:171], v[184:187], v[52:55]
	v_mfma_f32_16x16x32_bf16 v[48:51], v[176:179], v[184:187], v[48:51]
	v_mfma_f32_16x16x32_bf16 v[36:39], v[168:171], v[192:195], v[36:39]
	v_mfma_f32_16x16x32_bf16 v[32:35], v[176:179], v[192:195], v[32:35]
	v_mfma_f32_16x16x32_bf16 v[20:23], v[168:171], v[200:203], v[20:23]
	v_mfma_f32_16x16x32_bf16 v[16:19], v[176:179], v[200:203], v[16:19]
	v_mfma_f32_16x16x32_bf16 v[4:7], v[168:171], v[208:211], v[4:7]
	v_mfma_f32_16x16x32_bf16 v[0:3], v[176:179], v[208:211], v[0:3]
	v_mfma_f32_16x16x32_bf16 v[52:55], v[172:175], v[188:191], v[52:55]
	v_mfma_f32_16x16x32_bf16 v[48:51], v[180:183], v[188:191], v[48:51]
	v_mfma_f32_16x16x32_bf16 v[36:39], v[172:175], v[196:199], v[36:39]
	v_mfma_f32_16x16x32_bf16 v[32:35], v[180:183], v[196:199], v[32:35]
	v_mfma_f32_16x16x32_bf16 v[20:23], v[172:175], v[204:207], v[20:23]
	v_mfma_f32_16x16x32_bf16 v[16:19], v[180:183], v[204:207], v[16:19]
	v_mfma_f32_16x16x32_bf16 v[4:7], v[172:175], v[212:215], v[4:7]
	v_mfma_f32_16x16x32_bf16 v[0:3], v[180:183], v[212:215], v[0:3]
	s_setprio 0
	s_barrier
	s_add_i32 s53, 0, 0x18000
	s_add_i32 s54, 0, 0x1c000
	v_add_u32_e32 v164, s53, v147
	v_add_u32_e32 v180, s54, v147
	ds_read_b128 v[152:155], v164
	ds_read_b128 v[156:159], v164 offset:1024
	ds_read_b128 v[160:163], v164 offset:2048
	ds_read_b128 v[164:167], v164 offset:3072
	ds_read_b128 v[168:171], v180
	ds_read_b128 v[172:175], v180 offset:1024
	ds_read_b128 v[176:179], v180 offset:2048
	ds_read_b128 v[180:183], v180 offset:3072
	s_add_u32 s30, s30, 0x40000
	s_addc_u32 s31, s31, 0
	s_mov_b32 m0, s38
	v_lshl_add_u64 v[222:223], s[30:31], 0, v[134:135]
	ds_read_b128 v[184:187], v151 offset:32768
	ds_read_b128 v[188:191], v151 offset:33792
	ds_read_b128 v[192:195], v151 offset:34816
	ds_read_b128 v[196:199], v151 offset:35840
	ds_read_b128 v[200:203], v151 offset:36864
	ds_read_b128 v[204:207], v151 offset:37888
	ds_read_b128 v[208:211], v151 offset:38912
	ds_read_b128 v[212:215], v151 offset:39936
	global_load_lds_dwordx4 v[222:223], off
	v_lshl_add_u64 v[222:223], s[30:31], 0, v[130:131]
	s_mov_b32 m0, s39
	s_nop 0
	global_load_lds_dwordx4 v[222:223], off
	s_waitcnt vmcnt(8)
	s_waitcnt lgkmcnt(0)
	s_barrier
	s_setprio 1
	v_mfma_f32_16x16x32_bf16 v[124:127], v[152:155], v[184:187], v[124:127]
	v_mfma_f32_16x16x32_bf16 v[120:123], v[160:163], v[184:187], v[120:123]
	v_mfma_f32_16x16x32_bf16 v[108:111], v[152:155], v[192:195], v[108:111]
	v_mfma_f32_16x16x32_bf16 v[104:107], v[160:163], v[192:195], v[104:107]
	v_mfma_f32_16x16x32_bf16 v[92:95], v[152:155], v[200:203], v[92:95]
	v_mfma_f32_16x16x32_bf16 v[88:91], v[160:163], v[200:203], v[88:91]
	v_mfma_f32_16x16x32_bf16 v[76:79], v[152:155], v[208:211], v[76:79]
	v_mfma_f32_16x16x32_bf16 v[72:75], v[160:163], v[208:211], v[72:75]
	v_mfma_f32_16x16x32_bf16 v[124:127], v[156:159], v[188:191], v[124:127]
	v_mfma_f32_16x16x32_bf16 v[120:123], v[164:167], v[188:191], v[120:123]
	v_mfma_f32_16x16x32_bf16 v[108:111], v[156:159], v[196:199], v[108:111]
	v_mfma_f32_16x16x32_bf16 v[104:107], v[164:167], v[196:199], v[104:107]
	v_mfma_f32_16x16x32_bf16 v[92:95], v[156:159], v[204:207], v[92:95]
	v_mfma_f32_16x16x32_bf16 v[88:91], v[164:167], v[204:207], v[88:91]
	v_mfma_f32_16x16x32_bf16 v[76:79], v[156:159], v[212:215], v[76:79]
	v_mfma_f32_16x16x32_bf16 v[72:75], v[164:167], v[212:215], v[72:75]
	v_mfma_f32_16x16x32_bf16 v[116:119], v[168:171], v[184:187], v[116:119]
	v_mfma_f32_16x16x32_bf16 v[112:115], v[176:179], v[184:187], v[112:115]
	v_mfma_f32_16x16x32_bf16 v[100:103], v[168:171], v[192:195], v[100:103]
	v_mfma_f32_16x16x32_bf16 v[96:99], v[176:179], v[192:195], v[96:99]
	v_mfma_f32_16x16x32_bf16 v[84:87], v[168:171], v[200:203], v[84:87]
	v_mfma_f32_16x16x32_bf16 v[80:83], v[176:179], v[200:203], v[80:83]
	v_mfma_f32_16x16x32_bf16 v[68:71], v[168:171], v[208:211], v[68:71]
	v_mfma_f32_16x16x32_bf16 v[64:67], v[176:179], v[208:211], v[64:67]
	v_mfma_f32_16x16x32_bf16 v[116:119], v[172:175], v[188:191], v[116:119]
	v_mfma_f32_16x16x32_bf16 v[112:115], v[180:183], v[188:191], v[112:115]
	v_mfma_f32_16x16x32_bf16 v[100:103], v[172:175], v[196:199], v[100:103]
	v_mfma_f32_16x16x32_bf16 v[96:99], v[180:183], v[196:199], v[96:99]
	v_mfma_f32_16x16x32_bf16 v[84:87], v[172:175], v[204:207], v[84:87]
	v_mfma_f32_16x16x32_bf16 v[80:83], v[180:183], v[204:207], v[80:83]
	v_mfma_f32_16x16x32_bf16 v[68:71], v[172:175], v[212:215], v[68:71]
	v_mfma_f32_16x16x32_bf16 v[64:67], v[180:183], v[212:215], v[64:67]
	s_setprio 0
	s_barrier
; #define PG8_STAGE(bufoff, gbase, voff) do { _Pragma("unroll") for (int _i = 0; _i < 2; ++_i) \
;         __builtin_amdgcn_global_load_lds((const unsigned*)((const char*)(gbase) + (voff)[_i]), (LAS unsigned*)(lds + (bufoff) + ldsw + _i * 8192), 16, 0, 0); } while (0)
; #define PG8_LDA(dst, b, h) do { _Pragma("unroll") for (int m = 0; m < 4; ++m) _Pragma("unroll") for (int k = 0; k < 2; ++k) dst[m][k] = *(const LAS bf16x8*)(lds + PG8_SA(b, h) + aoff + m * 2048 + k * 1024); } while (0)
; #define PG8_MMA(ai, bj, At, Bt) do { __builtin_amdgcn_s_setprio(1); _Pragma("unroll") for (int m = 0; m < 4; ++m) _Pragma("unroll") for (int n = 0; n < 2; ++n) _Pragma("unroll") for (int k = 0; k < 2; ++k) \
;         acc[ai][bj][m][n] = __builtin_amdgcn_mfma_f32_16x16x32_bf16(Bt[n][k], At[m][k], acc[ai][bj][m][n], 0, 0, 0); __builtin_amdgcn_s_setprio(0); } while (0)
; #define PG8_WAIT_V(n) asm volatile("s_waitcnt vmcnt(" #n ")" ::: "memory")
; #define PG8_WAIT_L(n) asm volatile("s_waitcnt lgkmcnt(" #n ")" ::: "memory")
; #define PG8_BAR __builtin_amdgcn_s_barrier()
; #define PG8_SCHED __builtin_amdgcn_sched_barrier(0)
; template <class Epi, bool ALIGN_EPI = true, bool SP2 = true>
; __device__ __forceinline__ void gemm_phase(LAS unsigned char* lds, const Gemm g, const StaticOrder& S, const Epi& E, const int wave_s) {
;     ...
;             PG8_LDA(At, 1, 1); PG8_STAGE(PG8_SB(1, 0), b3, voffB); PG8_STAGE(PG8_SB(1, 1), b3 + hstep, voffB); PG8_STAGE(PG8_SA(1, 0), a3, voffA);
;             PG8_WAIT_V(8); PG8_WAIT_L(0); PG8_BAR; PG8_MMA(1, 0, At, B0); PG8_MMA(1, 1, At, B1); PG8_BAR; PG8_SCHED;
;     ...
;         if constexpr (ALIGN_EPI) { if (wr == 0) PG8_BAR; }
	s_add_i32 s30, s53, s61
	v_lshl_add_u64 v[144:145], v[144:145], 0, s[10:11]
	s_mov_b32 m0, s30
	ds_read_b128 v[184:187], v151 offset:49152
	ds_read_b128 v[188:191], v151 offset:50176
	ds_read_b128 v[192:195], v151 offset:51200
	ds_read_b128 v[196:199], v151 offset:52224
	ds_read_b128 v[200:203], v151 offset:53248
	ds_read_b128 v[204:207], v151 offset:54272
	ds_read_b128 v[208:211], v151 offset:55296
	ds_read_b128 v[212:215], v151 offset:56320
	global_load_lds_dwordx4 v[144:145], off
	s_add_i32 m0, s30, 0x2000
	s_add_u32 s28, s28, 0x40080
	v_lshl_add_u64 v[144:145], v[216:217], 0, s[10:11]
	s_addc_u32 s29, s29, 0
	s_add_i32 s30, s54, s61
	global_load_lds_dwordx4 v[144:145], off
	v_lshl_add_u64 v[144:145], s[28:29], 0, v[132:133]
	s_mov_b32 m0, s30
	s_nop 0
	global_load_lds_dwordx4 v[144:145], off
	v_lshl_add_u64 v[144:145], s[28:29], 0, v[128:129]
	s_add_i32 m0, s30, 0x2000
	s_nop 0
	global_load_lds_dwordx4 v[144:145], off
	v_lshl_add_u64 v[144:145], v[218:219], 0, s[10:11]
	s_mov_b32 m0, s40
	s_nop 0
	global_load_lds_dwordx4 v[144:145], off
	v_lshl_add_u64 v[144:145], v[220:221], 0, s[10:11]
	s_mov_b32 m0, s41
	s_nop 0
	global_load_lds_dwordx4 v[144:145], off
	s_waitcnt vmcnt(8)
	s_waitcnt lgkmcnt(0)
	s_barrier
	s_setprio 1
	v_mfma_f32_16x16x32_bf16 v[60:63], v[152:155], v[184:187], v[60:63]
	v_mfma_f32_16x16x32_bf16 v[56:59], v[160:163], v[184:187], v[56:59]
	v_mfma_f32_16x16x32_bf16 v[44:47], v[152:155], v[192:195], v[44:47]
	v_mfma_f32_16x16x32_bf16 v[40:43], v[160:163], v[192:195], v[40:43]
	v_mfma_f32_16x16x32_bf16 v[28:31], v[152:155], v[200:203], v[28:31]
	v_mfma_f32_16x16x32_bf16 v[24:27], v[160:163], v[200:203], v[24:27]
	v_mfma_f32_16x16x32_bf16 v[12:15], v[152:155], v[208:211], v[12:15]
	v_mfma_f32_16x16x32_bf16 v[8:11], v[160:163], v[208:211], v[8:11]
	v_mfma_f32_16x16x32_bf16 v[60:63], v[156:159], v[188:191], v[60:63]
	v_mfma_f32_16x16x32_bf16 v[56:59], v[164:167], v[188:191], v[56:59]
	v_mfma_f32_16x16x32_bf16 v[44:47], v[156:159], v[196:199], v[44:47]
	v_mfma_f32_16x16x32_bf16 v[40:43], v[164:167], v[196:199], v[40:43]
	v_mfma_f32_16x16x32_bf16 v[28:31], v[156:159], v[204:207], v[28:31]
	v_mfma_f32_16x16x32_bf16 v[24:27], v[164:167], v[204:207], v[24:27]
	v_mfma_f32_16x16x32_bf16 v[12:15], v[156:159], v[212:215], v[12:15]
	v_mfma_f32_16x16x32_bf16 v[8:11], v[164:167], v[212:215], v[8:11]
	v_mfma_f32_16x16x32_bf16 v[52:55], v[168:171], v[184:187], v[52:55]
	v_mfma_f32_16x16x32_bf16 v[48:51], v[176:179], v[184:187], v[48:51]
	v_mfma_f32_16x16x32_bf16 v[36:39], v[168:171], v[192:195], v[36:39]
	v_mfma_f32_16x16x32_bf16 v[32:35], v[176:179], v[192:195], v[32:35]
	v_mfma_f32_16x16x32_bf16 v[20:23], v[168:171], v[200:203], v[20:23]
	v_mfma_f32_16x16x32_bf16 v[16:19], v[176:179], v[200:203], v[16:19]
	v_mfma_f32_16x16x32_bf16 v[4:7], v[168:171], v[208:211], v[4:7]
	v_mfma_f32_16x16x32_bf16 v[0:3], v[176:179], v[208:211], v[0:3]
	v_mfma_f32_16x16x32_bf16 v[52:55], v[172:175], v[188:191], v[52:55]
	v_mfma_f32_16x16x32_bf16 v[48:51], v[180:183], v[188:191], v[48:51]
	v_mfma_f32_16x16x32_bf16 v[36:39], v[172:175], v[196:199], v[36:39]
	v_mfma_f32_16x16x32_bf16 v[32:35], v[180:183], v[196:199], v[32:35]
	v_mfma_f32_16x16x32_bf16 v[20:23], v[172:175], v[204:207], v[20:23]
	v_mfma_f32_16x16x32_bf16 v[16:19], v[180:183], v[204:207], v[16:19]
	v_mfma_f32_16x16x32_bf16 v[4:7], v[172:175], v[212:215], v[4:7]
	v_mfma_f32_16x16x32_bf16 v[0:3], v[180:183], v[212:215], v[0:3]
	s_setprio 0
	s_barrier
	s_add_i32 s52, s52, 2
	s_add_u32 s50, s50, 0x100
	s_addc_u32 s51, s51, 0
	s_add_u32 s26, s26, 0x100
	s_addc_u32 s27, s27, 0
	s_cmp_gt_u32 s52, 13
	s_cbranch_scc0 .LBB0_616
	s_and_b64 vcc, exec, s[14:15]
	s_cbranch_vccz .LBB0_619
	s_barrier

; #define PG8_STAGE(bufoff, gbase, voff) do { _Pragma("unroll") for (int _i = 0; _i < 2; ++_i) \
;         __builtin_amdgcn_global_load_lds((const unsigned*)((const char*)(gbase) + (voff)[_i]), (LAS unsigned*)(lds + (bufoff) + ldsw + _i * 8192), 16, 0, 0); } while (0)
; #define PG8_LDA(dst, b, h) do { _Pragma("unroll") for (int m = 0; m < 4; ++m) _Pragma("unroll") for (int k = 0; k < 2; ++k) dst[m][k] = *(const LAS bf16x8*)(lds + PG8_SA(b, h) + aoff + m * 2048 + k * 1024); } while (0)
; #define PG8_LDB(dst, b, h) do { _Pragma("unroll") for (int n = 0; n < 2; ++n) _Pragma("unroll") for (int k = 0; k < 2; ++k) dst[n][k] = *(const LAS bf16x8*)(lds + PG8_SB(b, h) + boff + n * 2048 + k * 1024); } while (0)
; #define PG8_MMA(ai, bj, At, Bt) do { __builtin_amdgcn_s_setprio(1); _Pragma("unroll") for (int m = 0; m < 4; ++m) _Pragma("unroll") for (int n = 0; n < 2; ++n) _Pragma("unroll") for (int k = 0; k < 2; ++k) \
;         acc[ai][bj][m][n] = __builtin_amdgcn_mfma_f32_16x16x32_bf16(Bt[n][k], At[m][k], acc[ai][bj][m][n], 0, 0, 0); __builtin_amdgcn_s_setprio(0); } while (0)
; #define PG8_WAIT_V(n) asm volatile("s_waitcnt vmcnt(" #n ")" ::: "memory")
; #define PG8_WAIT_L(n) asm volatile("s_waitcnt lgkmcnt(" #n ")" ::: "memory")
; #define PG8_BAR __builtin_amdgcn_s_barrier()
; #define PG8_SCHED __builtin_amdgcn_sched_barrier(0)
; template <class Epi, bool ALIGN_EPI = true, bool SP2 = true>
; __device__ __forceinline__ void gemm_phase(LAS unsigned char* lds, const Gemm g, const StaticOrder& S, const Epi& E, const int wave_s) {
;     ...
;             PG8_LDB(B0, 0, 0); PG8_LDB(B1, 0, 1); PG8_SCHED; PG8_LDA(At, 0, 0); PG8_STAGE(PG8_SA(1, 1), a1 + hstep, voffA);
;             PG8_WAIT_V(8); PG8_WAIT_L(0); PG8_BAR; PG8_MMA(0, 0, At, B0); PG8_MMA(0, 1, At, B1); PG8_BAR; PG8_SCHED;
;             PG8_LDA(At, 0, 1); PG8_STAGE(PG8_SB(0, 0), b2, voffB); PG8_STAGE(PG8_SB(0, 1), b2 + hstep, voffB); PG8_STAGE(PG8_SA(0, 0), a2, voffA);
;             PG8_WAIT_V(8); PG8_WAIT_L(0); PG8_BAR; PG8_MMA(1, 0, At, B0); PG8_MMA(1, 1, At, B1); PG8_BAR; PG8_SCHED;
.LBB0_690:
	ds_read_b128 v[140:143], v185
	ds_read_b128 v[144:147], v185 offset:1024
	ds_read_b128 v[148:151], v185 offset:2048
	ds_read_b128 v[152:155], v185 offset:3072
	ds_read_b128 v[156:159], v186
	ds_read_b128 v[160:163], v186 offset:1024
	ds_read_b128 v[164:167], v186 offset:2048
	ds_read_b128 v[168:171], v186 offset:3072
	s_add_u32 s44, s42, 0x100
	s_addc_u32 s45, s43, 0
	s_cmp_eq_u32 s66, 40
	s_cselect_b32 s49, s7, s45
	s_cselect_b32 s48, s6, s44
	s_cselect_b32 s47, s37, s65
	s_cselect_b32 s46, s36, s64
	v_lshl_add_u64 v[180:181], s[42:43], 0, v[138:139]
	s_add_i32 m0, s39, 0xc000
	ds_read_b128 v[172:175], v187
	ds_read_b128 v[176:179], v187 offset:1024
	ds_read_b128 v[188:191], v187 offset:2048
	ds_read_b128 v[192:195], v187 offset:3072
	ds_read_b128 v[196:199], v187 offset:4096
	ds_read_b128 v[200:203], v187 offset:5120
	ds_read_b128 v[204:207], v187 offset:6144
	ds_read_b128 v[208:211], v187 offset:7168
	global_load_lds_dwordx4 v[180:181], off
	v_lshl_add_u64 v[180:181], s[42:43], 0, v[136:137]
	s_add_i32 m0, s39, 0xe000
	s_nop 0
	global_load_lds_dwordx4 v[180:181], off
	s_waitcnt vmcnt(8)
	s_waitcnt lgkmcnt(0)
	s_barrier
	s_setprio 1
	v_mfma_f32_16x16x32_bf16 v[124:127], v[140:143], v[172:175], v[124:127]
	v_mfma_f32_16x16x32_bf16 v[120:123], v[148:151], v[172:175], v[120:123]
	v_mfma_f32_16x16x32_bf16 v[116:119], v[140:143], v[188:191], v[116:119]
	v_mfma_f32_16x16x32_bf16 v[112:115], v[148:151], v[188:191], v[112:115]
	v_mfma_f32_16x16x32_bf16 v[108:111], v[140:143], v[196:199], v[108:111]
	v_mfma_f32_16x16x32_bf16 v[104:107], v[148:151], v[196:199], v[104:107]
	v_mfma_f32_16x16x32_bf16 v[100:103], v[140:143], v[204:207], v[100:103]
	v_mfma_f32_16x16x32_bf16 v[96:99], v[148:151], v[204:207], v[96:99]
	v_mfma_f32_16x16x32_bf16 v[124:127], v[144:147], v[176:179], v[124:127]
	v_mfma_f32_16x16x32_bf16 v[120:123], v[152:155], v[176:179], v[120:123]
	v_mfma_f32_16x16x32_bf16 v[116:119], v[144:147], v[192:195], v[116:119]
	v_mfma_f32_16x16x32_bf16 v[112:115], v[152:155], v[192:195], v[112:115]
	v_mfma_f32_16x16x32_bf16 v[108:111], v[144:147], v[200:203], v[108:111]
	v_mfma_f32_16x16x32_bf16 v[104:107], v[152:155], v[200:203], v[104:107]
	v_mfma_f32_16x16x32_bf16 v[100:103], v[144:147], v[208:211], v[100:103]
	v_mfma_f32_16x16x32_bf16 v[96:99], v[152:155], v[208:211], v[96:99]
	v_mfma_f32_16x16x32_bf16 v[60:63], v[156:159], v[172:175], v[60:63]
	v_mfma_f32_16x16x32_bf16 v[56:59], v[164:167], v[172:175], v[56:59]
	v_mfma_f32_16x16x32_bf16 v[52:55], v[156:159], v[188:191], v[52:55]
	v_mfma_f32_16x16x32_bf16 v[48:51], v[164:167], v[188:191], v[48:51]
	v_mfma_f32_16x16x32_bf16 v[44:47], v[156:159], v[196:199], v[44:47]
	v_mfma_f32_16x16x32_bf16 v[40:43], v[164:167], v[196:199], v[40:43]
	v_mfma_f32_16x16x32_bf16 v[36:39], v[156:159], v[204:207], v[36:39]
	v_mfma_f32_16x16x32_bf16 v[32:35], v[164:167], v[204:207], v[32:35]
	v_mfma_f32_16x16x32_bf16 v[60:63], v[160:163], v[176:179], v[60:63]
	v_mfma_f32_16x16x32_bf16 v[56:59], v[168:171], v[176:179], v[56:59]
	v_mfma_f32_16x16x32_bf16 v[52:55], v[160:163], v[192:195], v[52:55]
	v_mfma_f32_16x16x32_bf16 v[48:51], v[168:171], v[192:195], v[48:51]
	v_mfma_f32_16x16x32_bf16 v[44:47], v[160:163], v[200:203], v[44:47]
	v_mfma_f32_16x16x32_bf16 v[40:43], v[168:171], v[200:203], v[40:43]
	v_mfma_f32_16x16x32_bf16 v[36:39], v[160:163], v[208:211], v[36:39]
	v_mfma_f32_16x16x32_bf16 v[32:35], v[168:171], v[208:211], v[32:35]
	s_setprio 0
	s_barrier
	s_add_i32 s42, s57, s61
	v_lshl_add_u64 v[180:181], s[46:47], 0, v[130:131]
	s_mov_b32 m0, s42
	ds_read_b128 v[172:175], v187 offset:16384
	ds_read_b128 v[176:179], v187 offset:17408
	ds_read_b128 v[188:191], v187 offset:18432
	ds_read_b128 v[192:195], v187 offset:19456
	ds_read_b128 v[196:199], v187 offset:20480
	ds_read_b128 v[200:203], v187 offset:21504
	ds_read_b128 v[204:207], v187 offset:22528
	ds_read_b128 v[208:211], v187 offset:23552
	global_load_lds_dwordx4 v[180:181], off
	s_add_i32 m0, s42, 0x2000
	s_add_u32 s42, s46, 0xb0000
	v_lshl_add_u64 v[212:213], s[46:47], 0, v[134:135]
	s_addc_u32 s43, s47, 0
	s_add_i32 s68, s58, s61
	global_load_lds_dwordx4 v[212:213], off
	v_lshl_add_u64 v[214:215], s[42:43], 0, v[130:131]
	s_mov_b32 m0, s68
	v_lshl_add_u64 v[216:217], s[48:49], 0, v[132:133]
	global_load_lds_dwordx4 v[214:215], off
	v_lshl_add_u64 v[214:215], s[42:43], 0, v[134:135]
	s_add_i32 m0, s68, 0x2000
	s_nop 0
	global_load_lds_dwordx4 v[214:215], off
	v_lshl_add_u64 v[214:215], s[48:49], 0, v[128:129]
	s_mov_b32 m0, s39
	s_nop 0
	global_load_lds_dwordx4 v[214:215], off
	s_mov_b32 m0, s40
	s_nop 0
	global_load_lds_dwordx4 v[216:217], off
	s_waitcnt vmcnt(8)
	s_waitcnt lgkmcnt(0)
	s_barrier
; #define PG8_STAGE(bufoff, gbase, voff) do { _Pragma("unroll") for (int _i = 0; _i < 2; ++_i) \
;         __builtin_amdgcn_global_load_lds((const unsigned*)((const char*)(gbase) + (voff)[_i]), (LAS unsigned*)(lds + (bufoff) + ldsw + _i * 8192), 16, 0, 0); } while (0)
; #define PG8_LDA(dst, b, h) do { _Pragma("unroll") for (int m = 0; m < 4; ++m) _Pragma("unroll") for (int k = 0; k < 2; ++k) dst[m][k] = *(const LAS bf16x8*)(lds + PG8_SA(b, h) + aoff + m * 2048 + k * 1024); } while (0)
; #define PG8_LDB(dst, b, h) do { _Pragma("unroll") for (int n = 0; n < 2; ++n) _Pragma("unroll") for (int k = 0; k < 2; ++k) dst[n][k] = *(const LAS bf16x8*)(lds + PG8_SB(b, h) + boff + n * 2048 + k * 1024); } while (0)
; #define PG8_MMA(ai, bj, At, Bt) do { __builtin_amdgcn_s_setprio(1); _Pragma("unroll") for (int m = 0; m < 4; ++m) _Pragma("unroll") for (int n = 0; n < 2; ++n) _Pragma("unroll") for (int k = 0; k < 2; ++k) \
;         acc[ai][bj][m][n] = __builtin_amdgcn_mfma_f32_16x16x32_bf16(Bt[n][k], At[m][k], acc[ai][bj][m][n], 0, 0, 0); __builtin_amdgcn_s_setprio(0); } while (0)
; #define PG8_WAIT_V(n) asm volatile("s_waitcnt vmcnt(" #n ")" ::: "memory")
; #define PG8_WAIT_L(n) asm volatile("s_waitcnt lgkmcnt(" #n ")" ::: "memory")
; #define PG8_BAR __builtin_amdgcn_s_barrier()
; #define PG8_SCHED __builtin_amdgcn_sched_barrier(0)
; template <class Epi, bool ALIGN_EPI = true, bool SP2 = true>
; __device__ __forceinline__ void gemm_phase(LAS unsigned char* lds, const Gemm g, const StaticOrder& S, const Epi& E, const int wave_s) {
;     ...
;             PG8_WAIT_V(8); PG8_WAIT_L(0); PG8_BAR; PG8_MMA(1, 0, At, B0); PG8_MMA(1, 1, At, B1); PG8_BAR; PG8_SCHED;
;             PG8_LDB(B0, 1, 0); PG8_LDB(B1, 1, 1); PG8_SCHED; PG8_LDA(At, 1, 0); PG8_STAGE(PG8_SA(0, 1), a2 + hstep, voffA);
;             PG8_WAIT_V(8); PG8_WAIT_L(0); PG8_BAR; PG8_MMA(0, 0, At, B0); PG8_MMA(0, 1, At, B1); PG8_BAR; PG8_SCHED;
	s_setprio 1
	v_mfma_f32_16x16x32_bf16 v[92:95], v[140:143], v[172:175], v[92:95]
	v_mfma_f32_16x16x32_bf16 v[88:91], v[148:151], v[172:175], v[88:91]
	v_mfma_f32_16x16x32_bf16 v[84:87], v[140:143], v[188:191], v[84:87]
	v_mfma_f32_16x16x32_bf16 v[80:83], v[148:151], v[188:191], v[80:83]
	v_mfma_f32_16x16x32_bf16 v[76:79], v[140:143], v[196:199], v[76:79]
	v_mfma_f32_16x16x32_bf16 v[72:75], v[148:151], v[196:199], v[72:75]
	v_mfma_f32_16x16x32_bf16 v[68:71], v[140:143], v[204:207], v[68:71]
	v_mfma_f32_16x16x32_bf16 v[64:67], v[148:151], v[204:207], v[64:67]
	v_mfma_f32_16x16x32_bf16 v[92:95], v[144:147], v[176:179], v[92:95]
	v_mfma_f32_16x16x32_bf16 v[88:91], v[152:155], v[176:179], v[88:91]
	v_mfma_f32_16x16x32_bf16 v[84:87], v[144:147], v[192:195], v[84:87]
	v_mfma_f32_16x16x32_bf16 v[80:83], v[152:155], v[192:195], v[80:83]
	v_mfma_f32_16x16x32_bf16 v[76:79], v[144:147], v[200:203], v[76:79]
	v_mfma_f32_16x16x32_bf16 v[72:75], v[152:155], v[200:203], v[72:75]
	v_mfma_f32_16x16x32_bf16 v[68:71], v[144:147], v[208:211], v[68:71]
	v_mfma_f32_16x16x32_bf16 v[64:67], v[152:155], v[208:211], v[64:67]
	v_mfma_f32_16x16x32_bf16 v[28:31], v[156:159], v[172:175], v[28:31]
	v_mfma_f32_16x16x32_bf16 v[24:27], v[164:167], v[172:175], v[24:27]
	v_mfma_f32_16x16x32_bf16 v[20:23], v[156:159], v[188:191], v[20:23]
	v_mfma_f32_16x16x32_bf16 v[16:19], v[164:167], v[188:191], v[16:19]
	v_mfma_f32_16x16x32_bf16 v[12:15], v[156:159], v[196:199], v[12:15]
	v_mfma_f32_16x16x32_bf16 v[8:11], v[164:167], v[196:199], v[8:11]
	v_mfma_f32_16x16x32_bf16 v[4:7], v[156:159], v[204:207], v[4:7]
	v_mfma_f32_16x16x32_bf16 v[0:3], v[164:167], v[204:207], v[0:3]
	v_mfma_f32_16x16x32_bf16 v[28:31], v[160:163], v[176:179], v[28:31]
	v_mfma_f32_16x16x32_bf16 v[24:27], v[168:171], v[176:179], v[24:27]
	v_mfma_f32_16x16x32_bf16 v[20:23], v[160:163], v[192:195], v[20:23]
	v_mfma_f32_16x16x32_bf16 v[16:19], v[168:171], v[192:195], v[16:19]
	v_mfma_f32_16x16x32_bf16 v[12:15], v[160:163], v[200:203], v[12:15]
	v_mfma_f32_16x16x32_bf16 v[8:11], v[168:171], v[200:203], v[8:11]
	v_mfma_f32_16x16x32_bf16 v[4:7], v[160:163], v[208:211], v[4:7]
	v_mfma_f32_16x16x32_bf16 v[0:3], v[168:171], v[208:211], v[0:3]
	s_setprio 0
	s_barrier
	s_add_i32 s68, 0, 0x18000
	s_add_i32 s69, 0, 0x1c000
	v_add_u32_e32 v152, s68, v183
	v_add_u32_e32 v168, s69, v183
	ds_read_b128 v[140:143], v152
	ds_read_b128 v[144:147], v152 offset:1024
	ds_read_b128 v[148:151], v152 offset:2048
	ds_read_b128 v[152:155], v152 offset:3072
	ds_read_b128 v[156:159], v168
	ds_read_b128 v[160:163], v168 offset:1024
	ds_read_b128 v[164:167], v168 offset:2048
	ds_read_b128 v[168:171], v168 offset:3072
	s_add_u32 s42, s48, 0xb0000
	s_addc_u32 s43, s49, 0
	s_mov_b32 m0, s41
	v_lshl_add_u64 v[218:219], s[42:43], 0, v[128:129]
	ds_read_b128 v[172:175], v187 offset:32768
	ds_read_b128 v[176:179], v187 offset:33792
	ds_read_b128 v[188:191], v187 offset:34816
	ds_read_b128 v[192:195], v187 offset:35840
	ds_read_b128 v[196:199], v187 offset:36864
	ds_read_b128 v[200:203], v187 offset:37888
	ds_read_b128 v[204:207], v187 offset:38912
	ds_read_b128 v[208:211], v187 offset:39936
	global_load_lds_dwordx4 v[218:219], off
	v_lshl_add_u64 v[218:219], s[42:43], 0, v[132:133]
	s_mov_b32 m0, s50
	s_nop 0
	global_load_lds_dwordx4 v[218:219], off
	s_waitcnt vmcnt(8)
	s_waitcnt lgkmcnt(0)
	s_barrier
	s_setprio 1
	v_mfma_f32_16x16x32_bf16 v[124:127], v[140:143], v[172:175], v[124:127]
	v_mfma_f32_16x16x32_bf16 v[120:123], v[148:151], v[172:175], v[120:123]
	v_mfma_f32_16x16x32_bf16 v[116:119], v[140:143], v[188:191], v[116:119]
	v_mfma_f32_16x16x32_bf16 v[112:115], v[148:151], v[188:191], v[112:115]
	v_mfma_f32_16x16x32_bf16 v[108:111], v[140:143], v[196:199], v[108:111]
	v_mfma_f32_16x16x32_bf16 v[104:107], v[148:151], v[196:199], v[104:107]
	v_mfma_f32_16x16x32_bf16 v[100:103], v[140:143], v[204:207], v[100:103]
	v_mfma_f32_16x16x32_bf16 v[96:99], v[148:151], v[204:207], v[96:99]
	v_mfma_f32_16x16x32_bf16 v[124:127], v[144:147], v[176:179], v[124:127]
	v_mfma_f32_16x16x32_bf16 v[120:123], v[152:155], v[176:179], v[120:123]
	v_mfma_f32_16x16x32_bf16 v[116:119], v[144:147], v[192:195], v[116:119]
	v_mfma_f32_16x16x32_bf16 v[112:115], v[152:155], v[192:195], v[112:115]
	v_mfma_f32_16x16x32_bf16 v[108:111], v[144:147], v[200:203], v[108:111]
	v_mfma_f32_16x16x32_bf16 v[104:107], v[152:155], v[200:203], v[104:107]
	v_mfma_f32_16x16x32_bf16 v[100:103], v[144:147], v[208:211], v[100:103]
	v_mfma_f32_16x16x32_bf16 v[96:99], v[152:155], v[208:211], v[96:99]
	v_mfma_f32_16x16x32_bf16 v[60:63], v[156:159], v[172:175], v[60:63]
	v_mfma_f32_16x16x32_bf16 v[56:59], v[164:167], v[172:175], v[56:59]
	v_mfma_f32_16x16x32_bf16 v[52:55], v[156:159], v[188:191], v[52:55]
	v_mfma_f32_16x16x32_bf16 v[48:51], v[164:167], v[188:191], v[48:51]
	v_mfma_f32_16x16x32_bf16 v[44:47], v[156:159], v[196:199], v[44:47]
	v_mfma_f32_16x16x32_bf16 v[40:43], v[164:167], v[196:199], v[40:43]
	v_mfma_f32_16x16x32_bf16 v[36:39], v[156:159], v[204:207], v[36:39]
	v_mfma_f32_16x16x32_bf16 v[32:35], v[164:167], v[204:207], v[32:35]
	v_mfma_f32_16x16x32_bf16 v[60:63], v[160:163], v[176:179], v[60:63]
	v_mfma_f32_16x16x32_bf16 v[56:59], v[168:171], v[176:179], v[56:59]
	v_mfma_f32_16x16x32_bf16 v[52:55], v[160:163], v[192:195], v[52:55]
	v_mfma_f32_16x16x32_bf16 v[48:51], v[168:171], v[192:195], v[48:51]
	v_mfma_f32_16x16x32_bf16 v[44:47], v[160:163], v[200:203], v[44:47]
	v_mfma_f32_16x16x32_bf16 v[40:43], v[168:171], v[200:203], v[40:43]
	v_mfma_f32_16x16x32_bf16 v[36:39], v[160:163], v[208:211], v[36:39]
	v_mfma_f32_16x16x32_bf16 v[32:35], v[168:171], v[208:211], v[32:35]
	s_setprio 0
	s_barrier
; #define PG8_STAGE(bufoff, gbase, voff) do { _Pragma("unroll") for (int _i = 0; _i < 2; ++_i) \
;         __builtin_amdgcn_global_load_lds((const unsigned*)((const char*)(gbase) + (voff)[_i]), (LAS unsigned*)(lds + (bufoff) + ldsw + _i * 8192), 16, 0, 0); } while (0)
; #define PG8_LDA(dst, b, h) do { _Pragma("unroll") for (int m = 0; m < 4; ++m) _Pragma("unroll") for (int k = 0; k < 2; ++k) dst[m][k] = *(const LAS bf16x8*)(lds + PG8_SA(b, h) + aoff + m * 2048 + k * 1024); } while (0)
; #define PG8_MMA(ai, bj, At, Bt) do { __builtin_amdgcn_s_setprio(1); _Pragma("unroll") for (int m = 0; m < 4; ++m) _Pragma("unroll") for (int n = 0; n < 2; ++n) _Pragma("unroll") for (int k = 0; k < 2; ++k) \
;         acc[ai][bj][m][n] = __builtin_amdgcn_mfma_f32_16x16x32_bf16(Bt[n][k], At[m][k], acc[ai][bj][m][n], 0, 0, 0); __builtin_amdgcn_s_setprio(0); } while (0)
; #define PG8_WAIT_V(n) asm volatile("s_waitcnt vmcnt(" #n ")" ::: "memory")
; #define PG8_WAIT_L(n) asm volatile("s_waitcnt lgkmcnt(" #n ")" ::: "memory")
; #define PG8_BAR __builtin_amdgcn_s_barrier()
; #define PG8_SCHED __builtin_amdgcn_sched_barrier(0)
; template <class Epi, bool ALIGN_EPI = true, bool SP2 = true>
; __device__ __forceinline__ void gemm_phase(LAS unsigned char* lds, const Gemm g, const StaticOrder& S, const Epi& E, const int wave_s) {
;     ...
;             PG8_LDA(At, 1, 1); PG8_STAGE(PG8_SB(1, 0), b3, voffB); PG8_STAGE(PG8_SB(1, 1), b3 + hstep, voffB); PG8_STAGE(PG8_SA(1, 0), a3, voffA);
;             PG8_WAIT_V(8); PG8_WAIT_L(0); PG8_BAR; PG8_MMA(1, 0, At, B0); PG8_MMA(1, 1, At, B1); PG8_BAR; PG8_SCHED;
;     ...
;         if constexpr (ALIGN_EPI) { if (wr == 0) PG8_BAR; }
	s_add_i32 s42, s68, s61
	v_lshl_add_u64 v[180:181], v[180:181], 0, s[22:23]
	s_mov_b32 m0, s42
	ds_read_b128 v[172:175], v187 offset:49152
	ds_read_b128 v[176:179], v187 offset:50176
	ds_read_b128 v[188:191], v187 offset:51200
	ds_read_b128 v[192:195], v187 offset:52224
	ds_read_b128 v[196:199], v187 offset:53248
	ds_read_b128 v[200:203], v187 offset:54272
	ds_read_b128 v[204:207], v187 offset:55296
	ds_read_b128 v[208:211], v187 offset:56320
	global_load_lds_dwordx4 v[180:181], off
	s_add_i32 m0, s42, 0x2000
	s_add_u32 s42, s46, 0xb0080
	v_lshl_add_u64 v[180:181], v[212:213], 0, s[22:23]
	s_addc_u32 s43, s47, 0
	s_add_i32 s46, s69, s61
	global_load_lds_dwordx4 v[180:181], off
	v_lshl_add_u64 v[180:181], s[42:43], 0, v[130:131]
	s_mov_b32 m0, s46
	s_nop 0
	global_load_lds_dwordx4 v[180:181], off
	v_lshl_add_u64 v[180:181], s[42:43], 0, v[134:135]
	s_add_i32 m0, s46, 0x2000
	s_nop 0
	global_load_lds_dwordx4 v[180:181], off
	v_lshl_add_u64 v[180:181], v[214:215], 0, s[22:23]
	s_mov_b32 m0, s54
	s_nop 0
	global_load_lds_dwordx4 v[180:181], off
	v_lshl_add_u64 v[180:181], v[216:217], 0, s[22:23]
	s_mov_b32 m0, s55
	s_nop 0
	global_load_lds_dwordx4 v[180:181], off
	s_waitcnt vmcnt(8)
	s_waitcnt lgkmcnt(0)
	s_barrier
	s_setprio 1
	v_mfma_f32_16x16x32_bf16 v[92:95], v[140:143], v[172:175], v[92:95]
	v_mfma_f32_16x16x32_bf16 v[88:91], v[148:151], v[172:175], v[88:91]
	v_mfma_f32_16x16x32_bf16 v[84:87], v[140:143], v[188:191], v[84:87]
	v_mfma_f32_16x16x32_bf16 v[80:83], v[148:151], v[188:191], v[80:83]
	v_mfma_f32_16x16x32_bf16 v[76:79], v[140:143], v[196:199], v[76:79]
	v_mfma_f32_16x16x32_bf16 v[72:75], v[148:151], v[196:199], v[72:75]
	v_mfma_f32_16x16x32_bf16 v[68:71], v[140:143], v[204:207], v[68:71]
	v_mfma_f32_16x16x32_bf16 v[64:67], v[148:151], v[204:207], v[64:67]
	v_mfma_f32_16x16x32_bf16 v[92:95], v[144:147], v[176:179], v[92:95]
	v_mfma_f32_16x16x32_bf16 v[88:91], v[152:155], v[176:179], v[88:91]
	v_mfma_f32_16x16x32_bf16 v[84:87], v[144:147], v[192:195], v[84:87]
	v_mfma_f32_16x16x32_bf16 v[80:83], v[152:155], v[192:195], v[80:83]
	v_mfma_f32_16x16x32_bf16 v[76:79], v[144:147], v[200:203], v[76:79]
	v_mfma_f32_16x16x32_bf16 v[72:75], v[152:155], v[200:203], v[72:75]
	v_mfma_f32_16x16x32_bf16 v[68:71], v[144:147], v[208:211], v[68:71]
	v_mfma_f32_16x16x32_bf16 v[64:67], v[152:155], v[208:211], v[64:67]
	v_mfma_f32_16x16x32_bf16 v[28:31], v[156:159], v[172:175], v[28:31]
	v_mfma_f32_16x16x32_bf16 v[24:27], v[164:167], v[172:175], v[24:27]
	v_mfma_f32_16x16x32_bf16 v[20:23], v[156:159], v[188:191], v[20:23]
	v_mfma_f32_16x16x32_bf16 v[16:19], v[164:167], v[188:191], v[16:19]
	v_mfma_f32_16x16x32_bf16 v[12:15], v[156:159], v[196:199], v[12:15]
	v_mfma_f32_16x16x32_bf16 v[8:11], v[164:167], v[196:199], v[8:11]
	v_mfma_f32_16x16x32_bf16 v[4:7], v[156:159], v[204:207], v[4:7]
	v_mfma_f32_16x16x32_bf16 v[0:3], v[164:167], v[204:207], v[0:3]
	v_mfma_f32_16x16x32_bf16 v[28:31], v[160:163], v[176:179], v[28:31]
	v_mfma_f32_16x16x32_bf16 v[24:27], v[168:171], v[176:179], v[24:27]
	v_mfma_f32_16x16x32_bf16 v[20:23], v[160:163], v[192:195], v[20:23]
	v_mfma_f32_16x16x32_bf16 v[16:19], v[168:171], v[192:195], v[16:19]
	v_mfma_f32_16x16x32_bf16 v[12:15], v[160:163], v[200:203], v[12:15]
	v_mfma_f32_16x16x32_bf16 v[8:11], v[168:171], v[200:203], v[8:11]
	v_mfma_f32_16x16x32_bf16 v[4:7], v[160:163], v[208:211], v[4:7]
	v_mfma_f32_16x16x32_bf16 v[0:3], v[168:171], v[208:211], v[0:3]
	s_setprio 0
	s_barrier
	s_add_i32 s66, s66, 2
	s_add_u32 s64, s64, 0x100
	s_addc_u32 s65, s65, 0
	s_cmp_gt_u32 s66, 41
	s_mov_b64 s[42:43], s[44:45]
	s_cbranch_scc0 .LBB0_690
	s_and_b64 vcc, exec, s[24:25]
	s_cbranch_vccz .LBB0_693
	s_barrier

; #define PG8_STAGE(bufoff, gbase, voff) do { _Pragma("unroll") for (int _i = 0; _i < 2; ++_i) \
;         __builtin_amdgcn_global_load_lds((const unsigned*)((const char*)(gbase) + (voff)[_i]), (LAS unsigned*)(lds + (bufoff) + ldsw + _i * 8192), 16, 0, 0); } while (0)
; #define PG8_LDA(dst, b, h) do { _Pragma("unroll") for (int m = 0; m < 4; ++m) _Pragma("unroll") for (int k = 0; k < 2; ++k) dst[m][k] = *(const LAS bf16x8*)(lds + PG8_SA(b, h) + aoff + m * 2048 + k * 1024); } while (0)
; #define PG8_LDB(dst, b, h) do { _Pragma("unroll") for (int n = 0; n < 2; ++n) _Pragma("unroll") for (int k = 0; k < 2; ++k) dst[n][k] = *(const LAS bf16x8*)(lds + PG8_SB(b, h) + boff + n * 2048 + k * 1024); } while (0)
; #define PG8_MMA(ai, bj, At, Bt) do { __builtin_amdgcn_s_setprio(1); _Pragma("unroll") for (int m = 0; m < 4; ++m) _Pragma("unroll") for (int n = 0; n < 2; ++n) _Pragma("unroll") for (int k = 0; k < 2; ++k) \
;         acc[ai][bj][m][n] = __builtin_amdgcn_mfma_f32_16x16x32_bf16(Bt[n][k], At[m][k], acc[ai][bj][m][n], 0, 0, 0); __builtin_amdgcn_s_setprio(0); } while (0)
; #define PG8_WAIT_V(n) asm volatile("s_waitcnt vmcnt(" #n ")" ::: "memory")
; #define PG8_WAIT_L(n) asm volatile("s_waitcnt lgkmcnt(" #n ")" ::: "memory")
; #define PG8_BAR __builtin_amdgcn_s_barrier()
; #define PG8_SCHED __builtin_amdgcn_sched_barrier(0)
; template <class Epi, bool ALIGN_EPI = true, bool SP2 = true>
; __device__ __forceinline__ void gemm_phase(LAS unsigned char* lds, const Gemm g, const StaticOrder& S, const Epi& E, const int wave_s) {
;     ...
;             PG8_LDB(B0, 0, 0); PG8_LDB(B1, 0, 1); PG8_SCHED; PG8_LDA(At, 0, 0); PG8_STAGE(PG8_SA(1, 1), a1 + hstep, voffA);
;             PG8_WAIT_V(8); PG8_WAIT_L(0); PG8_BAR; PG8_MMA(0, 0, At, B0); PG8_MMA(0, 1, At, B1); PG8_BAR; PG8_SCHED;
;             PG8_LDA(At, 0, 1); PG8_STAGE(PG8_SB(0, 0), b2, voffB); PG8_STAGE(PG8_SB(0, 1), b2 + hstep, voffB); PG8_STAGE(PG8_SA(0, 0), a2, voffA);
;             PG8_WAIT_V(8); PG8_WAIT_L(0); PG8_BAR; PG8_MMA(1, 0, At, B0); PG8_MMA(1, 1, At, B1); PG8_BAR; PG8_SCHED;
.LBB0_829:
	ds_read_b128 v[144:147], v151
	ds_read_b128 v[154:157], v151 offset:1024
	ds_read_b128 v[158:161], v151 offset:2048
	ds_read_b128 v[162:165], v151 offset:3072
	ds_read_b128 v[166:169], v152
	ds_read_b128 v[170:173], v152 offset:1024
	ds_read_b128 v[174:177], v152 offset:2048
	ds_read_b128 v[178:181], v152 offset:3072
	s_add_u32 s28, s26, 0xfffc0080
	s_addc_u32 s29, s27, -1
	s_cmp_eq_u32 s52, 12
	s_cselect_b32 s31, s19, s29
	s_cselect_b32 s30, s48, s28
	s_cselect_b32 s29, s17, s51
	s_cselect_b32 s28, s49, s50
	v_lshl_add_u64 v[214:215], s[26:27], 0, v[138:139]
	s_add_i32 m0, s25, 0xc000
	ds_read_b128 v[182:185], v153
	ds_read_b128 v[186:189], v153 offset:1024
	ds_read_b128 v[190:193], v153 offset:2048
	ds_read_b128 v[194:197], v153 offset:3072
	ds_read_b128 v[198:201], v153 offset:4096
	ds_read_b128 v[202:205], v153 offset:5120
	ds_read_b128 v[206:209], v153 offset:6144
	ds_read_b128 v[210:213], v153 offset:7168
	global_load_lds_dwordx4 v[214:215], off
	v_lshl_add_u64 v[214:215], s[26:27], 0, v[136:137]
	s_add_i32 m0, s25, 0xe000
	s_nop 0
	global_load_lds_dwordx4 v[214:215], off
	s_waitcnt vmcnt(8)
	s_waitcnt lgkmcnt(0)
	s_barrier
	s_setprio 1
	v_mfma_f32_16x16x32_bf16 v[124:127], v[144:147], v[182:185], v[124:127]
	v_mfma_f32_16x16x32_bf16 v[120:123], v[158:161], v[182:185], v[120:123]
	v_mfma_f32_16x16x32_bf16 v[116:119], v[144:147], v[190:193], v[116:119]
	v_mfma_f32_16x16x32_bf16 v[108:111], v[158:161], v[190:193], v[108:111]
	v_mfma_f32_16x16x32_bf16 v[100:103], v[144:147], v[198:201], v[100:103]
	v_mfma_f32_16x16x32_bf16 v[92:95], v[158:161], v[198:201], v[92:95]
	v_mfma_f32_16x16x32_bf16 v[84:87], v[144:147], v[206:209], v[84:87]
	v_mfma_f32_16x16x32_bf16 v[76:79], v[158:161], v[206:209], v[76:79]
	v_mfma_f32_16x16x32_bf16 v[124:127], v[154:157], v[186:189], v[124:127]
	v_mfma_f32_16x16x32_bf16 v[120:123], v[162:165], v[186:189], v[120:123]
	v_mfma_f32_16x16x32_bf16 v[116:119], v[154:157], v[194:197], v[116:119]
	v_mfma_f32_16x16x32_bf16 v[108:111], v[162:165], v[194:197], v[108:111]
	v_mfma_f32_16x16x32_bf16 v[100:103], v[154:157], v[202:205], v[100:103]
	v_mfma_f32_16x16x32_bf16 v[92:95], v[162:165], v[202:205], v[92:95]
	v_mfma_f32_16x16x32_bf16 v[84:87], v[154:157], v[210:213], v[84:87]
	v_mfma_f32_16x16x32_bf16 v[76:79], v[162:165], v[210:213], v[76:79]
	v_mfma_f32_16x16x32_bf16 v[112:115], v[166:169], v[182:185], v[112:115]
	v_mfma_f32_16x16x32_bf16 v[104:107], v[174:177], v[182:185], v[104:107]
	v_mfma_f32_16x16x32_bf16 v[96:99], v[166:169], v[190:193], v[96:99]
	v_mfma_f32_16x16x32_bf16 v[88:91], v[174:177], v[190:193], v[88:91]
	v_mfma_f32_16x16x32_bf16 v[80:83], v[166:169], v[198:201], v[80:83]
	v_mfma_f32_16x16x32_bf16 v[72:75], v[174:177], v[198:201], v[72:75]
	v_mfma_f32_16x16x32_bf16 v[68:71], v[166:169], v[206:209], v[68:71]
	v_mfma_f32_16x16x32_bf16 v[64:67], v[174:177], v[206:209], v[64:67]
	v_mfma_f32_16x16x32_bf16 v[112:115], v[170:173], v[186:189], v[112:115]
	v_mfma_f32_16x16x32_bf16 v[104:107], v[178:181], v[186:189], v[104:107]
	v_mfma_f32_16x16x32_bf16 v[96:99], v[170:173], v[194:197], v[96:99]
	v_mfma_f32_16x16x32_bf16 v[88:91], v[178:181], v[194:197], v[88:91]
	v_mfma_f32_16x16x32_bf16 v[80:83], v[170:173], v[202:205], v[80:83]
	v_mfma_f32_16x16x32_bf16 v[72:75], v[178:181], v[202:205], v[72:75]
	v_mfma_f32_16x16x32_bf16 v[68:71], v[170:173], v[210:213], v[68:71]
	v_mfma_f32_16x16x32_bf16 v[64:67], v[178:181], v[210:213], v[64:67]
	s_setprio 0
	s_barrier
	s_add_i32 s53, s44, s61
	v_lshl_add_u64 v[214:215], s[28:29], 0, v[132:133]
	s_mov_b32 m0, s53
	ds_read_b128 v[182:185], v153 offset:16384
	ds_read_b128 v[186:189], v153 offset:17408
	ds_read_b128 v[190:193], v153 offset:18432
	ds_read_b128 v[194:197], v153 offset:19456
	ds_read_b128 v[198:201], v153 offset:20480
	ds_read_b128 v[202:205], v153 offset:21504
	ds_read_b128 v[206:209], v153 offset:22528
	ds_read_b128 v[210:213], v153 offset:23552
	global_load_lds_dwordx4 v[214:215], off
	s_add_i32 m0, s53, 0x2000
	s_add_u32 s54, s28, 0x40000
	v_lshl_add_u64 v[216:217], s[28:29], 0, v[128:129]
	s_addc_u32 s55, s29, 0
	s_add_i32 s53, s45, s61
	global_load_lds_dwordx4 v[216:217], off
	v_lshl_add_u64 v[218:219], s[54:55], 0, v[132:133]
	s_mov_b32 m0, s53
	v_lshl_add_u64 v[220:221], s[30:31], 0, v[130:131]
	global_load_lds_dwordx4 v[218:219], off
	v_lshl_add_u64 v[218:219], s[54:55], 0, v[128:129]
	s_add_i32 m0, s53, 0x2000
	s_nop 0
	global_load_lds_dwordx4 v[218:219], off
	v_lshl_add_u64 v[218:219], s[30:31], 0, v[134:135]
	s_mov_b32 m0, s25
	s_nop 0
	global_load_lds_dwordx4 v[218:219], off
	s_mov_b32 m0, s37
	s_nop 0
	global_load_lds_dwordx4 v[220:221], off
	s_waitcnt vmcnt(8)
	s_waitcnt lgkmcnt(0)
	s_barrier
; #define PG8_STAGE(bufoff, gbase, voff) do { _Pragma("unroll") for (int _i = 0; _i < 2; ++_i) \
;         __builtin_amdgcn_global_load_lds((const unsigned*)((const char*)(gbase) + (voff)[_i]), (LAS unsigned*)(lds + (bufoff) + ldsw + _i * 8192), 16, 0, 0); } while (0)
; #define PG8_LDA(dst, b, h) do { _Pragma("unroll") for (int m = 0; m < 4; ++m) _Pragma("unroll") for (int k = 0; k < 2; ++k) dst[m][k] = *(const LAS bf16x8*)(lds + PG8_SA(b, h) + aoff + m * 2048 + k * 1024); } while (0)
; #define PG8_LDB(dst, b, h) do { _Pragma("unroll") for (int n = 0; n < 2; ++n) _Pragma("unroll") for (int k = 0; k < 2; ++k) dst[n][k] = *(const LAS bf16x8*)(lds + PG8_SB(b, h) + boff + n * 2048 + k * 1024); } while (0)
; #define PG8_MMA(ai, bj, At, Bt) do { __builtin_amdgcn_s_setprio(1); _Pragma("unroll") for (int m = 0; m < 4; ++m) _Pragma("unroll") for (int n = 0; n < 2; ++n) _Pragma("unroll") for (int k = 0; k < 2; ++k) \
;         acc[ai][bj][m][n] = __builtin_amdgcn_mfma_f32_16x16x32_bf16(Bt[n][k], At[m][k], acc[ai][bj][m][n], 0, 0, 0); __builtin_amdgcn_s_setprio(0); } while (0)
; #define PG8_WAIT_V(n) asm volatile("s_waitcnt vmcnt(" #n ")" ::: "memory")
; #define PG8_WAIT_L(n) asm volatile("s_waitcnt lgkmcnt(" #n ")" ::: "memory")
; #define PG8_BAR __builtin_amdgcn_s_barrier()
; #define PG8_SCHED __builtin_amdgcn_sched_barrier(0)
; template <class Epi, bool ALIGN_EPI = true, bool SP2 = true>
; __device__ __forceinline__ void gemm_phase(LAS unsigned char* lds, const Gemm g, const StaticOrder& S, const Epi& E, const int wave_s) {
;     ...
;             PG8_WAIT_V(8); PG8_WAIT_L(0); PG8_BAR; PG8_MMA(1, 0, At, B0); PG8_MMA(1, 1, At, B1); PG8_BAR; PG8_SCHED;
;             PG8_LDB(B0, 1, 0); PG8_LDB(B1, 1, 1); PG8_SCHED; PG8_LDA(At, 1, 0); PG8_STAGE(PG8_SA(0, 1), a2 + hstep, voffA);
;             PG8_WAIT_V(8); PG8_WAIT_L(0); PG8_BAR; PG8_MMA(0, 0, At, B0); PG8_MMA(0, 1, At, B1); PG8_BAR; PG8_SCHED;
	s_setprio 1
	v_mfma_f32_16x16x32_bf16 v[60:63], v[144:147], v[182:185], v[60:63]
	v_mfma_f32_16x16x32_bf16 v[56:59], v[158:161], v[182:185], v[56:59]
	v_mfma_f32_16x16x32_bf16 v[52:55], v[144:147], v[190:193], v[52:55]
	v_mfma_f32_16x16x32_bf16 v[44:47], v[158:161], v[190:193], v[44:47]
	v_mfma_f32_16x16x32_bf16 v[36:39], v[144:147], v[198:201], v[36:39]
	v_mfma_f32_16x16x32_bf16 v[28:31], v[158:161], v[198:201], v[28:31]
	v_mfma_f32_16x16x32_bf16 v[20:23], v[144:147], v[206:209], v[20:23]
	v_mfma_f32_16x16x32_bf16 v[12:15], v[158:161], v[206:209], v[12:15]
	v_mfma_f32_16x16x32_bf16 v[60:63], v[154:157], v[186:189], v[60:63]
	v_mfma_f32_16x16x32_bf16 v[56:59], v[162:165], v[186:189], v[56:59]
	v_mfma_f32_16x16x32_bf16 v[52:55], v[154:157], v[194:197], v[52:55]
	v_mfma_f32_16x16x32_bf16 v[44:47], v[162:165], v[194:197], v[44:47]
	v_mfma_f32_16x16x32_bf16 v[36:39], v[154:157], v[202:205], v[36:39]
	v_mfma_f32_16x16x32_bf16 v[28:31], v[162:165], v[202:205], v[28:31]
	v_mfma_f32_16x16x32_bf16 v[20:23], v[154:157], v[210:213], v[20:23]
	v_mfma_f32_16x16x32_bf16 v[12:15], v[162:165], v[210:213], v[12:15]
	v_mfma_f32_16x16x32_bf16 v[48:51], v[166:169], v[182:185], v[48:51]
	v_mfma_f32_16x16x32_bf16 v[40:43], v[174:177], v[182:185], v[40:43]
	v_mfma_f32_16x16x32_bf16 v[32:35], v[166:169], v[190:193], v[32:35]
	v_mfma_f32_16x16x32_bf16 v[24:27], v[174:177], v[190:193], v[24:27]
	v_mfma_f32_16x16x32_bf16 v[16:19], v[166:169], v[198:201], v[16:19]
	v_mfma_f32_16x16x32_bf16 v[8:11], v[174:177], v[198:201], v[8:11]
	v_mfma_f32_16x16x32_bf16 v[4:7], v[166:169], v[206:209], v[4:7]
	v_mfma_f32_16x16x32_bf16 v[0:3], v[174:177], v[206:209], v[0:3]
	v_mfma_f32_16x16x32_bf16 v[48:51], v[170:173], v[186:189], v[48:51]
	v_mfma_f32_16x16x32_bf16 v[40:43], v[178:181], v[186:189], v[40:43]
	v_mfma_f32_16x16x32_bf16 v[32:35], v[170:173], v[194:197], v[32:35]
	v_mfma_f32_16x16x32_bf16 v[24:27], v[178:181], v[194:197], v[24:27]
	v_mfma_f32_16x16x32_bf16 v[16:19], v[170:173], v[202:205], v[16:19]
	v_mfma_f32_16x16x32_bf16 v[8:11], v[178:181], v[202:205], v[8:11]
	v_mfma_f32_16x16x32_bf16 v[4:7], v[170:173], v[210:213], v[4:7]
	v_mfma_f32_16x16x32_bf16 v[0:3], v[178:181], v[210:213], v[0:3]
	s_setprio 0
	s_barrier
	s_add_i32 s53, 0, 0x18000
	s_add_i32 s54, 0, 0x1c000
	v_add_u32_e32 v162, s53, v149
	v_add_u32_e32 v178, s54, v149
	ds_read_b128 v[144:147], v162
	ds_read_b128 v[154:157], v162 offset:1024
	ds_read_b128 v[158:161], v162 offset:2048
	ds_read_b128 v[162:165], v162 offset:3072
	ds_read_b128 v[166:169], v178
	ds_read_b128 v[170:173], v178 offset:1024
	ds_read_b128 v[174:177], v178 offset:2048
	ds_read_b128 v[178:181], v178 offset:3072
	s_add_u32 s30, s30, 0x40000
	s_addc_u32 s31, s31, 0
	s_mov_b32 m0, s38
	v_lshl_add_u64 v[222:223], s[30:31], 0, v[134:135]
	ds_read_b128 v[182:185], v153 offset:32768
	ds_read_b128 v[186:189], v153 offset:33792
	ds_read_b128 v[190:193], v153 offset:34816
	ds_read_b128 v[194:197], v153 offset:35840
	ds_read_b128 v[198:201], v153 offset:36864
	ds_read_b128 v[202:205], v153 offset:37888
	ds_read_b128 v[206:209], v153 offset:38912
	ds_read_b128 v[210:213], v153 offset:39936
	global_load_lds_dwordx4 v[222:223], off
	v_lshl_add_u64 v[222:223], s[30:31], 0, v[130:131]
	s_mov_b32 m0, s39
	s_nop 0
	global_load_lds_dwordx4 v[222:223], off
	s_waitcnt vmcnt(8)
	s_waitcnt lgkmcnt(0)
	s_barrier
	s_setprio 1
	v_mfma_f32_16x16x32_bf16 v[124:127], v[144:147], v[182:185], v[124:127]
	v_mfma_f32_16x16x32_bf16 v[120:123], v[158:161], v[182:185], v[120:123]
	v_mfma_f32_16x16x32_bf16 v[116:119], v[144:147], v[190:193], v[116:119]
	v_mfma_f32_16x16x32_bf16 v[108:111], v[158:161], v[190:193], v[108:111]
	v_mfma_f32_16x16x32_bf16 v[100:103], v[144:147], v[198:201], v[100:103]
	v_mfma_f32_16x16x32_bf16 v[92:95], v[158:161], v[198:201], v[92:95]
	v_mfma_f32_16x16x32_bf16 v[84:87], v[144:147], v[206:209], v[84:87]
	v_mfma_f32_16x16x32_bf16 v[76:79], v[158:161], v[206:209], v[76:79]
	v_mfma_f32_16x16x32_bf16 v[124:127], v[154:157], v[186:189], v[124:127]
	v_mfma_f32_16x16x32_bf16 v[120:123], v[162:165], v[186:189], v[120:123]
	v_mfma_f32_16x16x32_bf16 v[116:119], v[154:157], v[194:197], v[116:119]
	v_mfma_f32_16x16x32_bf16 v[108:111], v[162:165], v[194:197], v[108:111]
	v_mfma_f32_16x16x32_bf16 v[100:103], v[154:157], v[202:205], v[100:103]
	v_mfma_f32_16x16x32_bf16 v[92:95], v[162:165], v[202:205], v[92:95]
	v_mfma_f32_16x16x32_bf16 v[84:87], v[154:157], v[210:213], v[84:87]
	v_mfma_f32_16x16x32_bf16 v[76:79], v[162:165], v[210:213], v[76:79]
	v_mfma_f32_16x16x32_bf16 v[112:115], v[166:169], v[182:185], v[112:115]
	v_mfma_f32_16x16x32_bf16 v[104:107], v[174:177], v[182:185], v[104:107]
	v_mfma_f32_16x16x32_bf16 v[96:99], v[166:169], v[190:193], v[96:99]
	v_mfma_f32_16x16x32_bf16 v[88:91], v[174:177], v[190:193], v[88:91]
	v_mfma_f32_16x16x32_bf16 v[80:83], v[166:169], v[198:201], v[80:83]
	v_mfma_f32_16x16x32_bf16 v[72:75], v[174:177], v[198:201], v[72:75]
	v_mfma_f32_16x16x32_bf16 v[68:71], v[166:169], v[206:209], v[68:71]
	v_mfma_f32_16x16x32_bf16 v[64:67], v[174:177], v[206:209], v[64:67]
	v_mfma_f32_16x16x32_bf16 v[112:115], v[170:173], v[186:189], v[112:115]
	v_mfma_f32_16x16x32_bf16 v[104:107], v[178:181], v[186:189], v[104:107]
	v_mfma_f32_16x16x32_bf16 v[96:99], v[170:173], v[194:197], v[96:99]
	v_mfma_f32_16x16x32_bf16 v[88:91], v[178:181], v[194:197], v[88:91]
	v_mfma_f32_16x16x32_bf16 v[80:83], v[170:173], v[202:205], v[80:83]
	v_mfma_f32_16x16x32_bf16 v[72:75], v[178:181], v[202:205], v[72:75]
	v_mfma_f32_16x16x32_bf16 v[68:71], v[170:173], v[210:213], v[68:71]
	v_mfma_f32_16x16x32_bf16 v[64:67], v[178:181], v[210:213], v[64:67]
	s_setprio 0
	s_barrier
; #define PG8_STAGE(bufoff, gbase, voff) do { _Pragma("unroll") for (int _i = 0; _i < 2; ++_i) \
;         __builtin_amdgcn_global_load_lds((const unsigned*)((const char*)(gbase) + (voff)[_i]), (LAS unsigned*)(lds + (bufoff) + ldsw + _i * 8192), 16, 0, 0); } while (0)
; #define PG8_LDA(dst, b, h) do { _Pragma("unroll") for (int m = 0; m < 4; ++m) _Pragma("unroll") for (int k = 0; k < 2; ++k) dst[m][k] = *(const LAS bf16x8*)(lds + PG8_SA(b, h) + aoff + m * 2048 + k * 1024); } while (0)
; #define PG8_MMA(ai, bj, At, Bt) do { __builtin_amdgcn_s_setprio(1); _Pragma("unroll") for (int m = 0; m < 4; ++m) _Pragma("unroll") for (int n = 0; n < 2; ++n) _Pragma("unroll") for (int k = 0; k < 2; ++k) \
;         acc[ai][bj][m][n] = __builtin_amdgcn_mfma_f32_16x16x32_bf16(Bt[n][k], At[m][k], acc[ai][bj][m][n], 0, 0, 0); __builtin_amdgcn_s_setprio(0); } while (0)
; #define PG8_WAIT_V(n) asm volatile("s_waitcnt vmcnt(" #n ")" ::: "memory")
; #define PG8_WAIT_L(n) asm volatile("s_waitcnt lgkmcnt(" #n ")" ::: "memory")
; #define PG8_BAR __builtin_amdgcn_s_barrier()
; #define PG8_SCHED __builtin_amdgcn_sched_barrier(0)
; template <class Epi, bool ALIGN_EPI = true, bool SP2 = true>
; __device__ __forceinline__ void gemm_phase(LAS unsigned char* lds, const Gemm g, const StaticOrder& S, const Epi& E, const int wave_s) {
;     ...
;             PG8_LDA(At, 1, 1); PG8_STAGE(PG8_SB(1, 0), b3, voffB); PG8_STAGE(PG8_SB(1, 1), b3 + hstep, voffB); PG8_STAGE(PG8_SA(1, 0), a3, voffA);
;             PG8_WAIT_V(8); PG8_WAIT_L(0); PG8_BAR; PG8_MMA(1, 0, At, B0); PG8_MMA(1, 1, At, B1); PG8_BAR; PG8_SCHED;
;     ...
;         if constexpr (ALIGN_EPI) { if (wr == 0) PG8_BAR; }
	s_add_i32 s30, s53, s61
	v_lshl_add_u64 v[214:215], v[214:215], 0, s[10:11]
	s_mov_b32 m0, s30
	ds_read_b128 v[182:185], v153 offset:49152
	ds_read_b128 v[186:189], v153 offset:50176
	ds_read_b128 v[190:193], v153 offset:51200
	ds_read_b128 v[194:197], v153 offset:52224
	ds_read_b128 v[198:201], v153 offset:53248
	ds_read_b128 v[202:205], v153 offset:54272
	ds_read_b128 v[206:209], v153 offset:55296
	ds_read_b128 v[210:213], v153 offset:56320
	global_load_lds_dwordx4 v[214:215], off
	s_add_i32 m0, s30, 0x2000
	s_add_u32 s28, s28, 0x40080
	v_lshl_add_u64 v[214:215], v[216:217], 0, s[10:11]
	s_addc_u32 s29, s29, 0
	s_add_i32 s30, s54, s61
	global_load_lds_dwordx4 v[214:215], off
	v_lshl_add_u64 v[214:215], s[28:29], 0, v[132:133]
	s_mov_b32 m0, s30
	s_nop 0
	global_load_lds_dwordx4 v[214:215], off
	v_lshl_add_u64 v[214:215], s[28:29], 0, v[128:129]
	s_add_i32 m0, s30, 0x2000
	s_nop 0
	global_load_lds_dwordx4 v[214:215], off
	v_lshl_add_u64 v[214:215], v[218:219], 0, s[10:11]
	s_mov_b32 m0, s40
	s_nop 0
	global_load_lds_dwordx4 v[214:215], off
	v_lshl_add_u64 v[214:215], v[220:221], 0, s[10:11]
	s_mov_b32 m0, s41
	s_nop 0
	global_load_lds_dwordx4 v[214:215], off
	s_waitcnt vmcnt(8)
	s_waitcnt lgkmcnt(0)
	s_barrier
	s_setprio 1
	v_mfma_f32_16x16x32_bf16 v[60:63], v[144:147], v[182:185], v[60:63]
	v_mfma_f32_16x16x32_bf16 v[56:59], v[158:161], v[182:185], v[56:59]
	v_mfma_f32_16x16x32_bf16 v[52:55], v[144:147], v[190:193], v[52:55]
	v_mfma_f32_16x16x32_bf16 v[44:47], v[158:161], v[190:193], v[44:47]
	v_mfma_f32_16x16x32_bf16 v[36:39], v[144:147], v[198:201], v[36:39]
	v_mfma_f32_16x16x32_bf16 v[28:31], v[158:161], v[198:201], v[28:31]
	v_mfma_f32_16x16x32_bf16 v[20:23], v[144:147], v[206:209], v[20:23]
	v_mfma_f32_16x16x32_bf16 v[12:15], v[158:161], v[206:209], v[12:15]
	v_mfma_f32_16x16x32_bf16 v[60:63], v[154:157], v[186:189], v[60:63]
	v_mfma_f32_16x16x32_bf16 v[56:59], v[162:165], v[186:189], v[56:59]
	v_mfma_f32_16x16x32_bf16 v[52:55], v[154:157], v[194:197], v[52:55]
	v_mfma_f32_16x16x32_bf16 v[44:47], v[162:165], v[194:197], v[44:47]
	v_mfma_f32_16x16x32_bf16 v[36:39], v[154:157], v[202:205], v[36:39]
	v_mfma_f32_16x16x32_bf16 v[28:31], v[162:165], v[202:205], v[28:31]
	v_mfma_f32_16x16x32_bf16 v[20:23], v[154:157], v[210:213], v[20:23]
	v_mfma_f32_16x16x32_bf16 v[12:15], v[162:165], v[210:213], v[12:15]
	v_mfma_f32_16x16x32_bf16 v[48:51], v[166:169], v[182:185], v[48:51]
	v_mfma_f32_16x16x32_bf16 v[40:43], v[174:177], v[182:185], v[40:43]
	v_mfma_f32_16x16x32_bf16 v[32:35], v[166:169], v[190:193], v[32:35]
	v_mfma_f32_16x16x32_bf16 v[24:27], v[174:177], v[190:193], v[24:27]
	v_mfma_f32_16x16x32_bf16 v[16:19], v[166:169], v[198:201], v[16:19]
	v_mfma_f32_16x16x32_bf16 v[8:11], v[174:177], v[198:201], v[8:11]
	v_mfma_f32_16x16x32_bf16 v[4:7], v[166:169], v[206:209], v[4:7]
	v_mfma_f32_16x16x32_bf16 v[0:3], v[174:177], v[206:209], v[0:3]
	v_mfma_f32_16x16x32_bf16 v[48:51], v[170:173], v[186:189], v[48:51]
	v_mfma_f32_16x16x32_bf16 v[40:43], v[178:181], v[186:189], v[40:43]
	v_mfma_f32_16x16x32_bf16 v[32:35], v[170:173], v[194:197], v[32:35]
	v_mfma_f32_16x16x32_bf16 v[24:27], v[178:181], v[194:197], v[24:27]
	v_mfma_f32_16x16x32_bf16 v[16:19], v[170:173], v[202:205], v[16:19]
	v_mfma_f32_16x16x32_bf16 v[8:11], v[178:181], v[202:205], v[8:11]
	v_mfma_f32_16x16x32_bf16 v[4:7], v[170:173], v[210:213], v[4:7]
	v_mfma_f32_16x16x32_bf16 v[0:3], v[178:181], v[210:213], v[0:3]
	s_setprio 0
	s_barrier
	s_add_i32 s52, s52, 2
	s_add_u32 s50, s50, 0x100
	s_addc_u32 s51, s51, 0
	s_add_u32 s26, s26, 0x100
	s_addc_u32 s27, s27, 0
	s_cmp_gt_u32 s52, 13
	s_cbranch_scc0 .LBB0_829
	s_and_b64 vcc, exec, s[14:15]
	s_cbranch_vccz .LBB0_832
	s_barrier

; #define PG8_STAGE(bufoff, gbase, voff) do { _Pragma("unroll") for (int _i = 0; _i < 2; ++_i) \
;         __builtin_amdgcn_global_load_lds((const unsigned*)((const char*)(gbase) + (voff)[_i]), (LAS unsigned*)(lds + (bufoff) + ldsw + _i * 8192), 16, 0, 0); } while (0)
; #define PG8_LDA(dst, b, h) do { _Pragma("unroll") for (int m = 0; m < 4; ++m) _Pragma("unroll") for (int k = 0; k < 2; ++k) dst[m][k] = *(const LAS bf16x8*)(lds + PG8_SA(b, h) + aoff + m * 2048 + k * 1024); } while (0)
; #define PG8_LDB(dst, b, h) do { _Pragma("unroll") for (int n = 0; n < 2; ++n) _Pragma("unroll") for (int k = 0; k < 2; ++k) dst[n][k] = *(const LAS bf16x8*)(lds + PG8_SB(b, h) + boff + n * 2048 + k * 1024); } while (0)
; #define PG8_MMA(ai, bj, At, Bt) do { __builtin_amdgcn_s_setprio(1); _Pragma("unroll") for (int m = 0; m < 4; ++m) _Pragma("unroll") for (int n = 0; n < 2; ++n) _Pragma("unroll") for (int k = 0; k < 2; ++k) \
;         acc[ai][bj][m][n] = __builtin_amdgcn_mfma_f32_16x16x32_bf16(Bt[n][k], At[m][k], acc[ai][bj][m][n], 0, 0, 0); __builtin_amdgcn_s_setprio(0); } while (0)
; #define PG8_WAIT_V(n) asm volatile("s_waitcnt vmcnt(" #n ")" ::: "memory")
; #define PG8_WAIT_L(n) asm volatile("s_waitcnt lgkmcnt(" #n ")" ::: "memory")
; #define PG8_BAR __builtin_amdgcn_s_barrier()
; #define PG8_SCHED __builtin_amdgcn_sched_barrier(0)
; template <class Epi, bool ALIGN_EPI = true, bool SP2 = true>
; __device__ __forceinline__ void gemm_phase(LAS unsigned char* lds, const Gemm g, const StaticOrder& S, const Epi& E, const int wave_s) {
;     ...
;             PG8_LDB(B0, 0, 0); PG8_LDB(B1, 0, 1); PG8_SCHED; PG8_LDA(At, 0, 0); PG8_STAGE(PG8_SA(1, 1), a1 + hstep, voffA);
;             PG8_WAIT_V(8); PG8_WAIT_L(0); PG8_BAR; PG8_MMA(0, 0, At, B0); PG8_MMA(0, 1, At, B1); PG8_BAR; PG8_SCHED;
;             PG8_LDA(At, 0, 1); PG8_STAGE(PG8_SB(0, 0), b2, voffB); PG8_STAGE(PG8_SB(0, 1), b2 + hstep, voffB); PG8_STAGE(PG8_SA(0, 0), a2, voffA);
;             PG8_WAIT_V(8); PG8_WAIT_L(0); PG8_BAR; PG8_MMA(1, 0, At, B0); PG8_MMA(1, 1, At, B1); PG8_BAR; PG8_SCHED;
.LBB0_1190:
	ds_read_b128 v[140:143], v185
	ds_read_b128 v[144:147], v185 offset:1024
	ds_read_b128 v[148:151], v185 offset:2048
	ds_read_b128 v[152:155], v185 offset:3072
	ds_read_b128 v[156:159], v186
	ds_read_b128 v[160:163], v186 offset:1024
	ds_read_b128 v[164:167], v186 offset:2048
	ds_read_b128 v[168:171], v186 offset:3072
	s_add_u32 s50, s48, 0xfffc0080
	s_addc_u32 s51, s49, -1
	s_cmp_eq_u32 s68, 12
	s_cselect_b32 s53, s37, s51
	s_cselect_b32 s52, s64, s50
	s_cselect_b32 s51, s35, s67
	s_cselect_b32 s50, s65, s66
	v_lshl_add_u64 v[180:181], s[48:49], 0, v[138:139]
	s_add_i32 m0, s39, 0xc000
	ds_read_b128 v[172:175], v187
	ds_read_b128 v[176:179], v187 offset:1024
	ds_read_b128 v[188:191], v187 offset:2048
	ds_read_b128 v[192:195], v187 offset:3072
	ds_read_b128 v[196:199], v187 offset:4096
	ds_read_b128 v[200:203], v187 offset:5120
	ds_read_b128 v[204:207], v187 offset:6144
	ds_read_b128 v[208:211], v187 offset:7168
	global_load_lds_dwordx4 v[180:181], off
	v_lshl_add_u64 v[180:181], s[48:49], 0, v[136:137]
	s_add_i32 m0, s39, 0xe000
	s_nop 0
	global_load_lds_dwordx4 v[180:181], off
	s_waitcnt vmcnt(8)
	s_waitcnt lgkmcnt(0)
	s_barrier
	s_setprio 1
	v_mfma_f32_16x16x32_bf16 v[124:127], v[140:143], v[172:175], v[124:127]
	v_mfma_f32_16x16x32_bf16 v[120:123], v[148:151], v[172:175], v[120:123]
	v_mfma_f32_16x16x32_bf16 v[116:119], v[140:143], v[188:191], v[116:119]
	v_mfma_f32_16x16x32_bf16 v[112:115], v[148:151], v[188:191], v[112:115]
	v_mfma_f32_16x16x32_bf16 v[108:111], v[140:143], v[196:199], v[108:111]
	v_mfma_f32_16x16x32_bf16 v[104:107], v[148:151], v[196:199], v[104:107]
	v_mfma_f32_16x16x32_bf16 v[100:103], v[140:143], v[204:207], v[100:103]
	v_mfma_f32_16x16x32_bf16 v[96:99], v[148:151], v[204:207], v[96:99]
	v_mfma_f32_16x16x32_bf16 v[124:127], v[144:147], v[176:179], v[124:127]
	v_mfma_f32_16x16x32_bf16 v[120:123], v[152:155], v[176:179], v[120:123]
	v_mfma_f32_16x16x32_bf16 v[116:119], v[144:147], v[192:195], v[116:119]
	v_mfma_f32_16x16x32_bf16 v[112:115], v[152:155], v[192:195], v[112:115]
	v_mfma_f32_16x16x32_bf16 v[108:111], v[144:147], v[200:203], v[108:111]
	v_mfma_f32_16x16x32_bf16 v[104:107], v[152:155], v[200:203], v[104:107]
	v_mfma_f32_16x16x32_bf16 v[100:103], v[144:147], v[208:211], v[100:103]
	v_mfma_f32_16x16x32_bf16 v[96:99], v[152:155], v[208:211], v[96:99]
	v_mfma_f32_16x16x32_bf16 v[60:63], v[156:159], v[172:175], v[60:63]
	v_mfma_f32_16x16x32_bf16 v[56:59], v[164:167], v[172:175], v[56:59]
	v_mfma_f32_16x16x32_bf16 v[52:55], v[156:159], v[188:191], v[52:55]
	v_mfma_f32_16x16x32_bf16 v[48:51], v[164:167], v[188:191], v[48:51]
	v_mfma_f32_16x16x32_bf16 v[44:47], v[156:159], v[196:199], v[44:47]
	v_mfma_f32_16x16x32_bf16 v[40:43], v[164:167], v[196:199], v[40:43]
	v_mfma_f32_16x16x32_bf16 v[36:39], v[156:159], v[204:207], v[36:39]
	v_mfma_f32_16x16x32_bf16 v[32:35], v[164:167], v[204:207], v[32:35]
	v_mfma_f32_16x16x32_bf16 v[60:63], v[160:163], v[176:179], v[60:63]
	v_mfma_f32_16x16x32_bf16 v[56:59], v[168:171], v[176:179], v[56:59]
	v_mfma_f32_16x16x32_bf16 v[52:55], v[160:163], v[192:195], v[52:55]
	v_mfma_f32_16x16x32_bf16 v[48:51], v[168:171], v[192:195], v[48:51]
	v_mfma_f32_16x16x32_bf16 v[44:47], v[160:163], v[200:203], v[44:47]
	v_mfma_f32_16x16x32_bf16 v[40:43], v[168:171], v[200:203], v[40:43]
	v_mfma_f32_16x16x32_bf16 v[36:39], v[160:163], v[208:211], v[36:39]
	v_mfma_f32_16x16x32_bf16 v[32:35], v[168:171], v[208:211], v[32:35]
	s_setprio 0
	s_barrier
	s_add_i32 s69, s60, s61
	v_lshl_add_u64 v[180:181], s[50:51], 0, v[130:131]
	s_mov_b32 m0, s69
	ds_read_b128 v[172:175], v187 offset:16384
	ds_read_b128 v[176:179], v187 offset:17408
	ds_read_b128 v[188:191], v187 offset:18432
	ds_read_b128 v[192:195], v187 offset:19456
	ds_read_b128 v[196:199], v187 offset:20480
	ds_read_b128 v[200:203], v187 offset:21504
	ds_read_b128 v[204:207], v187 offset:22528
	ds_read_b128 v[208:211], v187 offset:23552
	global_load_lds_dwordx4 v[180:181], off
	s_add_i32 m0, s69, 0x2000
	s_add_u32 s70, s50, 0x40000
	v_lshl_add_u64 v[212:213], s[50:51], 0, v[134:135]
	s_addc_u32 s71, s51, 0
	s_add_i32 s69, s62, s61
	global_load_lds_dwordx4 v[212:213], off
	v_lshl_add_u64 v[214:215], s[70:71], 0, v[130:131]
	s_mov_b32 m0, s69
	v_lshl_add_u64 v[216:217], s[52:53], 0, v[132:133]
	global_load_lds_dwordx4 v[214:215], off
	v_lshl_add_u64 v[214:215], s[70:71], 0, v[134:135]
	s_add_i32 m0, s69, 0x2000
	s_nop 0
	global_load_lds_dwordx4 v[214:215], off
	v_lshl_add_u64 v[214:215], s[52:53], 0, v[128:129]
	s_mov_b32 m0, s39
	s_nop 0
	global_load_lds_dwordx4 v[214:215], off
	s_mov_b32 m0, s40
	s_nop 0
	global_load_lds_dwordx4 v[216:217], off
	s_waitcnt vmcnt(8)
	s_waitcnt lgkmcnt(0)
	s_barrier
; #define PG8_STAGE(bufoff, gbase, voff) do { _Pragma("unroll") for (int _i = 0; _i < 2; ++_i) \
;         __builtin_amdgcn_global_load_lds((const unsigned*)((const char*)(gbase) + (voff)[_i]), (LAS unsigned*)(lds + (bufoff) + ldsw + _i * 8192), 16, 0, 0); } while (0)
; #define PG8_LDA(dst, b, h) do { _Pragma("unroll") for (int m = 0; m < 4; ++m) _Pragma("unroll") for (int k = 0; k < 2; ++k) dst[m][k] = *(const LAS bf16x8*)(lds + PG8_SA(b, h) + aoff + m * 2048 + k * 1024); } while (0)
; #define PG8_LDB(dst, b, h) do { _Pragma("unroll") for (int n = 0; n < 2; ++n) _Pragma("unroll") for (int k = 0; k < 2; ++k) dst[n][k] = *(const LAS bf16x8*)(lds + PG8_SB(b, h) + boff + n * 2048 + k * 1024); } while (0)
; #define PG8_MMA(ai, bj, At, Bt) do { __builtin_amdgcn_s_setprio(1); _Pragma("unroll") for (int m = 0; m < 4; ++m) _Pragma("unroll") for (int n = 0; n < 2; ++n) _Pragma("unroll") for (int k = 0; k < 2; ++k) \
;         acc[ai][bj][m][n] = __builtin_amdgcn_mfma_f32_16x16x32_bf16(Bt[n][k], At[m][k], acc[ai][bj][m][n], 0, 0, 0); __builtin_amdgcn_s_setprio(0); } while (0)
; #define PG8_WAIT_V(n) asm volatile("s_waitcnt vmcnt(" #n ")" ::: "memory")
; #define PG8_WAIT_L(n) asm volatile("s_waitcnt lgkmcnt(" #n ")" ::: "memory")
; #define PG8_BAR __builtin_amdgcn_s_barrier()
; #define PG8_SCHED __builtin_amdgcn_sched_barrier(0)
; template <class Epi, bool ALIGN_EPI = true, bool SP2 = true>
; __device__ __forceinline__ void gemm_phase(LAS unsigned char* lds, const Gemm g, const StaticOrder& S, const Epi& E, const int wave_s) {
;     ...
;             PG8_WAIT_V(8); PG8_WAIT_L(0); PG8_BAR; PG8_MMA(1, 0, At, B0); PG8_MMA(1, 1, At, B1); PG8_BAR; PG8_SCHED;
;             PG8_LDB(B0, 1, 0); PG8_LDB(B1, 1, 1); PG8_SCHED; PG8_LDA(At, 1, 0); PG8_STAGE(PG8_SA(0, 1), a2 + hstep, voffA);
;             PG8_WAIT_V(8); PG8_WAIT_L(0); PG8_BAR; PG8_MMA(0, 0, At, B0); PG8_MMA(0, 1, At, B1); PG8_BAR; PG8_SCHED;
	s_setprio 1
	v_mfma_f32_16x16x32_bf16 v[92:95], v[140:143], v[172:175], v[92:95]
	v_mfma_f32_16x16x32_bf16 v[88:91], v[148:151], v[172:175], v[88:91]
	v_mfma_f32_16x16x32_bf16 v[84:87], v[140:143], v[188:191], v[84:87]
	v_mfma_f32_16x16x32_bf16 v[80:83], v[148:151], v[188:191], v[80:83]
	v_mfma_f32_16x16x32_bf16 v[76:79], v[140:143], v[196:199], v[76:79]
	v_mfma_f32_16x16x32_bf16 v[72:75], v[148:151], v[196:199], v[72:75]
	v_mfma_f32_16x16x32_bf16 v[68:71], v[140:143], v[204:207], v[68:71]
	v_mfma_f32_16x16x32_bf16 v[64:67], v[148:151], v[204:207], v[64:67]
	v_mfma_f32_16x16x32_bf16 v[92:95], v[144:147], v[176:179], v[92:95]
	v_mfma_f32_16x16x32_bf16 v[88:91], v[152:155], v[176:179], v[88:91]
	v_mfma_f32_16x16x32_bf16 v[84:87], v[144:147], v[192:195], v[84:87]
	v_mfma_f32_16x16x32_bf16 v[80:83], v[152:155], v[192:195], v[80:83]
	v_mfma_f32_16x16x32_bf16 v[76:79], v[144:147], v[200:203], v[76:79]
	v_mfma_f32_16x16x32_bf16 v[72:75], v[152:155], v[200:203], v[72:75]
	v_mfma_f32_16x16x32_bf16 v[68:71], v[144:147], v[208:211], v[68:71]
	v_mfma_f32_16x16x32_bf16 v[64:67], v[152:155], v[208:211], v[64:67]
	v_mfma_f32_16x16x32_bf16 v[28:31], v[156:159], v[172:175], v[28:31]
	v_mfma_f32_16x16x32_bf16 v[24:27], v[164:167], v[172:175], v[24:27]
	v_mfma_f32_16x16x32_bf16 v[20:23], v[156:159], v[188:191], v[20:23]
	v_mfma_f32_16x16x32_bf16 v[16:19], v[164:167], v[188:191], v[16:19]
	v_mfma_f32_16x16x32_bf16 v[12:15], v[156:159], v[196:199], v[12:15]
	v_mfma_f32_16x16x32_bf16 v[8:11], v[164:167], v[196:199], v[8:11]
	v_mfma_f32_16x16x32_bf16 v[4:7], v[156:159], v[204:207], v[4:7]
	v_mfma_f32_16x16x32_bf16 v[0:3], v[164:167], v[204:207], v[0:3]
	v_mfma_f32_16x16x32_bf16 v[28:31], v[160:163], v[176:179], v[28:31]
	v_mfma_f32_16x16x32_bf16 v[24:27], v[168:171], v[176:179], v[24:27]
	v_mfma_f32_16x16x32_bf16 v[20:23], v[160:163], v[192:195], v[20:23]
	v_mfma_f32_16x16x32_bf16 v[16:19], v[168:171], v[192:195], v[16:19]
	v_mfma_f32_16x16x32_bf16 v[12:15], v[160:163], v[200:203], v[12:15]
	v_mfma_f32_16x16x32_bf16 v[8:11], v[168:171], v[200:203], v[8:11]
	v_mfma_f32_16x16x32_bf16 v[4:7], v[160:163], v[208:211], v[4:7]
	v_mfma_f32_16x16x32_bf16 v[0:3], v[168:171], v[208:211], v[0:3]
	s_setprio 0
	s_barrier
	s_add_i32 s69, 0, 0x18000
	s_add_i32 s70, 0, 0x1c000
	v_add_u32_e32 v152, s69, v183
	v_add_u32_e32 v168, s70, v183
	ds_read_b128 v[140:143], v152
	ds_read_b128 v[144:147], v152 offset:1024
	ds_read_b128 v[148:151], v152 offset:2048
	ds_read_b128 v[152:155], v152 offset:3072
	ds_read_b128 v[156:159], v168
	ds_read_b128 v[160:163], v168 offset:1024
	ds_read_b128 v[164:167], v168 offset:2048
	ds_read_b128 v[168:171], v168 offset:3072
	s_add_u32 s52, s52, 0x40000
	s_addc_u32 s53, s53, 0
	s_mov_b32 m0, s41
	v_lshl_add_u64 v[218:219], s[52:53], 0, v[128:129]
	ds_read_b128 v[172:175], v187 offset:32768
	ds_read_b128 v[176:179], v187 offset:33792
	ds_read_b128 v[188:191], v187 offset:34816
	ds_read_b128 v[192:195], v187 offset:35840
	ds_read_b128 v[196:199], v187 offset:36864
	ds_read_b128 v[200:203], v187 offset:37888
	ds_read_b128 v[204:207], v187 offset:38912
	ds_read_b128 v[208:211], v187 offset:39936
	global_load_lds_dwordx4 v[218:219], off
	v_lshl_add_u64 v[218:219], s[52:53], 0, v[132:133]
	s_mov_b32 m0, s47
	s_nop 0
	global_load_lds_dwordx4 v[218:219], off
	s_waitcnt vmcnt(8)
	s_waitcnt lgkmcnt(0)
	s_barrier
	s_setprio 1
	v_mfma_f32_16x16x32_bf16 v[124:127], v[140:143], v[172:175], v[124:127]
	v_mfma_f32_16x16x32_bf16 v[120:123], v[148:151], v[172:175], v[120:123]
	v_mfma_f32_16x16x32_bf16 v[116:119], v[140:143], v[188:191], v[116:119]
	v_mfma_f32_16x16x32_bf16 v[112:115], v[148:151], v[188:191], v[112:115]
	v_mfma_f32_16x16x32_bf16 v[108:111], v[140:143], v[196:199], v[108:111]
	v_mfma_f32_16x16x32_bf16 v[104:107], v[148:151], v[196:199], v[104:107]
	v_mfma_f32_16x16x32_bf16 v[100:103], v[140:143], v[204:207], v[100:103]
	v_mfma_f32_16x16x32_bf16 v[96:99], v[148:151], v[204:207], v[96:99]
	v_mfma_f32_16x16x32_bf16 v[124:127], v[144:147], v[176:179], v[124:127]
	v_mfma_f32_16x16x32_bf16 v[120:123], v[152:155], v[176:179], v[120:123]
	v_mfma_f32_16x16x32_bf16 v[116:119], v[144:147], v[192:195], v[116:119]
	v_mfma_f32_16x16x32_bf16 v[112:115], v[152:155], v[192:195], v[112:115]
	v_mfma_f32_16x16x32_bf16 v[108:111], v[144:147], v[200:203], v[108:111]
	v_mfma_f32_16x16x32_bf16 v[104:107], v[152:155], v[200:203], v[104:107]
	v_mfma_f32_16x16x32_bf16 v[100:103], v[144:147], v[208:211], v[100:103]
	v_mfma_f32_16x16x32_bf16 v[96:99], v[152:155], v[208:211], v[96:99]
	v_mfma_f32_16x16x32_bf16 v[60:63], v[156:159], v[172:175], v[60:63]
	v_mfma_f32_16x16x32_bf16 v[56:59], v[164:167], v[172:175], v[56:59]
	v_mfma_f32_16x16x32_bf16 v[52:55], v[156:159], v[188:191], v[52:55]
	v_mfma_f32_16x16x32_bf16 v[48:51], v[164:167], v[188:191], v[48:51]
	v_mfma_f32_16x16x32_bf16 v[44:47], v[156:159], v[196:199], v[44:47]
	v_mfma_f32_16x16x32_bf16 v[40:43], v[164:167], v[196:199], v[40:43]
	v_mfma_f32_16x16x32_bf16 v[36:39], v[156:159], v[204:207], v[36:39]
	v_mfma_f32_16x16x32_bf16 v[32:35], v[164:167], v[204:207], v[32:35]
	v_mfma_f32_16x16x32_bf16 v[60:63], v[160:163], v[176:179], v[60:63]
	v_mfma_f32_16x16x32_bf16 v[56:59], v[168:171], v[176:179], v[56:59]
	v_mfma_f32_16x16x32_bf16 v[52:55], v[160:163], v[192:195], v[52:55]
	v_mfma_f32_16x16x32_bf16 v[48:51], v[168:171], v[192:195], v[48:51]
	v_mfma_f32_16x16x32_bf16 v[44:47], v[160:163], v[200:203], v[44:47]
	v_mfma_f32_16x16x32_bf16 v[40:43], v[168:171], v[200:203], v[40:43]
	v_mfma_f32_16x16x32_bf16 v[36:39], v[160:163], v[208:211], v[36:39]
	v_mfma_f32_16x16x32_bf16 v[32:35], v[168:171], v[208:211], v[32:35]
	s_setprio 0
	s_barrier
; #define PG8_STAGE(bufoff, gbase, voff) do { _Pragma("unroll") for (int _i = 0; _i < 2; ++_i) \
;         __builtin_amdgcn_global_load_lds((const unsigned*)((const char*)(gbase) + (voff)[_i]), (LAS unsigned*)(lds + (bufoff) + ldsw + _i * 8192), 16, 0, 0); } while (0)
; #define PG8_LDA(dst, b, h) do { _Pragma("unroll") for (int m = 0; m < 4; ++m) _Pragma("unroll") for (int k = 0; k < 2; ++k) dst[m][k] = *(const LAS bf16x8*)(lds + PG8_SA(b, h) + aoff + m * 2048 + k * 1024); } while (0)
; #define PG8_MMA(ai, bj, At, Bt) do { __builtin_amdgcn_s_setprio(1); _Pragma("unroll") for (int m = 0; m < 4; ++m) _Pragma("unroll") for (int n = 0; n < 2; ++n) _Pragma("unroll") for (int k = 0; k < 2; ++k) \
;         acc[ai][bj][m][n] = __builtin_amdgcn_mfma_f32_16x16x32_bf16(Bt[n][k], At[m][k], acc[ai][bj][m][n], 0, 0, 0); __builtin_amdgcn_s_setprio(0); } while (0)
; #define PG8_WAIT_V(n) asm volatile("s_waitcnt vmcnt(" #n ")" ::: "memory")
; #define PG8_WAIT_L(n) asm volatile("s_waitcnt lgkmcnt(" #n ")" ::: "memory")
; #define PG8_BAR __builtin_amdgcn_s_barrier()
; #define PG8_SCHED __builtin_amdgcn_sched_barrier(0)
; template <class Epi, bool ALIGN_EPI = true, bool SP2 = true>
; __device__ __forceinline__ void gemm_phase(LAS unsigned char* lds, const Gemm g, const StaticOrder& S, const Epi& E, const int wave_s) {
;     ...
;             PG8_LDA(At, 1, 1); PG8_STAGE(PG8_SB(1, 0), b3, voffB); PG8_STAGE(PG8_SB(1, 1), b3 + hstep, voffB); PG8_STAGE(PG8_SA(1, 0), a3, voffA);
;             PG8_WAIT_V(8); PG8_WAIT_L(0); PG8_BAR; PG8_MMA(1, 0, At, B0); PG8_MMA(1, 1, At, B1); PG8_BAR; PG8_SCHED;
;     ...
;         if constexpr (ALIGN_EPI) { if (wr == 0) PG8_BAR; }
	s_add_i32 s52, s69, s61
	v_lshl_add_u64 v[180:181], v[180:181], 0, s[18:19]
	s_mov_b32 m0, s52
	ds_read_b128 v[172:175], v187 offset:49152
	ds_read_b128 v[176:179], v187 offset:50176
	ds_read_b128 v[188:191], v187 offset:51200
	ds_read_b128 v[192:195], v187 offset:52224
	ds_read_b128 v[196:199], v187 offset:53248
	ds_read_b128 v[200:203], v187 offset:54272
	ds_read_b128 v[204:207], v187 offset:55296
	ds_read_b128 v[208:211], v187 offset:56320
	global_load_lds_dwordx4 v[180:181], off
	s_add_i32 m0, s52, 0x2000
	s_add_u32 s50, s50, 0x40080
	v_lshl_add_u64 v[180:181], v[212:213], 0, s[18:19]
	s_addc_u32 s51, s51, 0
	s_add_i32 s52, s70, s61
	global_load_lds_dwordx4 v[180:181], off
	v_lshl_add_u64 v[180:181], s[50:51], 0, v[130:131]
	s_mov_b32 m0, s52
	s_nop 0
	global_load_lds_dwordx4 v[180:181], off
	v_lshl_add_u64 v[180:181], s[50:51], 0, v[134:135]
	s_add_i32 m0, s52, 0x2000
	s_nop 0
	global_load_lds_dwordx4 v[180:181], off
	v_lshl_add_u64 v[180:181], v[214:215], 0, s[18:19]
	s_mov_b32 m0, s57
	s_nop 0
	global_load_lds_dwordx4 v[180:181], off
	v_lshl_add_u64 v[180:181], v[216:217], 0, s[18:19]
	s_mov_b32 m0, s58
	s_nop 0
	global_load_lds_dwordx4 v[180:181], off
	s_waitcnt vmcnt(8)
	s_waitcnt lgkmcnt(0)
	s_barrier
	s_setprio 1
	v_mfma_f32_16x16x32_bf16 v[92:95], v[140:143], v[172:175], v[92:95]
	v_mfma_f32_16x16x32_bf16 v[88:91], v[148:151], v[172:175], v[88:91]
	v_mfma_f32_16x16x32_bf16 v[84:87], v[140:143], v[188:191], v[84:87]
	v_mfma_f32_16x16x32_bf16 v[80:83], v[148:151], v[188:191], v[80:83]
	v_mfma_f32_16x16x32_bf16 v[76:79], v[140:143], v[196:199], v[76:79]
	v_mfma_f32_16x16x32_bf16 v[72:75], v[148:151], v[196:199], v[72:75]
	v_mfma_f32_16x16x32_bf16 v[68:71], v[140:143], v[204:207], v[68:71]
	v_mfma_f32_16x16x32_bf16 v[64:67], v[148:151], v[204:207], v[64:67]
	v_mfma_f32_16x16x32_bf16 v[92:95], v[144:147], v[176:179], v[92:95]
	v_mfma_f32_16x16x32_bf16 v[88:91], v[152:155], v[176:179], v[88:91]
	v_mfma_f32_16x16x32_bf16 v[84:87], v[144:147], v[192:195], v[84:87]
	v_mfma_f32_16x16x32_bf16 v[80:83], v[152:155], v[192:195], v[80:83]
	v_mfma_f32_16x16x32_bf16 v[76:79], v[144:147], v[200:203], v[76:79]
	v_mfma_f32_16x16x32_bf16 v[72:75], v[152:155], v[200:203], v[72:75]
	v_mfma_f32_16x16x32_bf16 v[68:71], v[144:147], v[208:211], v[68:71]
	v_mfma_f32_16x16x32_bf16 v[64:67], v[152:155], v[208:211], v[64:67]
	v_mfma_f32_16x16x32_bf16 v[28:31], v[156:159], v[172:175], v[28:31]
	v_mfma_f32_16x16x32_bf16 v[24:27], v[164:167], v[172:175], v[24:27]
	v_mfma_f32_16x16x32_bf16 v[20:23], v[156:159], v[188:191], v[20:23]
	v_mfma_f32_16x16x32_bf16 v[16:19], v[164:167], v[188:191], v[16:19]
	v_mfma_f32_16x16x32_bf16 v[12:15], v[156:159], v[196:199], v[12:15]
	v_mfma_f32_16x16x32_bf16 v[8:11], v[164:167], v[196:199], v[8:11]
	v_mfma_f32_16x16x32_bf16 v[4:7], v[156:159], v[204:207], v[4:7]
	v_mfma_f32_16x16x32_bf16 v[0:3], v[164:167], v[204:207], v[0:3]
	v_mfma_f32_16x16x32_bf16 v[28:31], v[160:163], v[176:179], v[28:31]
	v_mfma_f32_16x16x32_bf16 v[24:27], v[168:171], v[176:179], v[24:27]
	v_mfma_f32_16x16x32_bf16 v[20:23], v[160:163], v[192:195], v[20:23]
	v_mfma_f32_16x16x32_bf16 v[16:19], v[168:171], v[192:195], v[16:19]
	v_mfma_f32_16x16x32_bf16 v[12:15], v[160:163], v[200:203], v[12:15]
	v_mfma_f32_16x16x32_bf16 v[8:11], v[168:171], v[200:203], v[8:11]
	v_mfma_f32_16x16x32_bf16 v[4:7], v[160:163], v[208:211], v[4:7]
	v_mfma_f32_16x16x32_bf16 v[0:3], v[168:171], v[208:211], v[0:3]
	s_setprio 0
	s_barrier
	s_add_i32 s68, s68, 2
	s_add_u32 s66, s66, 0x100
	s_addc_u32 s67, s67, 0
	s_add_u32 s48, s48, 0x100
	s_addc_u32 s49, s49, 0
	s_cmp_gt_u32 s68, 13
	s_cbranch_scc0 .LBB0_1190
	s_and_b64 vcc, exec, s[20:21]
	s_cbranch_vccz .LBB0_1193
	s_barrier

; #define PG8_STAGE(bufoff, gbase, voff) do { _Pragma("unroll") for (int _i = 0; _i < 2; ++_i) \
;         __builtin_amdgcn_global_load_lds((const unsigned*)((const char*)(gbase) + (voff)[_i]), (LAS unsigned*)(lds + (bufoff) + ldsw + _i * 8192), 16, 0, 0); } while (0)
; #define PG8_LDA(dst, b, h) do { _Pragma("unroll") for (int m = 0; m < 4; ++m) _Pragma("unroll") for (int k = 0; k < 2; ++k) dst[m][k] = *(const LAS bf16x8*)(lds + PG8_SA(b, h) + aoff + m * 2048 + k * 1024); } while (0)
; #define PG8_LDB(dst, b, h) do { _Pragma("unroll") for (int n = 0; n < 2; ++n) _Pragma("unroll") for (int k = 0; k < 2; ++k) dst[n][k] = *(const LAS bf16x8*)(lds + PG8_SB(b, h) + boff + n * 2048 + k * 1024); } while (0)
; #define PG8_MMA(ai, bj, At, Bt) do { __builtin_amdgcn_s_setprio(1); _Pragma("unroll") for (int m = 0; m < 4; ++m) _Pragma("unroll") for (int n = 0; n < 2; ++n) _Pragma("unroll") for (int k = 0; k < 2; ++k) \
;         acc[ai][bj][m][n] = __builtin_amdgcn_mfma_f32_16x16x32_bf16(Bt[n][k], At[m][k], acc[ai][bj][m][n], 0, 0, 0); __builtin_amdgcn_s_setprio(0); } while (0)
; #define PG8_WAIT_V(n) asm volatile("s_waitcnt vmcnt(" #n ")" ::: "memory")
; #define PG8_WAIT_L(n) asm volatile("s_waitcnt lgkmcnt(" #n ")" ::: "memory")
; #define PG8_BAR __builtin_amdgcn_s_barrier()
; #define PG8_SCHED __builtin_amdgcn_sched_barrier(0)
; template <class Epi, bool ALIGN_EPI = true, bool SP2 = true>
; __device__ __forceinline__ void gemm_phase(LAS unsigned char* lds, const Gemm g, const StaticOrder& S, const Epi& E, const int wave_s) {
;     ...
;             PG8_LDB(B0, 0, 0); PG8_LDB(B1, 0, 1); PG8_SCHED; PG8_LDA(At, 0, 0); PG8_STAGE(PG8_SA(1, 1), a1 + hstep, voffA);
;             PG8_WAIT_V(8); PG8_WAIT_L(0); PG8_BAR; PG8_MMA(0, 0, At, B0); PG8_MMA(0, 1, At, B1); PG8_BAR; PG8_SCHED;
;             PG8_LDA(At, 0, 1); PG8_STAGE(PG8_SB(0, 0), b2, voffB); PG8_STAGE(PG8_SB(0, 1), b2 + hstep, voffB); PG8_STAGE(PG8_SA(0, 0), a2, voffA);
;             PG8_WAIT_V(8); PG8_WAIT_L(0); PG8_BAR; PG8_MMA(1, 0, At, B0); PG8_MMA(1, 1, At, B1); PG8_BAR; PG8_SCHED;
.LBB0_1404:
	ds_read_b128 v[140:143], v185
	ds_read_b128 v[144:147], v185 offset:1024
	ds_read_b128 v[148:151], v185 offset:2048
	ds_read_b128 v[152:155], v185 offset:3072
	ds_read_b128 v[156:159], v186
	ds_read_b128 v[160:163], v186 offset:1024
	ds_read_b128 v[164:167], v186 offset:2048
	ds_read_b128 v[168:171], v186 offset:3072
	s_add_u32 s42, s40, 0x100
	s_addc_u32 s43, s41, 0
	s_cmp_eq_u32 s66, 40
	s_cselect_b32 s47, s7, s43
	s_cselect_b32 s46, s6, s42
	s_cselect_b32 s45, s37, s65
	s_cselect_b32 s44, s36, s64
	v_lshl_add_u64 v[180:181], s[40:41], 0, v[138:139]
	s_add_i32 m0, s39, 0xc000
	ds_read_b128 v[172:175], v187
	ds_read_b128 v[176:179], v187 offset:1024
	ds_read_b128 v[188:191], v187 offset:2048
	ds_read_b128 v[192:195], v187 offset:3072
	ds_read_b128 v[196:199], v187 offset:4096
	ds_read_b128 v[200:203], v187 offset:5120
	ds_read_b128 v[204:207], v187 offset:6144
	ds_read_b128 v[208:211], v187 offset:7168
	global_load_lds_dwordx4 v[180:181], off
	v_lshl_add_u64 v[180:181], s[40:41], 0, v[136:137]
	s_add_i32 m0, s39, 0xe000
	s_nop 0
	global_load_lds_dwordx4 v[180:181], off
	s_waitcnt vmcnt(8)
	s_waitcnt lgkmcnt(0)
	s_barrier
	s_setprio 1
	v_mfma_f32_16x16x32_bf16 v[124:127], v[140:143], v[172:175], v[124:127]
	v_mfma_f32_16x16x32_bf16 v[120:123], v[148:151], v[172:175], v[120:123]
	v_mfma_f32_16x16x32_bf16 v[116:119], v[140:143], v[188:191], v[116:119]
	v_mfma_f32_16x16x32_bf16 v[112:115], v[148:151], v[188:191], v[112:115]
	v_mfma_f32_16x16x32_bf16 v[108:111], v[140:143], v[196:199], v[108:111]
	v_mfma_f32_16x16x32_bf16 v[104:107], v[148:151], v[196:199], v[104:107]
	v_mfma_f32_16x16x32_bf16 v[100:103], v[140:143], v[204:207], v[100:103]
	v_mfma_f32_16x16x32_bf16 v[96:99], v[148:151], v[204:207], v[96:99]
	v_mfma_f32_16x16x32_bf16 v[124:127], v[144:147], v[176:179], v[124:127]
	v_mfma_f32_16x16x32_bf16 v[120:123], v[152:155], v[176:179], v[120:123]
	v_mfma_f32_16x16x32_bf16 v[116:119], v[144:147], v[192:195], v[116:119]
	v_mfma_f32_16x16x32_bf16 v[112:115], v[152:155], v[192:195], v[112:115]
	v_mfma_f32_16x16x32_bf16 v[108:111], v[144:147], v[200:203], v[108:111]
	v_mfma_f32_16x16x32_bf16 v[104:107], v[152:155], v[200:203], v[104:107]
	v_mfma_f32_16x16x32_bf16 v[100:103], v[144:147], v[208:211], v[100:103]
	v_mfma_f32_16x16x32_bf16 v[96:99], v[152:155], v[208:211], v[96:99]
	v_mfma_f32_16x16x32_bf16 v[60:63], v[156:159], v[172:175], v[60:63]
	v_mfma_f32_16x16x32_bf16 v[56:59], v[164:167], v[172:175], v[56:59]
	v_mfma_f32_16x16x32_bf16 v[52:55], v[156:159], v[188:191], v[52:55]
	v_mfma_f32_16x16x32_bf16 v[48:51], v[164:167], v[188:191], v[48:51]
	v_mfma_f32_16x16x32_bf16 v[44:47], v[156:159], v[196:199], v[44:47]
	v_mfma_f32_16x16x32_bf16 v[40:43], v[164:167], v[196:199], v[40:43]
	v_mfma_f32_16x16x32_bf16 v[36:39], v[156:159], v[204:207], v[36:39]
	v_mfma_f32_16x16x32_bf16 v[32:35], v[164:167], v[204:207], v[32:35]
	v_mfma_f32_16x16x32_bf16 v[60:63], v[160:163], v[176:179], v[60:63]
	v_mfma_f32_16x16x32_bf16 v[56:59], v[168:171], v[176:179], v[56:59]
	v_mfma_f32_16x16x32_bf16 v[52:55], v[160:163], v[192:195], v[52:55]
	v_mfma_f32_16x16x32_bf16 v[48:51], v[168:171], v[192:195], v[48:51]
	v_mfma_f32_16x16x32_bf16 v[44:47], v[160:163], v[200:203], v[44:47]
	v_mfma_f32_16x16x32_bf16 v[40:43], v[168:171], v[200:203], v[40:43]
	v_mfma_f32_16x16x32_bf16 v[36:39], v[160:163], v[208:211], v[36:39]
	v_mfma_f32_16x16x32_bf16 v[32:35], v[168:171], v[208:211], v[32:35]
	s_setprio 0
	s_barrier
	s_add_i32 s40, s57, s61
	v_lshl_add_u64 v[180:181], s[44:45], 0, v[130:131]
	s_mov_b32 m0, s40
	ds_read_b128 v[172:175], v187 offset:16384
	ds_read_b128 v[176:179], v187 offset:17408
	ds_read_b128 v[188:191], v187 offset:18432
	ds_read_b128 v[192:195], v187 offset:19456
	ds_read_b128 v[196:199], v187 offset:20480
	ds_read_b128 v[200:203], v187 offset:21504
	ds_read_b128 v[204:207], v187 offset:22528
	ds_read_b128 v[208:211], v187 offset:23552
	global_load_lds_dwordx4 v[180:181], off
	s_add_i32 m0, s40, 0x2000
	s_add_u32 s40, s44, 0xb0000
	v_lshl_add_u64 v[212:213], s[44:45], 0, v[134:135]
	s_addc_u32 s41, s45, 0
	s_add_i32 s67, s58, s61
	global_load_lds_dwordx4 v[212:213], off
	v_lshl_add_u64 v[214:215], s[40:41], 0, v[130:131]
	s_mov_b32 m0, s67
	v_lshl_add_u64 v[216:217], s[46:47], 0, v[132:133]
	global_load_lds_dwordx4 v[214:215], off
	v_lshl_add_u64 v[214:215], s[40:41], 0, v[134:135]
	s_add_i32 m0, s67, 0x2000
	s_nop 0
	global_load_lds_dwordx4 v[214:215], off
	v_lshl_add_u64 v[214:215], s[46:47], 0, v[128:129]
	s_mov_b32 m0, s39
	s_nop 0
	global_load_lds_dwordx4 v[214:215], off
	s_mov_b32 m0, s48
	s_nop 0
	global_load_lds_dwordx4 v[216:217], off
	s_waitcnt vmcnt(8)
	s_waitcnt lgkmcnt(0)
	s_barrier
; #define PG8_STAGE(bufoff, gbase, voff) do { _Pragma("unroll") for (int _i = 0; _i < 2; ++_i) \
;         __builtin_amdgcn_global_load_lds((const unsigned*)((const char*)(gbase) + (voff)[_i]), (LAS unsigned*)(lds + (bufoff) + ldsw + _i * 8192), 16, 0, 0); } while (0)
; #define PG8_LDA(dst, b, h) do { _Pragma("unroll") for (int m = 0; m < 4; ++m) _Pragma("unroll") for (int k = 0; k < 2; ++k) dst[m][k] = *(const LAS bf16x8*)(lds + PG8_SA(b, h) + aoff + m * 2048 + k * 1024); } while (0)
; #define PG8_LDB(dst, b, h) do { _Pragma("unroll") for (int n = 0; n < 2; ++n) _Pragma("unroll") for (int k = 0; k < 2; ++k) dst[n][k] = *(const LAS bf16x8*)(lds + PG8_SB(b, h) + boff + n * 2048 + k * 1024); } while (0)
; #define PG8_MMA(ai, bj, At, Bt) do { __builtin_amdgcn_s_setprio(1); _Pragma("unroll") for (int m = 0; m < 4; ++m) _Pragma("unroll") for (int n = 0; n < 2; ++n) _Pragma("unroll") for (int k = 0; k < 2; ++k) \
;         acc[ai][bj][m][n] = __builtin_amdgcn_mfma_f32_16x16x32_bf16(Bt[n][k], At[m][k], acc[ai][bj][m][n], 0, 0, 0); __builtin_amdgcn_s_setprio(0); } while (0)
; #define PG8_WAIT_V(n) asm volatile("s_waitcnt vmcnt(" #n ")" ::: "memory")
; #define PG8_WAIT_L(n) asm volatile("s_waitcnt lgkmcnt(" #n ")" ::: "memory")
; #define PG8_BAR __builtin_amdgcn_s_barrier()
; #define PG8_SCHED __builtin_amdgcn_sched_barrier(0)
; template <class Epi, bool ALIGN_EPI = true, bool SP2 = true>
; __device__ __forceinline__ void gemm_phase(LAS unsigned char* lds, const Gemm g, const StaticOrder& S, const Epi& E, const int wave_s) {
;     ...
;             PG8_WAIT_V(8); PG8_WAIT_L(0); PG8_BAR; PG8_MMA(1, 0, At, B0); PG8_MMA(1, 1, At, B1); PG8_BAR; PG8_SCHED;
;             PG8_LDB(B0, 1, 0); PG8_LDB(B1, 1, 1); PG8_SCHED; PG8_LDA(At, 1, 0); PG8_STAGE(PG8_SA(0, 1), a2 + hstep, voffA);
;             PG8_WAIT_V(8); PG8_WAIT_L(0); PG8_BAR; PG8_MMA(0, 0, At, B0); PG8_MMA(0, 1, At, B1); PG8_BAR; PG8_SCHED;
	s_setprio 1
	v_mfma_f32_16x16x32_bf16 v[92:95], v[140:143], v[172:175], v[92:95]
	v_mfma_f32_16x16x32_bf16 v[88:91], v[148:151], v[172:175], v[88:91]
	v_mfma_f32_16x16x32_bf16 v[84:87], v[140:143], v[188:191], v[84:87]
	v_mfma_f32_16x16x32_bf16 v[80:83], v[148:151], v[188:191], v[80:83]
	v_mfma_f32_16x16x32_bf16 v[76:79], v[140:143], v[196:199], v[76:79]
	v_mfma_f32_16x16x32_bf16 v[72:75], v[148:151], v[196:199], v[72:75]
	v_mfma_f32_16x16x32_bf16 v[68:71], v[140:143], v[204:207], v[68:71]
	v_mfma_f32_16x16x32_bf16 v[64:67], v[148:151], v[204:207], v[64:67]
	v_mfma_f32_16x16x32_bf16 v[92:95], v[144:147], v[176:179], v[92:95]
	v_mfma_f32_16x16x32_bf16 v[88:91], v[152:155], v[176:179], v[88:91]
	v_mfma_f32_16x16x32_bf16 v[84:87], v[144:147], v[192:195], v[84:87]
	v_mfma_f32_16x16x32_bf16 v[80:83], v[152:155], v[192:195], v[80:83]
	v_mfma_f32_16x16x32_bf16 v[76:79], v[144:147], v[200:203], v[76:79]
	v_mfma_f32_16x16x32_bf16 v[72:75], v[152:155], v[200:203], v[72:75]
	v_mfma_f32_16x16x32_bf16 v[68:71], v[144:147], v[208:211], v[68:71]
	v_mfma_f32_16x16x32_bf16 v[64:67], v[152:155], v[208:211], v[64:67]
	v_mfma_f32_16x16x32_bf16 v[28:31], v[156:159], v[172:175], v[28:31]
	v_mfma_f32_16x16x32_bf16 v[24:27], v[164:167], v[172:175], v[24:27]
	v_mfma_f32_16x16x32_bf16 v[20:23], v[156:159], v[188:191], v[20:23]
	v_mfma_f32_16x16x32_bf16 v[16:19], v[164:167], v[188:191], v[16:19]
	v_mfma_f32_16x16x32_bf16 v[12:15], v[156:159], v[196:199], v[12:15]
	v_mfma_f32_16x16x32_bf16 v[8:11], v[164:167], v[196:199], v[8:11]
	v_mfma_f32_16x16x32_bf16 v[4:7], v[156:159], v[204:207], v[4:7]
	v_mfma_f32_16x16x32_bf16 v[0:3], v[164:167], v[204:207], v[0:3]
	v_mfma_f32_16x16x32_bf16 v[28:31], v[160:163], v[176:179], v[28:31]
	v_mfma_f32_16x16x32_bf16 v[24:27], v[168:171], v[176:179], v[24:27]
	v_mfma_f32_16x16x32_bf16 v[20:23], v[160:163], v[192:195], v[20:23]
	v_mfma_f32_16x16x32_bf16 v[16:19], v[168:171], v[192:195], v[16:19]
	v_mfma_f32_16x16x32_bf16 v[12:15], v[160:163], v[200:203], v[12:15]
	v_mfma_f32_16x16x32_bf16 v[8:11], v[168:171], v[200:203], v[8:11]
	v_mfma_f32_16x16x32_bf16 v[4:7], v[160:163], v[208:211], v[4:7]
	v_mfma_f32_16x16x32_bf16 v[0:3], v[168:171], v[208:211], v[0:3]
	s_setprio 0
	s_barrier
	s_add_i32 s67, 0, 0x18000
	s_add_i32 s68, 0, 0x1c000
	v_add_u32_e32 v152, s67, v183
	v_add_u32_e32 v168, s68, v183
	ds_read_b128 v[140:143], v152
	ds_read_b128 v[144:147], v152 offset:1024
	ds_read_b128 v[148:151], v152 offset:2048
	ds_read_b128 v[152:155], v152 offset:3072
	ds_read_b128 v[156:159], v168
	ds_read_b128 v[160:163], v168 offset:1024
	ds_read_b128 v[164:167], v168 offset:2048
	ds_read_b128 v[168:171], v168 offset:3072
	s_add_u32 s40, s46, 0xb0000
	s_addc_u32 s41, s47, 0
	s_mov_b32 m0, s49
	v_lshl_add_u64 v[218:219], s[40:41], 0, v[128:129]
	ds_read_b128 v[172:175], v187 offset:32768
	ds_read_b128 v[176:179], v187 offset:33792
	ds_read_b128 v[188:191], v187 offset:34816
	ds_read_b128 v[192:195], v187 offset:35840
	ds_read_b128 v[196:199], v187 offset:36864
	ds_read_b128 v[200:203], v187 offset:37888
	ds_read_b128 v[204:207], v187 offset:38912
	ds_read_b128 v[208:211], v187 offset:39936
	global_load_lds_dwordx4 v[218:219], off
	v_lshl_add_u64 v[218:219], s[40:41], 0, v[132:133]
	s_mov_b32 m0, s50
	s_nop 0
	global_load_lds_dwordx4 v[218:219], off
	s_waitcnt vmcnt(8)
	s_waitcnt lgkmcnt(0)
	s_barrier
	s_setprio 1
	v_mfma_f32_16x16x32_bf16 v[124:127], v[140:143], v[172:175], v[124:127]
	v_mfma_f32_16x16x32_bf16 v[120:123], v[148:151], v[172:175], v[120:123]
	v_mfma_f32_16x16x32_bf16 v[116:119], v[140:143], v[188:191], v[116:119]
	v_mfma_f32_16x16x32_bf16 v[112:115], v[148:151], v[188:191], v[112:115]
	v_mfma_f32_16x16x32_bf16 v[108:111], v[140:143], v[196:199], v[108:111]
	v_mfma_f32_16x16x32_bf16 v[104:107], v[148:151], v[196:199], v[104:107]
	v_mfma_f32_16x16x32_bf16 v[100:103], v[140:143], v[204:207], v[100:103]
	v_mfma_f32_16x16x32_bf16 v[96:99], v[148:151], v[204:207], v[96:99]
	v_mfma_f32_16x16x32_bf16 v[124:127], v[144:147], v[176:179], v[124:127]
	v_mfma_f32_16x16x32_bf16 v[120:123], v[152:155], v[176:179], v[120:123]
	v_mfma_f32_16x16x32_bf16 v[116:119], v[144:147], v[192:195], v[116:119]
	v_mfma_f32_16x16x32_bf16 v[112:115], v[152:155], v[192:195], v[112:115]
	v_mfma_f32_16x16x32_bf16 v[108:111], v[144:147], v[200:203], v[108:111]
	v_mfma_f32_16x16x32_bf16 v[104:107], v[152:155], v[200:203], v[104:107]
	v_mfma_f32_16x16x32_bf16 v[100:103], v[144:147], v[208:211], v[100:103]
	v_mfma_f32_16x16x32_bf16 v[96:99], v[152:155], v[208:211], v[96:99]
	v_mfma_f32_16x16x32_bf16 v[60:63], v[156:159], v[172:175], v[60:63]
	v_mfma_f32_16x16x32_bf16 v[56:59], v[164:167], v[172:175], v[56:59]
	v_mfma_f32_16x16x32_bf16 v[52:55], v[156:159], v[188:191], v[52:55]
	v_mfma_f32_16x16x32_bf16 v[48:51], v[164:167], v[188:191], v[48:51]
	v_mfma_f32_16x16x32_bf16 v[44:47], v[156:159], v[196:199], v[44:47]
	v_mfma_f32_16x16x32_bf16 v[40:43], v[164:167], v[196:199], v[40:43]
	v_mfma_f32_16x16x32_bf16 v[36:39], v[156:159], v[204:207], v[36:39]
	v_mfma_f32_16x16x32_bf16 v[32:35], v[164:167], v[204:207], v[32:35]
	v_mfma_f32_16x16x32_bf16 v[60:63], v[160:163], v[176:179], v[60:63]
	v_mfma_f32_16x16x32_bf16 v[56:59], v[168:171], v[176:179], v[56:59]
	v_mfma_f32_16x16x32_bf16 v[52:55], v[160:163], v[192:195], v[52:55]
	v_mfma_f32_16x16x32_bf16 v[48:51], v[168:171], v[192:195], v[48:51]
	v_mfma_f32_16x16x32_bf16 v[44:47], v[160:163], v[200:203], v[44:47]
	v_mfma_f32_16x16x32_bf16 v[40:43], v[168:171], v[200:203], v[40:43]
	v_mfma_f32_16x16x32_bf16 v[36:39], v[160:163], v[208:211], v[36:39]
	v_mfma_f32_16x16x32_bf16 v[32:35], v[168:171], v[208:211], v[32:35]
	s_setprio 0
	s_barrier
; #define PG8_STAGE(bufoff, gbase, voff) do { _Pragma("unroll") for (int _i = 0; _i < 2; ++_i) \
;         __builtin_amdgcn_global_load_lds((const unsigned*)((const char*)(gbase) + (voff)[_i]), (LAS unsigned*)(lds + (bufoff) + ldsw + _i * 8192), 16, 0, 0); } while (0)
; #define PG8_LDA(dst, b, h) do { _Pragma("unroll") for (int m = 0; m < 4; ++m) _Pragma("unroll") for (int k = 0; k < 2; ++k) dst[m][k] = *(const LAS bf16x8*)(lds + PG8_SA(b, h) + aoff + m * 2048 + k * 1024); } while (0)
; #define PG8_MMA(ai, bj, At, Bt) do { __builtin_amdgcn_s_setprio(1); _Pragma("unroll") for (int m = 0; m < 4; ++m) _Pragma("unroll") for (int n = 0; n < 2; ++n) _Pragma("unroll") for (int k = 0; k < 2; ++k) \
;         acc[ai][bj][m][n] = __builtin_amdgcn_mfma_f32_16x16x32_bf16(Bt[n][k], At[m][k], acc[ai][bj][m][n], 0, 0, 0); __builtin_amdgcn_s_setprio(0); } while (0)
; #define PG8_WAIT_V(n) asm volatile("s_waitcnt vmcnt(" #n ")" ::: "memory")
; #define PG8_WAIT_L(n) asm volatile("s_waitcnt lgkmcnt(" #n ")" ::: "memory")
; #define PG8_BAR __builtin_amdgcn_s_barrier()
; #define PG8_SCHED __builtin_amdgcn_sched_barrier(0)
; template <class Epi, bool ALIGN_EPI = true, bool SP2 = true>
; __device__ __forceinline__ void gemm_phase(LAS unsigned char* lds, const Gemm g, const StaticOrder& S, const Epi& E, const int wave_s) {
;     ...
;             PG8_LDA(At, 1, 1); PG8_STAGE(PG8_SB(1, 0), b3, voffB); PG8_STAGE(PG8_SB(1, 1), b3 + hstep, voffB); PG8_STAGE(PG8_SA(1, 0), a3, voffA);
;             PG8_WAIT_V(8); PG8_WAIT_L(0); PG8_BAR; PG8_MMA(1, 0, At, B0); PG8_MMA(1, 1, At, B1); PG8_BAR; PG8_SCHED;
;     ...
;         if constexpr (ALIGN_EPI) { if (wr == 0) PG8_BAR; }
	s_add_i32 s40, s67, s61
	v_lshl_add_u64 v[180:181], v[180:181], 0, s[22:23]
	s_mov_b32 m0, s40
	ds_read_b128 v[172:175], v187 offset:49152
	ds_read_b128 v[176:179], v187 offset:50176
	ds_read_b128 v[188:191], v187 offset:51200
	ds_read_b128 v[192:195], v187 offset:52224
	ds_read_b128 v[196:199], v187 offset:53248
	ds_read_b128 v[200:203], v187 offset:54272
	ds_read_b128 v[204:207], v187 offset:55296
	ds_read_b128 v[208:211], v187 offset:56320
	global_load_lds_dwordx4 v[180:181], off
	s_add_i32 m0, s40, 0x2000
	s_add_u32 s40, s44, 0xb0080
	v_lshl_add_u64 v[180:181], v[212:213], 0, s[22:23]
	s_addc_u32 s41, s45, 0
	s_add_i32 s44, s68, s61
	global_load_lds_dwordx4 v[180:181], off
	v_lshl_add_u64 v[180:181], s[40:41], 0, v[130:131]
	s_mov_b32 m0, s44
	s_nop 0
	global_load_lds_dwordx4 v[180:181], off
	v_lshl_add_u64 v[180:181], s[40:41], 0, v[134:135]
	s_add_i32 m0, s44, 0x2000
	s_nop 0
	global_load_lds_dwordx4 v[180:181], off
	v_lshl_add_u64 v[180:181], v[214:215], 0, s[22:23]
	s_mov_b32 m0, s54
	s_nop 0
	global_load_lds_dwordx4 v[180:181], off
	v_lshl_add_u64 v[180:181], v[216:217], 0, s[22:23]
	s_mov_b32 m0, s55
	s_nop 0
	global_load_lds_dwordx4 v[180:181], off
	s_waitcnt vmcnt(8)
	s_waitcnt lgkmcnt(0)
	s_barrier
	s_setprio 1
	v_mfma_f32_16x16x32_bf16 v[92:95], v[140:143], v[172:175], v[92:95]
	v_mfma_f32_16x16x32_bf16 v[88:91], v[148:151], v[172:175], v[88:91]
	v_mfma_f32_16x16x32_bf16 v[84:87], v[140:143], v[188:191], v[84:87]
	v_mfma_f32_16x16x32_bf16 v[80:83], v[148:151], v[188:191], v[80:83]
	v_mfma_f32_16x16x32_bf16 v[76:79], v[140:143], v[196:199], v[76:79]
	v_mfma_f32_16x16x32_bf16 v[72:75], v[148:151], v[196:199], v[72:75]
	v_mfma_f32_16x16x32_bf16 v[68:71], v[140:143], v[204:207], v[68:71]
	v_mfma_f32_16x16x32_bf16 v[64:67], v[148:151], v[204:207], v[64:67]
	v_mfma_f32_16x16x32_bf16 v[92:95], v[144:147], v[176:179], v[92:95]
	v_mfma_f32_16x16x32_bf16 v[88:91], v[152:155], v[176:179], v[88:91]
	v_mfma_f32_16x16x32_bf16 v[84:87], v[144:147], v[192:195], v[84:87]
	v_mfma_f32_16x16x32_bf16 v[80:83], v[152:155], v[192:195], v[80:83]
	v_mfma_f32_16x16x32_bf16 v[76:79], v[144:147], v[200:203], v[76:79]
	v_mfma_f32_16x16x32_bf16 v[72:75], v[152:155], v[200:203], v[72:75]
	v_mfma_f32_16x16x32_bf16 v[68:71], v[144:147], v[208:211], v[68:71]
	v_mfma_f32_16x16x32_bf16 v[64:67], v[152:155], v[208:211], v[64:67]
	v_mfma_f32_16x16x32_bf16 v[28:31], v[156:159], v[172:175], v[28:31]
	v_mfma_f32_16x16x32_bf16 v[24:27], v[164:167], v[172:175], v[24:27]
	v_mfma_f32_16x16x32_bf16 v[20:23], v[156:159], v[188:191], v[20:23]
	v_mfma_f32_16x16x32_bf16 v[16:19], v[164:167], v[188:191], v[16:19]
	v_mfma_f32_16x16x32_bf16 v[12:15], v[156:159], v[196:199], v[12:15]
	v_mfma_f32_16x16x32_bf16 v[8:11], v[164:167], v[196:199], v[8:11]
	v_mfma_f32_16x16x32_bf16 v[4:7], v[156:159], v[204:207], v[4:7]
	v_mfma_f32_16x16x32_bf16 v[0:3], v[164:167], v[204:207], v[0:3]
	v_mfma_f32_16x16x32_bf16 v[28:31], v[160:163], v[176:179], v[28:31]
	v_mfma_f32_16x16x32_bf16 v[24:27], v[168:171], v[176:179], v[24:27]
	v_mfma_f32_16x16x32_bf16 v[20:23], v[160:163], v[192:195], v[20:23]
	v_mfma_f32_16x16x32_bf16 v[16:19], v[168:171], v[192:195], v[16:19]
	v_mfma_f32_16x16x32_bf16 v[12:15], v[160:163], v[200:203], v[12:15]
	v_mfma_f32_16x16x32_bf16 v[8:11], v[168:171], v[200:203], v[8:11]
	v_mfma_f32_16x16x32_bf16 v[4:7], v[160:163], v[208:211], v[4:7]
	v_mfma_f32_16x16x32_bf16 v[0:3], v[168:171], v[208:211], v[0:3]
	s_setprio 0
	s_barrier
	s_add_i32 s66, s66, 2
	s_add_u32 s64, s64, 0x100
	s_addc_u32 s65, s65, 0
	s_cmp_gt_u32 s66, 41
	s_mov_b64 s[40:41], s[42:43]
	s_cbranch_scc0 .LBB0_1404
	s_and_b64 vcc, exec, s[24:25]
	s_cbranch_vccz .LBB0_1407
	s_barrier
